# all 12 gemm256 k-loops converted to LDS-DMA staging (swizzle on global side) with double-buffered fragments: next k-step's LDS reads and DMA ride inside the MFMA burst
# speedup vs baseline: 1.1369x; 1.0148x over previous
; DI int tidx() { int t = __builtin_amdgcn_workitem_id_x(); asm volatile("" : "+v"(t)); return t; }
; DI brsrc_t make_rsrc(const void* p) { return __builtin_amdgcn_make_buffer_rsrc((void*)p, 0, 0x7fffffff, 0x00020000); }
; DI void cfence() { asm volatile("" ::: "memory"); }
; DI int swz4(int row) { const int g = (row >> 2) & 3; return ((g << 1) ^ ((g >> 1) * 3)) & 3; }
; #define LSTORE2(RA, RB, P)                                       \
;   {                                                              \
;     char* dA_ = smem + (P) * 24576 + wofs;                       \
;     _Pragma("unroll") for (int j = 0; j < 4; ++j) *(u32x4*)(dA_ + j * 4096) = RA[j]; \
;     _Pragma("unroll") for (int j = 0; j < 2; ++j) *(u32x4*)(dA_ + 16384 + j * 4096) = RB[j]; \
;   }
; DI void gemm256_kloop(f32x4 (&acc)[8][4], const bf16_t* __restrict__ A, int lda, const bf16_t* __restrict__ Bt, int ldb,
;                       int K, int b, int s0, int col0, char* smem) {
;   const int tid = tidx(), lane = tid & 63, wid = tid >> 6;
;   const int wr = wid >> 1, wc = wid & 1, fr = lane & 15, fq = lane >> 4;
;   const int lrow = tid >> 2, lkc = tid & 3;
;   const brsrc_t rA = make_rsrc(A), rB = make_rsrc(Bt);
;   unsigned aoff[4];
; #pragma unroll
;   for (int j = 0; j < 4; ++j) {
;     int s = s0 + lrow + 64 * j;
;     s = s < 0 ? 0 : (s > SB - 1 ? SB - 1 : s);
;     aoff[j] = ((unsigned)(b * SB + s) * (unsigned)lda + lkc * 8) * 2u;
;   }
;   const unsigned boff = ((unsigned)(col0 + lrow) * (unsigned)ldb + lkc * 8) * 2u;
;   const unsigned bstep = 64u * (unsigned)ldb * 2u;
;   const int wofs = lrow * 64 + ((lkc ^ swz4(lrow)) << 4);
;   const int nk = K >> 5;
;   u32x4 xa[4], xb[2], ya[4], yb[2];
;     ...
;   GLOAD2(xa, xb, 0);
;   GLOAD2(ya, yb, 1);
;   cfence();
;   LSTORE2(xa, xb, 0);
;   __syncthreads();
;   const int co = ((fq ^ swz4(fr)) << 4);
;   const int aofs = (wr * 128 + fr) * 64 + co, bofs = (wc * 64 + fr) * 64 + co;
; template <class Epi>
; DI void gemm256_tile(const bf16_t* A, int lda, const bf16_t* Bt, int ldb, int K, int b, int s0, int col0, char* smem,
;                      const Epi& epi, int rstep) {
;   f32x4 acc[8][4];
; #pragma unroll
;   for (int m = 0; m < 8; ++m)
; #pragma unroll
;     for (int n = 0; n < 4; ++n) acc[m][n] = f32x4{0.f, 0.f, 0.f, 0.f};
.LBB0_36:
	s_ashr_i32 s6, s14, 31
	s_lshr_b32 s6, s6, 28
	s_add_i32 s6, s14, s6
	s_ashr_i32 s8, s6, 4
	s_mul_hi_i32 s6, s14, 0x7e07e07f
	s_lshr_b32 s7, s6, 31
	s_ashr_i32 s15, s6, 9
	s_add_i32 s15, s15, s7
	s_mul_i32 s6, s15, 0xffffffbf
	s_waitcnt vmcnt(0)
	v_mov_b32_e32 v7, v194
	s_add_i32 s6, s6, s8
	s_lshl_b32 s7, s8, 11
	v_ashrrev_i32_e32 v32, 2, v7
	v_lshl_add_u32 v2, s6, 8, v32
	v_max_i32_e32 v4, 0xffffffc0, v2
	s_lshl_b32 s9, s14, 7
	v_add_u32_e32 v4, 64, v4
	s_sub_i32 s16, s9, s7
	s_mul_i32 s9, s15, 0x4100
	v_min_u32_e32 v4, 0x40ff, v4
	v_and_b32_e32 v33, 3, v7
	v_add_u32_e32 v4, s9, v4
	v_lshlrev_b32_e32 v3, 4, v33
	v_mul_lo_u32 v4, v4, s78
	v_med3_i32 v0, v2, 0, v201
	v_or_b32_e32 v154, v4, v3
	v_max_i32_e32 v4, 0xffffff80, v2
	v_max_i32_e32 v2, 0xffffff40, v2
	v_add_u32_e32 v2, 0xc0, v2
	v_min_u32_e32 v2, 0x40ff, v2
	v_add_u32_e32 v2, s9, v2
	v_mul_lo_u32 v2, v2, s78
	v_add_u32_e32 v4, 0x80, v4
	v_or_b32_e32 v156, v2, v3
	v_add_u32_e32 v2, s16, v32
	v_add_u32_e32 v0, s9, v0
	v_min_u32_e32 v4, 0x40ff, v4
	v_mul_lo_u32 v2, v2, s78
	v_mul_lo_u32 v0, v0, s78
	v_add_u32_e32 v4, s9, v4
	v_or_b32_e32 v157, v2, v3
	v_or_b32_e32 v0, v0, v3
	v_mul_lo_u32 v4, v4, s78
	s_mov_b32 s6, s22
	s_mov_b32 s7, s23
	v_add_u32_e32 v158, 0xb2000, v157
	v_or_b32_e32 v155, v4, v3
	v_bfe_u32 v162, v194, 4, 2
	v_lshlrev_b32_e32 v162, 2, v162
	v_mov_b32_e32 v163, 0x1320
	v_lshrrev_b32_e32 v162, v162, v163
	v_and_b32_e32 v162, 3, v162
	v_lshlrev_b32_e32 v162, 4, v162
	v_xor_b32_e32 v0, v0, v162
	v_xor_b32_e32 v154, v154, v162
	v_xor_b32_e32 v155, v155, v162
	v_xor_b32_e32 v156, v156, v162
	v_xor_b32_e32 v157, v157, v162
	v_xor_b32_e32 v158, v158, v162
	v_lshrrev_b32_e32 v163, 6, v194
	s_nop 0
	v_readfirstlane_b32 s98, v163
	s_lshl_b32 s98, s98, 10
	s_mov_b32 m0, s98
	s_nop 0
	buffer_load_dwordx4 v0, s[20:23], 0 offen lds
	s_add_u32 m0, m0, 0x1000
	s_nop 0
	buffer_load_dwordx4 v154, s[20:23], 0 offen lds
	s_add_u32 m0, m0, 0x1000
	s_nop 0
	buffer_load_dwordx4 v155, s[20:23], 0 offen lds
	s_add_u32 m0, m0, 0x1000
	s_nop 0
	buffer_load_dwordx4 v156, s[20:23], 0 offen lds
	s_add_u32 m0, m0, 0x1000
	s_nop 0
	buffer_load_dwordx4 v157, s[4:7], 0 offen lds
	s_add_u32 m0, m0, 0x1000
	s_nop 0
	buffer_load_dwordx4 v158, s[4:7], 0 offen lds
	s_add_u32 m0, s98, 0x6000
	s_nop 0
	buffer_load_dwordx4 v0, s[20:23], 64 offen lds
	s_add_u32 m0, m0, 0x1000
	s_nop 0
	buffer_load_dwordx4 v154, s[20:23], 64 offen lds
	s_add_u32 m0, m0, 0x1000
	s_nop 0
	buffer_load_dwordx4 v155, s[20:23], 64 offen lds
	s_add_u32 m0, m0, 0x1000
	s_nop 0
	buffer_load_dwordx4 v156, s[20:23], 64 offen lds
	s_add_u32 m0, m0, 0x1000
	s_nop 0
	buffer_load_dwordx4 v157, s[4:7], 64 offen lds
	s_add_u32 m0, m0, 0x1000
	s_nop 0
	buffer_load_dwordx4 v158, s[4:7], 64 offen lds
	v_lshrrev_b32_e32 v36, 1, v7
	v_bfe_i32 v35, v7, 3, 1
	v_lshlrev_b32_e32 v38, 6, v32
	v_lshrrev_b32_e32 v32, 1, v32
	v_and_b32_e32 v36, 2, v36
	v_bfe_i32 v34, v7, 5, 1
	v_and_b32_e32 v32, 2, v32
	v_bitop3_b32 v35, v35, v36, 3 bitop3:0x6c
	v_bitop3_b32 v32, v34, v32, 3 bitop3:0x6c
	v_lshlrev_b32_e32 v34, 4, v35
	v_lshlrev_b32_e32 v37, 6, v7
	v_xor_b32_e32 v32, v32, v33
	v_bitop3_b32 v7, v34, v7, 48 bitop3:0x78
	s_movk_i32 s12, 0x13c0
	v_mov_b32_e32 v2, 0
	v_lshl_or_b32 v159, v32, 4, v38
	v_and_or_b32 v160, v37, s12, v7
	s_movk_i32 s12, 0xe3c0
	s_mov_b32 s11, 0
	s_movk_i32 s10, 0x80
	v_mov_b32_e32 v3, v2
	v_mov_b32_e32 v4, v2
	v_mov_b32_e32 v5, v2
	v_mov_b32_e32 v6, v2
	v_and_or_b32 v161, v37, s12, v7
	v_mov_b32_e32 v7, v2
	v_mov_b32_e32 v32, v2
	v_mov_b32_e32 v33, v2
	v_mov_b32_e32 v34, v2
	v_mov_b32_e32 v35, v2
	v_mov_b32_e32 v36, v2
	v_mov_b32_e32 v37, v2
	v_mov_b32_e32 v38, v2
	v_mov_b32_e32 v39, v2
	v_mov_b32_e32 v40, v2
	v_mov_b32_e32 v41, v2
	v_mov_b32_e32 v42, v2
	v_mov_b32_e32 v43, v2
	v_mov_b32_e32 v44, v2
	v_mov_b32_e32 v45, v2
	v_mov_b32_e32 v46, v2
	v_mov_b32_e32 v47, v2
	v_mov_b32_e32 v48, v2
	v_mov_b32_e32 v49, v2
	v_mov_b32_e32 v50, v2
	v_mov_b32_e32 v51, v2
	v_mov_b32_e32 v52, v2
	v_mov_b32_e32 v53, v2
	v_mov_b32_e32 v54, v2
	v_mov_b32_e32 v55, v2
	v_mov_b32_e32 v8, v2
	v_mov_b32_e32 v9, v2
	v_mov_b32_e32 v10, v2
	v_mov_b32_e32 v11, v2
	v_mov_b32_e32 v12, v2
	v_mov_b32_e32 v13, v2
	v_mov_b32_e32 v14, v2
	v_mov_b32_e32 v15, v2
	v_mov_b32_e32 v16, v2
	v_mov_b32_e32 v17, v2
	v_mov_b32_e32 v18, v2
	v_mov_b32_e32 v19, v2
	v_mov_b32_e32 v20, v2
	v_mov_b32_e32 v21, v2
	v_mov_b32_e32 v22, v2
	v_mov_b32_e32 v23, v2
	v_mov_b32_e32 v24, v2
	v_mov_b32_e32 v25, v2
	v_mov_b32_e32 v26, v2
	v_mov_b32_e32 v27, v2
	v_mov_b32_e32 v28, v2
	v_mov_b32_e32 v29, v2
	v_mov_b32_e32 v30, v2
	v_mov_b32_e32 v31, v2
	v_mov_b32_e32 v56, v2
	v_mov_b32_e32 v57, v2
	v_mov_b32_e32 v58, v2
	v_mov_b32_e32 v59, v2
	v_mov_b32_e32 v60, v2
	v_mov_b32_e32 v61, v2
	v_mov_b32_e32 v62, v2
	v_mov_b32_e32 v63, v2
	v_mov_b32_e32 v64, v2
	v_mov_b32_e32 v65, v2
	v_mov_b32_e32 v66, v2
	v_mov_b32_e32 v67, v2
	v_mov_b32_e32 v68, v2
	v_mov_b32_e32 v69, v2
	v_mov_b32_e32 v70, v2
	v_mov_b32_e32 v71, v2
	v_mov_b32_e32 v72, v2
	v_mov_b32_e32 v73, v2
	v_mov_b32_e32 v74, v2
	v_mov_b32_e32 v75, v2
	v_mov_b32_e32 v76, v2
	v_mov_b32_e32 v77, v2
	v_mov_b32_e32 v78, v2
	v_mov_b32_e32 v79, v2
	v_mov_b32_e32 v80, v2
	v_mov_b32_e32 v81, v2
	v_mov_b32_e32 v82, v2
	v_mov_b32_e32 v83, v2
	v_mov_b32_e32 v84, v2
	v_mov_b32_e32 v85, v2
	v_mov_b32_e32 v86, v2
	v_mov_b32_e32 v87, v2
	v_mov_b32_e32 v88, v2
	v_mov_b32_e32 v89, v2
	v_mov_b32_e32 v90, v2
	v_mov_b32_e32 v91, v2
	v_mov_b32_e32 v92, v2
	v_mov_b32_e32 v93, v2
	v_mov_b32_e32 v94, v2
	v_mov_b32_e32 v95, v2
	v_mov_b32_e32 v96, v2
	v_mov_b32_e32 v97, v2
	v_mov_b32_e32 v98, v2
	v_mov_b32_e32 v99, v2
	v_mov_b32_e32 v100, v2
	v_mov_b32_e32 v101, v2
	v_mov_b32_e32 v102, v2
	v_mov_b32_e32 v103, v2
	v_mov_b32_e32 v104, v2
	v_mov_b32_e32 v105, v2
	v_mov_b32_e32 v106, v2
	v_mov_b32_e32 v107, v2
	v_mov_b32_e32 v108, v2
	v_mov_b32_e32 v109, v2
	v_mov_b32_e32 v110, v2
	v_mov_b32_e32 v111, v2
	v_mov_b32_e32 v112, v2
	v_mov_b32_e32 v113, v2
	v_mov_b32_e32 v114, v2
	v_mov_b32_e32 v115, v2
	v_mov_b32_e32 v116, v2
	v_mov_b32_e32 v117, v2
	v_mov_b32_e32 v118, v2
	v_mov_b32_e32 v119, v2
	v_mov_b32_e32 v120, v2
	v_mov_b32_e32 v121, v2
	v_mov_b32_e32 v122, v2
	v_mov_b32_e32 v123, v2
	v_mov_b32_e32 v124, v2
	v_mov_b32_e32 v125, v2
	v_mov_b32_e32 v126, v2
	v_mov_b32_e32 v127, v2
	v_mov_b32_e32 v128, v2
	v_mov_b32_e32 v129, v2
	s_waitcnt vmcnt(6) lgkmcnt(0)
	s_barrier
	ds_read_b128 v[236:239], v160 offset:16384
	ds_read_b128 v[240:243], v160 offset:17408
	ds_read_b128 v[244:247], v160 offset:18432
	ds_read_b128 v[248:251], v160 offset:19456
	ds_read_b128 v[186:189], v161
	ds_read_b128 v[190:193], v161 offset:1024
	ds_read_b128 v[212:215], v161 offset:2048
	ds_read_b128 v[216:219], v161 offset:3072
	ds_read_b128 v[220:223], v161 offset:4096
	ds_read_b128 v[224:227], v161 offset:5120
	ds_read_b128 v[228:231], v161 offset:6144
	ds_read_b128 v[232:235], v161 offset:7168
	s_waitcnt vmcnt(0) lgkmcnt(0)
	s_barrier
; DI void cfence() { asm volatile("" ::: "memory"); }
; DI int swz4(int row) { const int g = (row >> 2) & 3; return ((g << 1) ^ ((g >> 1) * 3)) & 3; }
; #define LSTORE2(RA, RB, P)                                       \
;   {                                                              \
;     char* dA_ = smem + (P) * 24576 + wofs;                       \
;     _Pragma("unroll") for (int j = 0; j < 4; ++j) *(u32x4*)(dA_ + j * 4096) = RA[j]; \
;     _Pragma("unroll") for (int j = 0; j < 2; ++j) *(u32x4*)(dA_ + 16384 + j * 4096) = RB[j]; \
;   }
; DI void gemm256_kloop(f32x4 (&acc)[8][4], const bf16_t* __restrict__ A, int lda, const bf16_t* __restrict__ Bt, int ldb,
;                       int K, int b, int s0, int col0, char* smem) {
;     ...
;   GLOAD2(xa, xb, 0);
;   GLOAD2(ya, yb, 1);
;   cfence();
;   LSTORE2(xa, xb, 0);
;   __syncthreads();
;   const int co = ((fq ^ swz4(fr)) << 4);
;   const int aofs = (wr * 128 + fr) * 64 + co, bofs = (wc * 64 + fr) * 64 + co;
;   for (int kt = 0; kt < nk; kt += 2) {
;     GLOAD2(xa, xb, kt + 2);
;     cfence();
;     COMPUTE2(0);
;     LSTORE2(ya, yb, 1);
;     __syncthreads();
;     if (kt + 1 < nk) {
;       GLOAD2(ya, yb, kt + 3);
;       cfence();
;       COMPUTE2(1);
;       LSTORE2(xa, xb, 0);
;       __syncthreads();
;     }
;   }
.LBB0_37:
	s_add_i32 s12, s11, 2
	s_cmpk_lt_u32 s11, 0xae
	s_cselect_b64 s[18:19], -1, 0
	s_and_b64 vcc, s[18:19], exec
	s_cselect_b32 s13, s10, 0x2bc0
	s_setprio 1
	s_mov_b32 m0, s98
	v_mfma_f32_16x16x32_bf16 v[126:129], v[186:189], v[236:239], v[126:129]
	buffer_load_dwordx4 v0, s[20:23], s13 offen lds
	s_add_u32 m0, m0, 0x1000
	v_mfma_f32_16x16x32_bf16 v[122:125], v[186:189], v[240:243], v[122:125]
	buffer_load_dwordx4 v154, s[20:23], s13 offen lds
	s_add_u32 m0, m0, 0x1000
	v_mfma_f32_16x16x32_bf16 v[118:121], v[186:189], v[244:247], v[118:121]
	buffer_load_dwordx4 v155, s[20:23], s13 offen lds
	s_add_u32 m0, m0, 0x1000
	v_mfma_f32_16x16x32_bf16 v[114:117], v[186:189], v[248:251], v[114:117]
	buffer_load_dwordx4 v156, s[20:23], s13 offen lds
	s_add_u32 m0, m0, 0x1000
	v_mfma_f32_16x16x32_bf16 v[110:113], v[190:193], v[236:239], v[110:113]
	buffer_load_dwordx4 v157, s[4:7], s13 offen lds
	s_add_u32 m0, m0, 0x1000
	v_mfma_f32_16x16x32_bf16 v[106:109], v[190:193], v[240:243], v[106:109]
	buffer_load_dwordx4 v158, s[4:7], s13 offen lds
	v_mfma_f32_16x16x32_bf16 v[102:105], v[190:193], v[244:247], v[102:105]
	ds_read_b128 v[170:173], v160 offset:40960
	v_mfma_f32_16x16x32_bf16 v[98:101], v[190:193], v[248:251], v[98:101]
	v_mfma_f32_16x16x32_bf16 v[94:97], v[212:215], v[236:239], v[94:97]
	ds_read_b128 v[174:177], v160 offset:41984
	v_mfma_f32_16x16x32_bf16 v[90:93], v[212:215], v[240:243], v[90:93]
	v_mfma_f32_16x16x32_bf16 v[86:89], v[212:215], v[244:247], v[86:89]
	ds_read_b128 v[178:181], v160 offset:43008
	v_mfma_f32_16x16x32_bf16 v[82:85], v[212:215], v[248:251], v[82:85]
	v_mfma_f32_16x16x32_bf16 v[78:81], v[216:219], v[236:239], v[78:81]
	ds_read_b128 v[182:185], v160 offset:44032
	v_mfma_f32_16x16x32_bf16 v[74:77], v[216:219], v[240:243], v[74:77]
	v_mfma_f32_16x16x32_bf16 v[70:73], v[216:219], v[244:247], v[70:73]
	ds_read_b128 v[130:133], v161 offset:24576
	v_mfma_f32_16x16x32_bf16 v[66:69], v[216:219], v[248:251], v[66:69]
	v_mfma_f32_16x16x32_bf16 v[62:65], v[220:223], v[236:239], v[62:65]
	ds_read_b128 v[134:137], v161 offset:25600
	v_mfma_f32_16x16x32_bf16 v[58:61], v[220:223], v[240:243], v[58:61]
	v_mfma_f32_16x16x32_bf16 v[54:57], v[220:223], v[244:247], v[54:57]
	ds_read_b128 v[138:141], v161 offset:26624
	v_mfma_f32_16x16x32_bf16 v[50:53], v[220:223], v[248:251], v[50:53]
	v_mfma_f32_16x16x32_bf16 v[46:49], v[224:227], v[236:239], v[46:49]
	ds_read_b128 v[142:145], v161 offset:27648
	v_mfma_f32_16x16x32_bf16 v[42:45], v[224:227], v[240:243], v[42:45]
	v_mfma_f32_16x16x32_bf16 v[38:41], v[224:227], v[244:247], v[38:41]
	ds_read_b128 v[146:149], v161 offset:28672
	v_mfma_f32_16x16x32_bf16 v[34:37], v[224:227], v[248:251], v[34:37]
	v_mfma_f32_16x16x32_bf16 v[30:33], v[228:231], v[236:239], v[30:33]
	ds_read_b128 v[150:153], v161 offset:29696
	v_mfma_f32_16x16x32_bf16 v[26:29], v[228:231], v[240:243], v[26:29]
	v_mfma_f32_16x16x32_bf16 v[22:25], v[228:231], v[244:247], v[22:25]
	ds_read_b128 v[162:165], v161 offset:30720
	v_mfma_f32_16x16x32_bf16 v[18:21], v[228:231], v[248:251], v[18:21]
	v_mfma_f32_16x16x32_bf16 v[14:17], v[232:235], v[236:239], v[14:17]
	ds_read_b128 v[166:169], v161 offset:31744
	v_mfma_f32_16x16x32_bf16 v[10:13], v[232:235], v[240:243], v[10:13]
	v_mfma_f32_16x16x32_bf16 v[6:9], v[232:235], v[244:247], v[6:9]
	v_mfma_f32_16x16x32_bf16 v[2:5], v[232:235], v[248:251], v[2:5]
	s_setprio 0
	s_min_u32 s11, s11, 0xac
	s_lshl_b32 s11, s11, 6
	s_addk_i32 s11, 0xc0
	s_waitcnt vmcnt(0) lgkmcnt(0)
	s_barrier
	s_setprio 1
	s_add_u32 m0, s98, 0x6000
	v_mfma_f32_16x16x32_bf16 v[126:129], v[130:133], v[170:173], v[126:129]
	buffer_load_dwordx4 v0, s[20:23], s11 offen lds
	s_add_u32 m0, m0, 0x1000
	v_mfma_f32_16x16x32_bf16 v[122:125], v[130:133], v[174:177], v[122:125]
	buffer_load_dwordx4 v154, s[20:23], s11 offen lds
	s_add_u32 m0, m0, 0x1000
	v_mfma_f32_16x16x32_bf16 v[118:121], v[130:133], v[178:181], v[118:121]
	buffer_load_dwordx4 v155, s[20:23], s11 offen lds
	s_add_u32 m0, m0, 0x1000
	v_mfma_f32_16x16x32_bf16 v[114:117], v[130:133], v[182:185], v[114:117]
	buffer_load_dwordx4 v156, s[20:23], s11 offen lds
	s_add_u32 m0, m0, 0x1000
	v_mfma_f32_16x16x32_bf16 v[110:113], v[134:137], v[170:173], v[110:113]
	buffer_load_dwordx4 v157, s[4:7], s11 offen lds
	s_add_u32 m0, m0, 0x1000
	v_mfma_f32_16x16x32_bf16 v[106:109], v[134:137], v[174:177], v[106:109]
	buffer_load_dwordx4 v158, s[4:7], s11 offen lds
	v_mfma_f32_16x16x32_bf16 v[102:105], v[134:137], v[178:181], v[102:105]
	ds_read_b128 v[236:239], v160 offset:16384
	v_mfma_f32_16x16x32_bf16 v[98:101], v[134:137], v[182:185], v[98:101]
	v_mfma_f32_16x16x32_bf16 v[94:97], v[138:141], v[170:173], v[94:97]
	ds_read_b128 v[240:243], v160 offset:17408
	v_mfma_f32_16x16x32_bf16 v[90:93], v[138:141], v[174:177], v[90:93]
	v_mfma_f32_16x16x32_bf16 v[86:89], v[138:141], v[178:181], v[86:89]
	ds_read_b128 v[244:247], v160 offset:18432
	v_mfma_f32_16x16x32_bf16 v[82:85], v[138:141], v[182:185], v[82:85]
	v_mfma_f32_16x16x32_bf16 v[78:81], v[142:145], v[170:173], v[78:81]
	ds_read_b128 v[248:251], v160 offset:19456
	v_mfma_f32_16x16x32_bf16 v[74:77], v[142:145], v[174:177], v[74:77]
	v_mfma_f32_16x16x32_bf16 v[70:73], v[142:145], v[178:181], v[70:73]
	ds_read_b128 v[186:189], v161
	v_mfma_f32_16x16x32_bf16 v[66:69], v[142:145], v[182:185], v[66:69]
	v_mfma_f32_16x16x32_bf16 v[62:65], v[146:149], v[170:173], v[62:65]
	ds_read_b128 v[190:193], v161 offset:1024
	v_mfma_f32_16x16x32_bf16 v[58:61], v[146:149], v[174:177], v[58:61]
	v_mfma_f32_16x16x32_bf16 v[54:57], v[146:149], v[178:181], v[54:57]
	ds_read_b128 v[212:215], v161 offset:2048
	v_mfma_f32_16x16x32_bf16 v[50:53], v[146:149], v[182:185], v[50:53]
	v_mfma_f32_16x16x32_bf16 v[46:49], v[150:153], v[170:173], v[46:49]
	ds_read_b128 v[216:219], v161 offset:3072
	v_mfma_f32_16x16x32_bf16 v[42:45], v[150:153], v[174:177], v[42:45]
	v_mfma_f32_16x16x32_bf16 v[38:41], v[150:153], v[178:181], v[38:41]
	ds_read_b128 v[220:223], v161 offset:4096
	v_mfma_f32_16x16x32_bf16 v[34:37], v[150:153], v[182:185], v[34:37]
	v_mfma_f32_16x16x32_bf16 v[30:33], v[162:165], v[170:173], v[30:33]
	ds_read_b128 v[224:227], v161 offset:5120
	v_mfma_f32_16x16x32_bf16 v[26:29], v[162:165], v[174:177], v[26:29]
	v_mfma_f32_16x16x32_bf16 v[22:25], v[162:165], v[178:181], v[22:25]
	ds_read_b128 v[228:231], v161 offset:6144
	v_mfma_f32_16x16x32_bf16 v[18:21], v[162:165], v[182:185], v[18:21]
	v_mfma_f32_16x16x32_bf16 v[14:17], v[166:169], v[170:173], v[14:17]
	ds_read_b128 v[232:235], v161 offset:7168
	v_mfma_f32_16x16x32_bf16 v[10:13], v[166:169], v[174:177], v[10:13]
	v_mfma_f32_16x16x32_bf16 v[6:9], v[166:169], v[178:181], v[6:9]
	v_mfma_f32_16x16x32_bf16 v[2:5], v[166:169], v[182:185], v[2:5]
	s_setprio 0
	s_addk_i32 s10, 0x80
	s_mov_b32 s11, s12
	s_waitcnt vmcnt(0) lgkmcnt(0)
	s_barrier
	s_cbranch_vccnz .LBB0_37
	s_lshl_b32 s17, s8, 8
	s_sub_i32 s18, s17, s9
	s_mov_b32 s10, 0
	s_mov_b64 s[6:7], -1
	s_branch .LBB0_40

; DI int tidx() { int t = __builtin_amdgcn_workitem_id_x(); asm volatile("" : "+v"(t)); return t; }
; DI int bidx() { int t = __builtin_amdgcn_workgroup_id_x(); asm volatile("" : "+s"(t)); return t; }
; DI int gdim() { int t = (int)__ockl_get_num_groups(0); asm volatile("" : "+s"(t)); return t; }
; DI brsrc_t make_rsrc(const void* p) { return __builtin_amdgcn_make_buffer_rsrc((void*)p, 0, 0x7fffffff, 0x00020000); }
; DI void cfence() { asm volatile("" ::: "memory"); }
; DI int swz4(int row) { const int g = (row >> 2) & 3; return ((g << 1) ^ ((g >> 1) * 3)) & 3; }
; DI void gemm256_kloop(f32x4 (&acc)[8][4], const bf16_t* __restrict__ A, int lda, const bf16_t* __restrict__ Bt, int ldb,
;                       int K, int b, int s0, int col0, char* smem) {
;   const int tid = tidx(), lane = tid & 63, wid = tid >> 6;
;   const int wr = wid >> 1, wc = wid & 1, fr = lane & 15, fq = lane >> 4;
;   const int lrow = tid >> 2, lkc = tid & 3;
;   const brsrc_t rA = make_rsrc(A), rB = make_rsrc(Bt);
;   unsigned aoff[4];
; #pragma unroll
;   for (int j = 0; j < 4; ++j) {
;     int s = s0 + lrow + 64 * j;
;     s = s < 0 ? 0 : (s > SB - 1 ? SB - 1 : s);
;     aoff[j] = ((unsigned)(b * SB + s) * (unsigned)lda + lkc * 8) * 2u;
;   }
;   const unsigned boff = ((unsigned)(col0 + lrow) * (unsigned)ldb + lkc * 8) * 2u;
;   const unsigned bstep = 64u * (unsigned)ldb * 2u;
;   const int wofs = lrow * 64 + ((lkc ^ swz4(lrow)) << 4);
;   const int nk = K >> 5;
;   u32x4 xa[4], xb[2], ya[4], yb[2];
;     ...
;   GLOAD2(xa, xb, 0);
;   GLOAD2(ya, yb, 1);
;   cfence();
;   LSTORE2(xa, xb, 0);
;   __syncthreads();
;   const int co = ((fq ^ swz4(fr)) << 4);
;   const int aofs = (wr * 128 + fr) * 64 + co, bofs = (wc * 64 + fr) * 64 + co;
; template <class Epi>
; DI void gemm256_phase_plain(const bf16_t* A, int lda, const bf16_t* Bt, int ldb, int K, int ntn, char* smem, const Epi& epi,
;                             bool skip_ctx = false) {
;     ...
;     const int total = 128 * ntn;
;     for (int it = bidx(); it < total; it += gdim()) {
;       const int mt = it / ntn, nt = it - mt * ntn;
;       const int mt2 = mt + 1 + (mt >= 64 ? 1 : 0);
;       gemm256_item_plain(A, lda, Bt, ldb, K, ntn, smem, epi, mt2 * ntn + nt);
.LBB0_58:
	s_ashr_i32 s1, s14, 31
	s_lshr_b32 s1, s1, 28
	s_add_i32 s1, s14, s1
	s_lshr_b32 s8, s1, 4
	s_and_b32 s1, s1, -16
	s_sub_i32 s1, s14, s1
	s_cmpk_gt_i32 s14, 0x3ff
	s_cselect_b64 s[6:7], -1, 0
	s_cmp_lg_u64 s[6:7], 0
	s_addc_u32 s6, s8, 0
	s_lshl_b32 s6, s6, 4
	s_add_i32 s1, s6, s1
	s_add_i32 s6, s1, 16
	s_ashr_i32 s1, s6, 31
	s_lshr_b32 s1, s1, 28
	s_add_i32 s1, s6, s1
	s_ashr_i32 s8, s1, 4
	s_mul_hi_i32 s1, s6, 0x7e07e07f
	s_lshr_b32 s7, s1, 31
	s_ashr_i32 s1, s1, 9
	s_add_i32 s1, s1, s7
	s_mul_i32 s7, s1, 0xffffffbf
	s_waitcnt vmcnt(0)
	v_mov_b32_e32 v30, v194
	s_add_i32 s7, s7, s8
	s_lshl_b32 s9, s8, 11
	v_ashrrev_i32_e32 v31, 2, v30
	v_lshl_add_u32 v2, s7, 8, v31
	v_max_i32_e32 v4, 0xffffffc0, v2
	s_lshl_b32 s6, s6, 7
	v_add_u32_e32 v4, 64, v4
	s_sub_i32 s15, s6, s9
	s_mul_i32 s9, s1, 0x4100
	v_min_u32_e32 v4, 0x40ff, v4
	v_and_b32_e32 v32, 3, v30
	v_add_u32_e32 v4, s9, v4
	v_lshlrev_b32_e32 v3, 4, v32
	v_mul_lo_u32 v4, v4, s78
	v_med3_i32 v0, v2, 0, v201
	v_or_b32_e32 v154, v4, v3
	v_max_i32_e32 v4, 0xffffff80, v2
	v_max_i32_e32 v2, 0xffffff40, v2
	v_add_u32_e32 v2, 0xc0, v2
	v_min_u32_e32 v2, 0x40ff, v2
	v_add_u32_e32 v2, s9, v2
	v_mul_lo_u32 v2, v2, s78
	v_add_u32_e32 v4, 0x80, v4
	v_or_b32_e32 v156, v2, v3
	v_add_u32_e32 v2, s15, v31
	v_add_u32_e32 v0, s9, v0
	v_min_u32_e32 v4, 0x40ff, v4
	v_mul_lo_u32 v2, v2, s78
	v_mul_lo_u32 v0, v0, s78
	v_add_u32_e32 v4, s9, v4
	v_or_b32_e32 v157, v2, v3
	v_or_b32_e32 v0, v0, v3
	v_mul_lo_u32 v4, v4, s78
	s_mov_b32 s6, s22
	s_mov_b32 s7, s23
	v_add_u32_e32 v158, 0xb2000, v157
	v_or_b32_e32 v155, v4, v3
	v_bfe_u32 v162, v194, 4, 2
	v_lshlrev_b32_e32 v162, 2, v162
	v_mov_b32_e32 v163, 0x1320
	v_lshrrev_b32_e32 v162, v162, v163
	v_and_b32_e32 v162, 3, v162
	v_lshlrev_b32_e32 v162, 4, v162
	v_xor_b32_e32 v0, v0, v162
	v_xor_b32_e32 v154, v154, v162
	v_xor_b32_e32 v155, v155, v162
	v_xor_b32_e32 v156, v156, v162
	v_xor_b32_e32 v157, v157, v162
	v_xor_b32_e32 v158, v158, v162
	v_lshrrev_b32_e32 v163, 6, v194
	s_nop 0
	v_readfirstlane_b32 s98, v163
	s_lshl_b32 s98, s98, 10
	s_mov_b32 m0, s98
	s_nop 0
	buffer_load_dwordx4 v0, s[20:23], 0 offen lds
	s_add_u32 m0, m0, 0x1000
	s_nop 0
	buffer_load_dwordx4 v154, s[20:23], 0 offen lds
	s_add_u32 m0, m0, 0x1000
	s_nop 0
	buffer_load_dwordx4 v155, s[20:23], 0 offen lds
	s_add_u32 m0, m0, 0x1000
	s_nop 0
	buffer_load_dwordx4 v156, s[20:23], 0 offen lds
	s_add_u32 m0, m0, 0x1000
	s_nop 0
	buffer_load_dwordx4 v157, s[4:7], 0 offen lds
	s_add_u32 m0, m0, 0x1000
	s_nop 0
	buffer_load_dwordx4 v158, s[4:7], 0 offen lds
	s_add_u32 m0, s98, 0x6000
	s_nop 0
	buffer_load_dwordx4 v0, s[20:23], 64 offen lds
	s_add_u32 m0, m0, 0x1000
	s_nop 0
	buffer_load_dwordx4 v154, s[20:23], 64 offen lds
	s_add_u32 m0, m0, 0x1000
	s_nop 0
	buffer_load_dwordx4 v155, s[20:23], 64 offen lds
	s_add_u32 m0, m0, 0x1000
	s_nop 0
	buffer_load_dwordx4 v156, s[20:23], 64 offen lds
	s_add_u32 m0, m0, 0x1000
	s_nop 0
	buffer_load_dwordx4 v157, s[4:7], 64 offen lds
	s_add_u32 m0, m0, 0x1000
	s_nop 0
	buffer_load_dwordx4 v158, s[4:7], 64 offen lds
	v_lshrrev_b32_e32 v35, 1, v30
	v_bfe_i32 v34, v30, 3, 1
	v_lshlrev_b32_e32 v37, 6, v31
	v_lshrrev_b32_e32 v31, 1, v31
	v_and_b32_e32 v35, 2, v35
	v_bfe_i32 v33, v30, 5, 1
	v_and_b32_e32 v31, 2, v31
	v_bitop3_b32 v34, v34, v35, 3 bitop3:0x6c
	v_bitop3_b32 v31, v33, v31, 3 bitop3:0x6c
	v_lshlrev_b32_e32 v33, 4, v34
	v_lshlrev_b32_e32 v36, 6, v30
	v_xor_b32_e32 v31, v31, v32
	v_bitop3_b32 v30, v33, v30, 48 bitop3:0x78
	s_movk_i32 s12, 0x13c0
	v_mov_b32_e32 v2, 0
	v_lshl_or_b32 v159, v31, 4, v37
	v_and_or_b32 v160, v36, s12, v30
	s_movk_i32 s12, 0xe3c0
	s_mov_b32 s11, 0
	s_movk_i32 s10, 0x80
	v_mov_b32_e32 v3, v2
	v_mov_b32_e32 v4, v2
	v_mov_b32_e32 v5, v2
	v_and_or_b32 v161, v36, s12, v30
	v_mov_b32_e32 v30, v2
	v_mov_b32_e32 v31, v2
	v_mov_b32_e32 v32, v2
	v_mov_b32_e32 v33, v2
	v_mov_b32_e32 v34, v2
	v_mov_b32_e32 v35, v2
	v_mov_b32_e32 v36, v2
	v_mov_b32_e32 v37, v2
	v_mov_b32_e32 v38, v2
	v_mov_b32_e32 v39, v2
	v_mov_b32_e32 v40, v2
	v_mov_b32_e32 v41, v2
	v_mov_b32_e32 v42, v2
	v_mov_b32_e32 v43, v2
	v_mov_b32_e32 v44, v2
	v_mov_b32_e32 v45, v2
	v_mov_b32_e32 v46, v2
	v_mov_b32_e32 v47, v2
	v_mov_b32_e32 v48, v2
	v_mov_b32_e32 v49, v2
	v_mov_b32_e32 v50, v2
	v_mov_b32_e32 v51, v2
	v_mov_b32_e32 v52, v2
	v_mov_b32_e32 v53, v2
	v_mov_b32_e32 v54, v2
	v_mov_b32_e32 v6, v2
	v_mov_b32_e32 v7, v2
	v_mov_b32_e32 v8, v2
	v_mov_b32_e32 v9, v2
	v_mov_b32_e32 v10, v2
	v_mov_b32_e32 v11, v2
	v_mov_b32_e32 v12, v2
	v_mov_b32_e32 v13, v2
	v_mov_b32_e32 v14, v2
	v_mov_b32_e32 v15, v2
	v_mov_b32_e32 v16, v2
	v_mov_b32_e32 v17, v2
	v_mov_b32_e32 v18, v2
	v_mov_b32_e32 v19, v2
	v_mov_b32_e32 v20, v2
	v_mov_b32_e32 v21, v2
	v_mov_b32_e32 v22, v2
	v_mov_b32_e32 v23, v2
	v_mov_b32_e32 v24, v2
	v_mov_b32_e32 v25, v2
	v_mov_b32_e32 v26, v2
	v_mov_b32_e32 v27, v2
	v_mov_b32_e32 v28, v2
	v_mov_b32_e32 v29, v2
	v_mov_b32_e32 v55, v2
	v_mov_b32_e32 v56, v2
	v_mov_b32_e32 v57, v2
	v_mov_b32_e32 v58, v2
	v_mov_b32_e32 v59, v2
	v_mov_b32_e32 v60, v2
	v_mov_b32_e32 v61, v2
	v_mov_b32_e32 v62, v2
	v_mov_b32_e32 v63, v2
	v_mov_b32_e32 v64, v2
	v_mov_b32_e32 v65, v2
	v_mov_b32_e32 v66, v2
	v_mov_b32_e32 v67, v2
	v_mov_b32_e32 v68, v2
	v_mov_b32_e32 v69, v2
	v_mov_b32_e32 v70, v2
	v_mov_b32_e32 v71, v2
	v_mov_b32_e32 v72, v2
	v_mov_b32_e32 v73, v2
	v_mov_b32_e32 v74, v2
	v_mov_b32_e32 v75, v2
	v_mov_b32_e32 v76, v2
	v_mov_b32_e32 v77, v2
	v_mov_b32_e32 v78, v2
	v_mov_b32_e32 v79, v2
	v_mov_b32_e32 v80, v2
	v_mov_b32_e32 v81, v2
	v_mov_b32_e32 v82, v2
	v_mov_b32_e32 v83, v2
	v_mov_b32_e32 v84, v2
	v_mov_b32_e32 v85, v2
	v_mov_b32_e32 v86, v2
	v_mov_b32_e32 v87, v2
	v_mov_b32_e32 v88, v2
	v_mov_b32_e32 v89, v2
	v_mov_b32_e32 v90, v2
	v_mov_b32_e32 v91, v2
	v_mov_b32_e32 v92, v2
	v_mov_b32_e32 v93, v2
	v_mov_b32_e32 v94, v2
	v_mov_b32_e32 v95, v2
	v_mov_b32_e32 v96, v2
	v_mov_b32_e32 v97, v2
	v_mov_b32_e32 v98, v2
	v_mov_b32_e32 v99, v2
	v_mov_b32_e32 v100, v2
	v_mov_b32_e32 v101, v2
	v_mov_b32_e32 v102, v2
	v_mov_b32_e32 v103, v2
	v_mov_b32_e32 v104, v2
	v_mov_b32_e32 v105, v2
	v_mov_b32_e32 v106, v2
	v_mov_b32_e32 v107, v2
	v_mov_b32_e32 v108, v2
	v_mov_b32_e32 v109, v2
	v_mov_b32_e32 v110, v2
	v_mov_b32_e32 v111, v2
	v_mov_b32_e32 v112, v2
	v_mov_b32_e32 v113, v2
	v_mov_b32_e32 v114, v2
	v_mov_b32_e32 v115, v2
	v_mov_b32_e32 v116, v2
	v_mov_b32_e32 v117, v2
	v_mov_b32_e32 v118, v2
	v_mov_b32_e32 v119, v2
	v_mov_b32_e32 v120, v2
	v_mov_b32_e32 v121, v2
	v_mov_b32_e32 v122, v2
	v_mov_b32_e32 v123, v2
	v_mov_b32_e32 v124, v2
	v_mov_b32_e32 v125, v2
	v_mov_b32_e32 v126, v2
	v_mov_b32_e32 v127, v2
	v_mov_b32_e32 v128, v2
	v_mov_b32_e32 v129, v2
	s_waitcnt vmcnt(6) lgkmcnt(0)
	s_barrier
; DI void cfence() { asm volatile("" ::: "memory"); }
; DI int swz4(int row) { const int g = (row >> 2) & 3; return ((g << 1) ^ ((g >> 1) * 3)) & 3; }
; #define LSTORE2(RA, RB, P)                                       \
;   {                                                              \
;     char* dA_ = smem + (P) * 24576 + wofs;                       \
;     _Pragma("unroll") for (int j = 0; j < 4; ++j) *(u32x4*)(dA_ + j * 4096) = RA[j]; \
;     _Pragma("unroll") for (int j = 0; j < 2; ++j) *(u32x4*)(dA_ + 16384 + j * 4096) = RB[j]; \
;   }
; DI void gemm256_kloop(f32x4 (&acc)[8][4], const bf16_t* __restrict__ A, int lda, const bf16_t* __restrict__ Bt, int ldb,
;                       int K, int b, int s0, int col0, char* smem) {
;     ...
;   GLOAD2(xa, xb, 0);
;   GLOAD2(ya, yb, 1);
;   cfence();
;   LSTORE2(xa, xb, 0);
;   __syncthreads();
;   const int co = ((fq ^ swz4(fr)) << 4);
;   const int aofs = (wr * 128 + fr) * 64 + co, bofs = (wc * 64 + fr) * 64 + co;
	ds_read_b128 v[236:239], v160 offset:16384
	ds_read_b128 v[240:243], v160 offset:17408
	ds_read_b128 v[244:247], v160 offset:18432
	ds_read_b128 v[248:251], v160 offset:19456
	ds_read_b128 v[186:189], v161
	ds_read_b128 v[190:193], v161 offset:1024
	ds_read_b128 v[212:215], v161 offset:2048
	ds_read_b128 v[216:219], v161 offset:3072
	ds_read_b128 v[220:223], v161 offset:4096
	ds_read_b128 v[224:227], v161 offset:5120
	ds_read_b128 v[228:231], v161 offset:6144
	ds_read_b128 v[232:235], v161 offset:7168
	s_waitcnt vmcnt(0) lgkmcnt(0)
	s_barrier
; DI void cfence() { asm volatile("" ::: "memory"); }
; DI int swz4(int row) { const int g = (row >> 2) & 3; return ((g << 1) ^ ((g >> 1) * 3)) & 3; }
; #define LSTORE2(RA, RB, P)                                       \
;   {                                                              \
;     char* dA_ = smem + (P) * 24576 + wofs;                       \
;     _Pragma("unroll") for (int j = 0; j < 4; ++j) *(u32x4*)(dA_ + j * 4096) = RA[j]; \
;     _Pragma("unroll") for (int j = 0; j < 2; ++j) *(u32x4*)(dA_ + 16384 + j * 4096) = RB[j]; \
;   }
; DI void gemm256_kloop(f32x4 (&acc)[8][4], const bf16_t* __restrict__ A, int lda, const bf16_t* __restrict__ Bt, int ldb,
;                       int K, int b, int s0, int col0, char* smem) {
;     ...
;   GLOAD2(xa, xb, 0);
;   GLOAD2(ya, yb, 1);
;   cfence();
;   LSTORE2(xa, xb, 0);
;   __syncthreads();
;   const int co = ((fq ^ swz4(fr)) << 4);
;   const int aofs = (wr * 128 + fr) * 64 + co, bofs = (wc * 64 + fr) * 64 + co;
;   for (int kt = 0; kt < nk; kt += 2) {
;     GLOAD2(xa, xb, kt + 2);
;     cfence();
;     COMPUTE2(0);
;     LSTORE2(ya, yb, 1);
;     __syncthreads();
;     if (kt + 1 < nk) {
;       GLOAD2(ya, yb, kt + 3);
;       cfence();
;       COMPUTE2(1);
;       LSTORE2(xa, xb, 0);
;       __syncthreads();
;     }
;   }
.LBB0_59:
	s_add_i32 s12, s11, 2
	s_cmpk_lt_u32 s11, 0xae
	s_cselect_b64 s[16:17], -1, 0
	s_and_b64 vcc, s[16:17], exec
	s_cselect_b32 s13, s10, 0x2bc0
	s_setprio 1
	s_mov_b32 m0, s98
	v_mfma_f32_16x16x32_bf16 v[126:129], v[186:189], v[236:239], v[126:129]
	buffer_load_dwordx4 v0, s[20:23], s13 offen lds
	s_add_u32 m0, m0, 0x1000
	v_mfma_f32_16x16x32_bf16 v[122:125], v[186:189], v[240:243], v[122:125]
	buffer_load_dwordx4 v154, s[20:23], s13 offen lds
	s_add_u32 m0, m0, 0x1000
	v_mfma_f32_16x16x32_bf16 v[118:121], v[186:189], v[244:247], v[118:121]
	buffer_load_dwordx4 v155, s[20:23], s13 offen lds
	s_add_u32 m0, m0, 0x1000
	v_mfma_f32_16x16x32_bf16 v[114:117], v[186:189], v[248:251], v[114:117]
	buffer_load_dwordx4 v156, s[20:23], s13 offen lds
	s_add_u32 m0, m0, 0x1000
	v_mfma_f32_16x16x32_bf16 v[110:113], v[190:193], v[236:239], v[110:113]
	buffer_load_dwordx4 v157, s[4:7], s13 offen lds
	s_add_u32 m0, m0, 0x1000
	v_mfma_f32_16x16x32_bf16 v[106:109], v[190:193], v[240:243], v[106:109]
	buffer_load_dwordx4 v158, s[4:7], s13 offen lds
	v_mfma_f32_16x16x32_bf16 v[102:105], v[190:193], v[244:247], v[102:105]
	ds_read_b128 v[170:173], v160 offset:40960
	v_mfma_f32_16x16x32_bf16 v[98:101], v[190:193], v[248:251], v[98:101]
	v_mfma_f32_16x16x32_bf16 v[94:97], v[212:215], v[236:239], v[94:97]
	ds_read_b128 v[174:177], v160 offset:41984
	v_mfma_f32_16x16x32_bf16 v[90:93], v[212:215], v[240:243], v[90:93]
	v_mfma_f32_16x16x32_bf16 v[86:89], v[212:215], v[244:247], v[86:89]
	ds_read_b128 v[178:181], v160 offset:43008
	v_mfma_f32_16x16x32_bf16 v[82:85], v[212:215], v[248:251], v[82:85]
	v_mfma_f32_16x16x32_bf16 v[78:81], v[216:219], v[236:239], v[78:81]
	ds_read_b128 v[182:185], v160 offset:44032
	v_mfma_f32_16x16x32_bf16 v[74:77], v[216:219], v[240:243], v[74:77]
	v_mfma_f32_16x16x32_bf16 v[70:73], v[216:219], v[244:247], v[70:73]
	ds_read_b128 v[130:133], v161 offset:24576
	v_mfma_f32_16x16x32_bf16 v[66:69], v[216:219], v[248:251], v[66:69]
	v_mfma_f32_16x16x32_bf16 v[62:65], v[220:223], v[236:239], v[62:65]
	ds_read_b128 v[134:137], v161 offset:25600
	v_mfma_f32_16x16x32_bf16 v[58:61], v[220:223], v[240:243], v[58:61]
	v_mfma_f32_16x16x32_bf16 v[54:57], v[220:223], v[244:247], v[54:57]
	ds_read_b128 v[138:141], v161 offset:26624
	v_mfma_f32_16x16x32_bf16 v[50:53], v[220:223], v[248:251], v[50:53]
	v_mfma_f32_16x16x32_bf16 v[46:49], v[224:227], v[236:239], v[46:49]
	ds_read_b128 v[142:145], v161 offset:27648
	v_mfma_f32_16x16x32_bf16 v[42:45], v[224:227], v[240:243], v[42:45]
	v_mfma_f32_16x16x32_bf16 v[38:41], v[224:227], v[244:247], v[38:41]
	ds_read_b128 v[146:149], v161 offset:28672
	v_mfma_f32_16x16x32_bf16 v[34:37], v[224:227], v[248:251], v[34:37]
	v_mfma_f32_16x16x32_bf16 v[30:33], v[228:231], v[236:239], v[30:33]
	ds_read_b128 v[150:153], v161 offset:29696
	v_mfma_f32_16x16x32_bf16 v[26:29], v[228:231], v[240:243], v[26:29]
	v_mfma_f32_16x16x32_bf16 v[22:25], v[228:231], v[244:247], v[22:25]
	ds_read_b128 v[162:165], v161 offset:30720
	v_mfma_f32_16x16x32_bf16 v[18:21], v[228:231], v[248:251], v[18:21]
	v_mfma_f32_16x16x32_bf16 v[14:17], v[232:235], v[236:239], v[14:17]
	ds_read_b128 v[166:169], v161 offset:31744
	v_mfma_f32_16x16x32_bf16 v[10:13], v[232:235], v[240:243], v[10:13]
	v_mfma_f32_16x16x32_bf16 v[6:9], v[232:235], v[244:247], v[6:9]
	v_mfma_f32_16x16x32_bf16 v[2:5], v[232:235], v[248:251], v[2:5]
	s_setprio 0
	s_min_u32 s11, s11, 0xac
	s_lshl_b32 s11, s11, 6
	s_addk_i32 s11, 0xc0
	s_waitcnt vmcnt(0) lgkmcnt(0)
	s_barrier
	s_setprio 1
	s_add_u32 m0, s98, 0x6000
	v_mfma_f32_16x16x32_bf16 v[126:129], v[130:133], v[170:173], v[126:129]
	buffer_load_dwordx4 v0, s[20:23], s11 offen lds
	s_add_u32 m0, m0, 0x1000
	v_mfma_f32_16x16x32_bf16 v[122:125], v[130:133], v[174:177], v[122:125]
	buffer_load_dwordx4 v154, s[20:23], s11 offen lds
	s_add_u32 m0, m0, 0x1000
	v_mfma_f32_16x16x32_bf16 v[118:121], v[130:133], v[178:181], v[118:121]
	buffer_load_dwordx4 v155, s[20:23], s11 offen lds
	s_add_u32 m0, m0, 0x1000
	v_mfma_f32_16x16x32_bf16 v[114:117], v[130:133], v[182:185], v[114:117]
	buffer_load_dwordx4 v156, s[20:23], s11 offen lds
	s_add_u32 m0, m0, 0x1000
	v_mfma_f32_16x16x32_bf16 v[110:113], v[134:137], v[170:173], v[110:113]
	buffer_load_dwordx4 v157, s[4:7], s11 offen lds
	s_add_u32 m0, m0, 0x1000
	v_mfma_f32_16x16x32_bf16 v[106:109], v[134:137], v[174:177], v[106:109]
	buffer_load_dwordx4 v158, s[4:7], s11 offen lds
	v_mfma_f32_16x16x32_bf16 v[102:105], v[134:137], v[178:181], v[102:105]
	ds_read_b128 v[236:239], v160 offset:16384
	v_mfma_f32_16x16x32_bf16 v[98:101], v[134:137], v[182:185], v[98:101]
	v_mfma_f32_16x16x32_bf16 v[94:97], v[138:141], v[170:173], v[94:97]
	ds_read_b128 v[240:243], v160 offset:17408
	v_mfma_f32_16x16x32_bf16 v[90:93], v[138:141], v[174:177], v[90:93]
	v_mfma_f32_16x16x32_bf16 v[86:89], v[138:141], v[178:181], v[86:89]
	ds_read_b128 v[244:247], v160 offset:18432
	v_mfma_f32_16x16x32_bf16 v[82:85], v[138:141], v[182:185], v[82:85]
	v_mfma_f32_16x16x32_bf16 v[78:81], v[142:145], v[170:173], v[78:81]
	ds_read_b128 v[248:251], v160 offset:19456
	v_mfma_f32_16x16x32_bf16 v[74:77], v[142:145], v[174:177], v[74:77]
	v_mfma_f32_16x16x32_bf16 v[70:73], v[142:145], v[178:181], v[70:73]
	ds_read_b128 v[186:189], v161
	v_mfma_f32_16x16x32_bf16 v[66:69], v[142:145], v[182:185], v[66:69]
	v_mfma_f32_16x16x32_bf16 v[62:65], v[146:149], v[170:173], v[62:65]
	ds_read_b128 v[190:193], v161 offset:1024
	v_mfma_f32_16x16x32_bf16 v[58:61], v[146:149], v[174:177], v[58:61]
	v_mfma_f32_16x16x32_bf16 v[54:57], v[146:149], v[178:181], v[54:57]
	ds_read_b128 v[212:215], v161 offset:2048
	v_mfma_f32_16x16x32_bf16 v[50:53], v[146:149], v[182:185], v[50:53]
	v_mfma_f32_16x16x32_bf16 v[46:49], v[150:153], v[170:173], v[46:49]
	ds_read_b128 v[216:219], v161 offset:3072
	v_mfma_f32_16x16x32_bf16 v[42:45], v[150:153], v[174:177], v[42:45]
	v_mfma_f32_16x16x32_bf16 v[38:41], v[150:153], v[178:181], v[38:41]
	ds_read_b128 v[220:223], v161 offset:4096
	v_mfma_f32_16x16x32_bf16 v[34:37], v[150:153], v[182:185], v[34:37]
	v_mfma_f32_16x16x32_bf16 v[30:33], v[162:165], v[170:173], v[30:33]
	ds_read_b128 v[224:227], v161 offset:5120
	v_mfma_f32_16x16x32_bf16 v[26:29], v[162:165], v[174:177], v[26:29]
	v_mfma_f32_16x16x32_bf16 v[22:25], v[162:165], v[178:181], v[22:25]
	ds_read_b128 v[228:231], v161 offset:6144
	v_mfma_f32_16x16x32_bf16 v[18:21], v[162:165], v[182:185], v[18:21]
	v_mfma_f32_16x16x32_bf16 v[14:17], v[166:169], v[170:173], v[14:17]
	ds_read_b128 v[232:235], v161 offset:7168
	v_mfma_f32_16x16x32_bf16 v[10:13], v[166:169], v[174:177], v[10:13]
	v_mfma_f32_16x16x32_bf16 v[6:9], v[166:169], v[178:181], v[6:9]
	v_mfma_f32_16x16x32_bf16 v[2:5], v[166:169], v[182:185], v[2:5]
	s_setprio 0
	s_addk_i32 s10, 0x80
	s_mov_b32 s11, s12
	s_waitcnt vmcnt(0) lgkmcnt(0)
	s_barrier
	s_cbranch_vccnz .LBB0_59
	s_lshl_b32 s16, s8, 8
	s_sub_i32 s17, s16, s9
	s_mov_b32 s10, 0
	s_mov_b64 s[6:7], -1
	s_branch .LBB0_62

; DI int tidx() { int t = __builtin_amdgcn_workitem_id_x(); asm volatile("" : "+v"(t)); return t; }
; DI int bidx() { int t = __builtin_amdgcn_workgroup_id_x(); asm volatile("" : "+s"(t)); return t; }
; DI int gdim() { int t = (int)__ockl_get_num_groups(0); asm volatile("" : "+s"(t)); return t; }
; DI brsrc_t make_rsrc(const void* p) { return __builtin_amdgcn_make_buffer_rsrc((void*)p, 0, 0x7fffffff, 0x00020000); }
; DI void cfence() { asm volatile("" ::: "memory"); }
; DI int swz4(int row) { const int g = (row >> 2) & 3; return ((g << 1) ^ ((g >> 1) * 3)) & 3; }
; DI void gemm256_kloop(f32x4 (&acc)[8][4], const bf16_t* __restrict__ A, int lda, const bf16_t* __restrict__ Bt, int ldb,
;                       int K, int b, int s0, int col0, char* smem) {
;   const int tid = tidx(), lane = tid & 63, wid = tid >> 6;
;   const int wr = wid >> 1, wc = wid & 1, fr = lane & 15, fq = lane >> 4;
;   const int lrow = tid >> 2, lkc = tid & 3;
;   const brsrc_t rA = make_rsrc(A), rB = make_rsrc(Bt);
;   unsigned aoff[4];
; #pragma unroll
;   for (int j = 0; j < 4; ++j) {
;     int s = s0 + lrow + 64 * j;
;     s = s < 0 ? 0 : (s > SB - 1 ? SB - 1 : s);
;     aoff[j] = ((unsigned)(b * SB + s) * (unsigned)lda + lkc * 8) * 2u;
;   }
;   const unsigned boff = ((unsigned)(col0 + lrow) * (unsigned)ldb + lkc * 8) * 2u;
;   const unsigned bstep = 64u * (unsigned)ldb * 2u;
;   const int wofs = lrow * 64 + ((lkc ^ swz4(lrow)) << 4);
;   const int nk = K >> 5;
;   u32x4 xa[4], xb[2], ya[4], yb[2];
;     ...
;   GLOAD2(xa, xb, 0);
;   GLOAD2(ya, yb, 1);
;   cfence();
;   LSTORE2(xa, xb, 0);
;   __syncthreads();
;   const int co = ((fq ^ swz4(fr)) << 4);
;   const int aofs = (wr * 128 + fr) * 64 + co, bofs = (wc * 64 + fr) * 64 + co;
; template <class Epi>
; DI void gemm256_phase_overlap(const bf16_t* A, int lda, const bf16_t* Bt, int ldb, int K, int ntn, char* smem, const Epi& epi) {
;   const int total = 134 * ntn;
;   for (int it = bidx(); it < total; it += gdim()) {
;     int mt = it / ntn, nt = it - mt * ntn;
;     int b = mt / 67, s0 = (mt - b * 67) * 252 - 1;
;     gemm256_tile(A, lda, Bt, ldb, K, b, s0, nt * 128, smem, epi, 126);
.LBB0_80:
	s_mul_hi_i32 s4, s1, 0x2e8ba2e9
	s_lshr_b32 s5, s4, 31
	s_ashr_i32 s4, s4, 4
	s_add_i32 s4, s4, s5
	s_mul_hi_i32 s5, s1, 0x58ec3369
	s_lshr_b32 s7, s5, 31
	s_ashr_i32 s5, s5, 11
	s_add_i32 s5, s5, s7
	s_mul_i32 s7, s5, 0xffffffbd
	s_add_i32 s7, s7, s4
	s_waitcnt vmcnt(0)
	v_mov_b32_e32 v32, v194
	s_mulk_i32 s7, 0xfc
	s_movk_i32 s8, 0x1080
	v_ashrrev_i32_e32 v33, 2, v32
	v_add3_u32 v2, s7, -1, v33
	v_max_i32_e32 v4, 0xffffffc0, v2
	v_add_u32_e32 v4, 64, v4
	s_mul_i32 s7, s5, 0x4100
	v_min_u32_e32 v4, 0x40ff, v4
	v_and_b32_e32 v34, 3, v32
	v_add_u32_e32 v4, s7, v4
	v_lshlrev_b32_e32 v3, 4, v34
	v_mul_lo_u32 v4, v4, s8
	v_med3_i32 v0, v2, 0, v201
	v_or_b32_e32 v154, v4, v3
	v_max_i32_e32 v4, 0xffffff80, v2
	v_max_i32_e32 v2, 0xffffff40, v2
	v_add_u32_e32 v2, 0xc0, v2
	v_min_u32_e32 v2, 0x40ff, v2
	s_mul_i32 s6, s4, 0xffffffa8
	v_add_u32_e32 v2, s7, v2
	s_add_i32 s6, s6, s1
	v_mul_lo_u32 v2, v2, s8
	v_add_u32_e32 v4, 0x80, v4
	v_or_b32_e32 v156, v2, v3
	v_lshl_add_u32 v2, s6, 7, v33
	v_min_u32_e32 v4, 0x40ff, v4
	v_mul_lo_u32 v2, v2, s8
	v_add_u32_e32 v0, s7, v0
	v_add_u32_e32 v4, s7, v4
	v_or_b32_e32 v157, v2, v3
	v_mul_lo_u32 v0, v0, s8
	v_mul_lo_u32 v4, v4, s8
	s_mov_b32 s14, s22
	s_mov_b32 s15, s23
	v_add_u32_e32 v158, 0x42000, v157
	v_or_b32_e32 v0, v0, v3
	v_or_b32_e32 v155, v4, v3
	v_bfe_u32 v162, v194, 4, 2
	v_lshlrev_b32_e32 v162, 2, v162
	v_mov_b32_e32 v163, 0x1320
	v_lshrrev_b32_e32 v162, v162, v163
	v_and_b32_e32 v162, 3, v162
	v_lshlrev_b32_e32 v162, 4, v162
	v_xor_b32_e32 v0, v0, v162
	v_xor_b32_e32 v154, v154, v162
	v_xor_b32_e32 v155, v155, v162
	v_xor_b32_e32 v156, v156, v162
	v_xor_b32_e32 v157, v157, v162
	v_xor_b32_e32 v158, v158, v162
	v_lshrrev_b32_e32 v163, 6, v194
	s_nop 0
	v_readfirstlane_b32 s98, v163
	s_lshl_b32 s98, s98, 10
	s_mov_b32 m0, s98
	s_nop 0
	buffer_load_dwordx4 v0, s[20:23], 0 offen lds
	s_add_u32 m0, m0, 0x1000
	s_nop 0
	buffer_load_dwordx4 v154, s[20:23], 0 offen lds
	s_add_u32 m0, m0, 0x1000
	s_nop 0
	buffer_load_dwordx4 v155, s[20:23], 0 offen lds
	s_add_u32 m0, m0, 0x1000
	s_nop 0
	buffer_load_dwordx4 v156, s[20:23], 0 offen lds
	s_add_u32 m0, m0, 0x1000
	s_nop 0
	buffer_load_dwordx4 v157, s[12:15], 0 offen lds
	s_add_u32 m0, m0, 0x1000
	s_nop 0
	buffer_load_dwordx4 v158, s[12:15], 0 offen lds
	s_add_u32 m0, s98, 0x6000
	s_nop 0
	buffer_load_dwordx4 v0, s[20:23], 64 offen lds
	s_add_u32 m0, m0, 0x1000
	s_nop 0
	buffer_load_dwordx4 v154, s[20:23], 64 offen lds
	s_add_u32 m0, m0, 0x1000
	s_nop 0
	buffer_load_dwordx4 v155, s[20:23], 64 offen lds
	s_add_u32 m0, m0, 0x1000
	s_nop 0
	buffer_load_dwordx4 v156, s[20:23], 64 offen lds
	s_add_u32 m0, m0, 0x1000
	s_nop 0
	buffer_load_dwordx4 v157, s[12:15], 64 offen lds
	s_add_u32 m0, m0, 0x1000
	s_nop 0
	buffer_load_dwordx4 v158, s[12:15], 64 offen lds
	v_bfe_i32 v35, v32, 5, 1
	v_lshrrev_b32_e32 v37, 1, v32
	v_bfe_i32 v36, v32, 3, 1
	v_lshlrev_b32_e32 v39, 6, v33
	v_lshrrev_b32_e32 v33, 1, v33
	v_and_b32_e32 v35, 3, v35
	v_and_b32_e32 v37, 2, v37
	v_bitop3_b32 v33, v33, v35, 2 bitop3:0x6c
	v_bitop3_b32 v35, v36, v37, 3 bitop3:0x6c
	v_xor_b32_e32 v33, v33, v34
	v_lshlrev_b32_e32 v34, 4, v35
	v_lshlrev_b32_e32 v38, 6, v32
	v_bitop3_b32 v32, v34, v32, 48 bitop3:0x78
	s_movk_i32 s9, 0x13c0
	v_mov_b32_e32 v2, 0
	v_lshl_or_b32 v159, v33, 4, v39
	v_and_or_b32 v160, v38, s9, v32
	s_movk_i32 s9, 0xe3c0
	s_mov_b32 s8, 0
	s_movk_i32 s7, 0x80
	v_mov_b32_e32 v3, v2
	v_mov_b32_e32 v4, v2
	v_mov_b32_e32 v5, v2
	v_mov_b32_e32 v6, v2
	v_mov_b32_e32 v7, v2
	v_and_or_b32 v161, v38, s9, v32
	v_mov_b32_e32 v32, v2
	v_mov_b32_e32 v33, v2
	v_mov_b32_e32 v34, v2
	v_mov_b32_e32 v35, v2
	v_mov_b32_e32 v36, v2
	v_mov_b32_e32 v37, v2
	v_mov_b32_e32 v38, v2
	v_mov_b32_e32 v39, v2
	v_mov_b32_e32 v40, v2
	v_mov_b32_e32 v41, v2
	v_mov_b32_e32 v42, v2
	v_mov_b32_e32 v43, v2
	v_mov_b32_e32 v44, v2
	v_mov_b32_e32 v45, v2
	v_mov_b32_e32 v46, v2
	v_mov_b32_e32 v47, v2
	v_mov_b32_e32 v48, v2
	v_mov_b32_e32 v49, v2
	v_mov_b32_e32 v50, v2
	v_mov_b32_e32 v51, v2
	v_mov_b32_e32 v52, v2
	v_mov_b32_e32 v53, v2
	v_mov_b32_e32 v54, v2
	v_mov_b32_e32 v55, v2
	v_mov_b32_e32 v8, v2
	v_mov_b32_e32 v9, v2
	v_mov_b32_e32 v10, v2
	v_mov_b32_e32 v11, v2
	v_mov_b32_e32 v12, v2
	v_mov_b32_e32 v13, v2
	v_mov_b32_e32 v14, v2
	v_mov_b32_e32 v15, v2
	v_mov_b32_e32 v16, v2
	v_mov_b32_e32 v17, v2
	v_mov_b32_e32 v18, v2
	v_mov_b32_e32 v19, v2
	v_mov_b32_e32 v20, v2
	v_mov_b32_e32 v21, v2
	v_mov_b32_e32 v22, v2
	v_mov_b32_e32 v23, v2
	v_mov_b32_e32 v24, v2
	v_mov_b32_e32 v25, v2
	v_mov_b32_e32 v26, v2
	v_mov_b32_e32 v27, v2
	v_mov_b32_e32 v28, v2
	v_mov_b32_e32 v29, v2
	v_mov_b32_e32 v30, v2
	v_mov_b32_e32 v31, v2
	v_mov_b32_e32 v56, v2
	v_mov_b32_e32 v57, v2
	v_mov_b32_e32 v58, v2
	v_mov_b32_e32 v59, v2
	v_mov_b32_e32 v60, v2
	v_mov_b32_e32 v61, v2
	v_mov_b32_e32 v62, v2
	v_mov_b32_e32 v63, v2
	v_mov_b32_e32 v64, v2
	v_mov_b32_e32 v65, v2
	v_mov_b32_e32 v66, v2
	v_mov_b32_e32 v67, v2
	v_mov_b32_e32 v68, v2
	v_mov_b32_e32 v69, v2
	v_mov_b32_e32 v70, v2
	v_mov_b32_e32 v71, v2
	v_mov_b32_e32 v72, v2
	v_mov_b32_e32 v73, v2
	v_mov_b32_e32 v74, v2
	v_mov_b32_e32 v75, v2
	v_mov_b32_e32 v76, v2
	v_mov_b32_e32 v77, v2
	v_mov_b32_e32 v78, v2
	v_mov_b32_e32 v79, v2
	v_mov_b32_e32 v80, v2
	v_mov_b32_e32 v81, v2
	v_mov_b32_e32 v82, v2
	v_mov_b32_e32 v83, v2
	v_mov_b32_e32 v84, v2
	v_mov_b32_e32 v85, v2
	v_mov_b32_e32 v86, v2
	v_mov_b32_e32 v87, v2
	v_mov_b32_e32 v88, v2
	v_mov_b32_e32 v89, v2
	v_mov_b32_e32 v90, v2
	v_mov_b32_e32 v91, v2
	v_mov_b32_e32 v92, v2
	v_mov_b32_e32 v93, v2
	v_mov_b32_e32 v94, v2
	v_mov_b32_e32 v95, v2
	v_mov_b32_e32 v96, v2
	v_mov_b32_e32 v97, v2
	v_mov_b32_e32 v98, v2
	v_mov_b32_e32 v99, v2
	v_mov_b32_e32 v100, v2
	v_mov_b32_e32 v101, v2
	v_mov_b32_e32 v102, v2
	v_mov_b32_e32 v103, v2
	v_mov_b32_e32 v104, v2
	v_mov_b32_e32 v105, v2
	v_mov_b32_e32 v106, v2
	v_mov_b32_e32 v107, v2
	v_mov_b32_e32 v108, v2
	v_mov_b32_e32 v109, v2
	v_mov_b32_e32 v110, v2
	v_mov_b32_e32 v111, v2
	v_mov_b32_e32 v112, v2
	v_mov_b32_e32 v113, v2
	v_mov_b32_e32 v114, v2
	v_mov_b32_e32 v115, v2
	v_mov_b32_e32 v116, v2
	v_mov_b32_e32 v117, v2
	v_mov_b32_e32 v118, v2
	v_mov_b32_e32 v119, v2
	v_mov_b32_e32 v120, v2
	v_mov_b32_e32 v121, v2
	v_mov_b32_e32 v122, v2
	v_mov_b32_e32 v123, v2
	v_mov_b32_e32 v124, v2
	v_mov_b32_e32 v125, v2
	v_mov_b32_e32 v126, v2
	v_mov_b32_e32 v127, v2
	v_mov_b32_e32 v128, v2
	v_mov_b32_e32 v129, v2
	s_waitcnt vmcnt(6) lgkmcnt(0)
	s_barrier
	ds_read_b128 v[236:239], v160 offset:16384
	ds_read_b128 v[240:243], v160 offset:17408
	ds_read_b128 v[244:247], v160 offset:18432
	ds_read_b128 v[248:251], v160 offset:19456
	ds_read_b128 v[186:189], v161
	ds_read_b128 v[190:193], v161 offset:1024
	ds_read_b128 v[212:215], v161 offset:2048
	ds_read_b128 v[216:219], v161 offset:3072
	ds_read_b128 v[220:223], v161 offset:4096
	ds_read_b128 v[224:227], v161 offset:5120
	ds_read_b128 v[228:231], v161 offset:6144
	ds_read_b128 v[232:235], v161 offset:7168
	s_waitcnt vmcnt(0) lgkmcnt(0)
	s_barrier
; DI void cfence() { asm volatile("" ::: "memory"); }
; DI int swz4(int row) { const int g = (row >> 2) & 3; return ((g << 1) ^ ((g >> 1) * 3)) & 3; }
; #define LSTORE2(RA, RB, P)                                       \
;   {                                                              \
;     char* dA_ = smem + (P) * 24576 + wofs;                       \
;     _Pragma("unroll") for (int j = 0; j < 4; ++j) *(u32x4*)(dA_ + j * 4096) = RA[j]; \
;     _Pragma("unroll") for (int j = 0; j < 2; ++j) *(u32x4*)(dA_ + 16384 + j * 4096) = RB[j]; \
;   }
; DI void gemm256_kloop(f32x4 (&acc)[8][4], const bf16_t* __restrict__ A, int lda, const bf16_t* __restrict__ Bt, int ldb,
;                       int K, int b, int s0, int col0, char* smem) {
;     ...
;   GLOAD2(xa, xb, 0);
;   GLOAD2(ya, yb, 1);
;   cfence();
;   LSTORE2(xa, xb, 0);
;   __syncthreads();
;   const int co = ((fq ^ swz4(fr)) << 4);
;   const int aofs = (wr * 128 + fr) * 64 + co, bofs = (wc * 64 + fr) * 64 + co;
;   for (int kt = 0; kt < nk; kt += 2) {
;     GLOAD2(xa, xb, kt + 2);
;     cfence();
;     COMPUTE2(0);
;     LSTORE2(ya, yb, 1);
;     __syncthreads();
.LBB0_81:
	s_add_i32 s9, s8, 2
	s_cmp_lt_u32 s8, 62
	s_cselect_b64 s[10:11], -1, 0
	s_and_b64 vcc, s[10:11], exec
	s_cselect_b32 s10, s7, 0xfc0
	s_setprio 1
	s_mov_b32 m0, s98
	v_mfma_f32_16x16x32_bf16 v[126:129], v[186:189], v[236:239], v[126:129]
	buffer_load_dwordx4 v0, s[20:23], s10 offen lds
	s_add_u32 m0, m0, 0x1000
	v_mfma_f32_16x16x32_bf16 v[122:125], v[186:189], v[240:243], v[122:125]
	buffer_load_dwordx4 v154, s[20:23], s10 offen lds
	s_add_u32 m0, m0, 0x1000
	v_mfma_f32_16x16x32_bf16 v[118:121], v[186:189], v[244:247], v[118:121]
	buffer_load_dwordx4 v155, s[20:23], s10 offen lds
	s_add_u32 m0, m0, 0x1000
	v_mfma_f32_16x16x32_bf16 v[114:117], v[186:189], v[248:251], v[114:117]
	buffer_load_dwordx4 v156, s[20:23], s10 offen lds
	s_add_u32 m0, m0, 0x1000
	v_mfma_f32_16x16x32_bf16 v[110:113], v[190:193], v[236:239], v[110:113]
	buffer_load_dwordx4 v157, s[12:15], s10 offen lds
	s_add_u32 m0, m0, 0x1000
	v_mfma_f32_16x16x32_bf16 v[106:109], v[190:193], v[240:243], v[106:109]
	buffer_load_dwordx4 v158, s[12:15], s10 offen lds
	v_mfma_f32_16x16x32_bf16 v[102:105], v[190:193], v[244:247], v[102:105]
	ds_read_b128 v[170:173], v160 offset:40960
	v_mfma_f32_16x16x32_bf16 v[98:101], v[190:193], v[248:251], v[98:101]
	v_mfma_f32_16x16x32_bf16 v[94:97], v[212:215], v[236:239], v[94:97]
	ds_read_b128 v[174:177], v160 offset:41984
	v_mfma_f32_16x16x32_bf16 v[90:93], v[212:215], v[240:243], v[90:93]
	v_mfma_f32_16x16x32_bf16 v[86:89], v[212:215], v[244:247], v[86:89]
	ds_read_b128 v[178:181], v160 offset:43008
	v_mfma_f32_16x16x32_bf16 v[82:85], v[212:215], v[248:251], v[82:85]
	v_mfma_f32_16x16x32_bf16 v[78:81], v[216:219], v[236:239], v[78:81]
	ds_read_b128 v[182:185], v160 offset:44032
	v_mfma_f32_16x16x32_bf16 v[74:77], v[216:219], v[240:243], v[74:77]
	v_mfma_f32_16x16x32_bf16 v[70:73], v[216:219], v[244:247], v[70:73]
	ds_read_b128 v[130:133], v161 offset:24576
	v_mfma_f32_16x16x32_bf16 v[66:69], v[216:219], v[248:251], v[66:69]
	v_mfma_f32_16x16x32_bf16 v[62:65], v[220:223], v[236:239], v[62:65]
	ds_read_b128 v[134:137], v161 offset:25600
	v_mfma_f32_16x16x32_bf16 v[58:61], v[220:223], v[240:243], v[58:61]
	v_mfma_f32_16x16x32_bf16 v[54:57], v[220:223], v[244:247], v[54:57]
	ds_read_b128 v[138:141], v161 offset:26624
	v_mfma_f32_16x16x32_bf16 v[50:53], v[220:223], v[248:251], v[50:53]
	v_mfma_f32_16x16x32_bf16 v[46:49], v[224:227], v[236:239], v[46:49]
	ds_read_b128 v[142:145], v161 offset:27648
	v_mfma_f32_16x16x32_bf16 v[42:45], v[224:227], v[240:243], v[42:45]
	v_mfma_f32_16x16x32_bf16 v[38:41], v[224:227], v[244:247], v[38:41]
	ds_read_b128 v[146:149], v161 offset:28672
	v_mfma_f32_16x16x32_bf16 v[34:37], v[224:227], v[248:251], v[34:37]
	v_mfma_f32_16x16x32_bf16 v[30:33], v[228:231], v[236:239], v[30:33]
	ds_read_b128 v[150:153], v161 offset:29696
	v_mfma_f32_16x16x32_bf16 v[26:29], v[228:231], v[240:243], v[26:29]
	v_mfma_f32_16x16x32_bf16 v[22:25], v[228:231], v[244:247], v[22:25]
	ds_read_b128 v[162:165], v161 offset:30720
	v_mfma_f32_16x16x32_bf16 v[18:21], v[228:231], v[248:251], v[18:21]
	v_mfma_f32_16x16x32_bf16 v[14:17], v[232:235], v[236:239], v[14:17]
	ds_read_b128 v[166:169], v161 offset:31744
	v_mfma_f32_16x16x32_bf16 v[10:13], v[232:235], v[240:243], v[10:13]
	v_mfma_f32_16x16x32_bf16 v[6:9], v[232:235], v[244:247], v[6:9]
	v_mfma_f32_16x16x32_bf16 v[2:5], v[232:235], v[248:251], v[2:5]
	s_setprio 0
	s_min_u32 s8, s8, 60
	s_lshl_b32 s8, s8, 6
	s_addk_i32 s8, 0xc0
	s_waitcnt vmcnt(0) lgkmcnt(0)
	s_barrier
; DI void cfence() { asm volatile("" ::: "memory"); }
; #define LSTORE2(RA, RB, P)                                       \
;   {                                                              \
;     char* dA_ = smem + (P) * 24576 + wofs;                       \
;     _Pragma("unroll") for (int j = 0; j < 4; ++j) *(u32x4*)(dA_ + j * 4096) = RA[j]; \
;     _Pragma("unroll") for (int j = 0; j < 2; ++j) *(u32x4*)(dA_ + 16384 + j * 4096) = RB[j]; \
;   }
; DI void gemm256_kloop(f32x4 (&acc)[8][4], const bf16_t* __restrict__ A, int lda, const bf16_t* __restrict__ Bt, int ldb,
;                       int K, int b, int s0, int col0, char* smem) {
;     ...
;   for (int kt = 0; kt < nk; kt += 2) {
;     GLOAD2(xa, xb, kt + 2);
;     cfence();
;     COMPUTE2(0);
;     LSTORE2(ya, yb, 1);
;     __syncthreads();
;     if (kt + 1 < nk) {
;       GLOAD2(ya, yb, kt + 3);
;       cfence();
;       COMPUTE2(1);
;       LSTORE2(xa, xb, 0);
;       __syncthreads();
;     }
;   }
	s_setprio 1
	s_add_u32 m0, s98, 0x6000
	v_mfma_f32_16x16x32_bf16 v[126:129], v[130:133], v[170:173], v[126:129]
	buffer_load_dwordx4 v0, s[20:23], s8 offen lds
	s_add_u32 m0, m0, 0x1000
	v_mfma_f32_16x16x32_bf16 v[122:125], v[130:133], v[174:177], v[122:125]
	buffer_load_dwordx4 v154, s[20:23], s8 offen lds
	s_add_u32 m0, m0, 0x1000
	v_mfma_f32_16x16x32_bf16 v[118:121], v[130:133], v[178:181], v[118:121]
	buffer_load_dwordx4 v155, s[20:23], s8 offen lds
	s_add_u32 m0, m0, 0x1000
	v_mfma_f32_16x16x32_bf16 v[114:117], v[130:133], v[182:185], v[114:117]
	buffer_load_dwordx4 v156, s[20:23], s8 offen lds
	s_add_u32 m0, m0, 0x1000
	v_mfma_f32_16x16x32_bf16 v[110:113], v[134:137], v[170:173], v[110:113]
	buffer_load_dwordx4 v157, s[12:15], s8 offen lds
	s_add_u32 m0, m0, 0x1000
	v_mfma_f32_16x16x32_bf16 v[106:109], v[134:137], v[174:177], v[106:109]
	buffer_load_dwordx4 v158, s[12:15], s8 offen lds
	v_mfma_f32_16x16x32_bf16 v[102:105], v[134:137], v[178:181], v[102:105]
	ds_read_b128 v[236:239], v160 offset:16384
	v_mfma_f32_16x16x32_bf16 v[98:101], v[134:137], v[182:185], v[98:101]
	v_mfma_f32_16x16x32_bf16 v[94:97], v[138:141], v[170:173], v[94:97]
	ds_read_b128 v[240:243], v160 offset:17408
	v_mfma_f32_16x16x32_bf16 v[90:93], v[138:141], v[174:177], v[90:93]
	v_mfma_f32_16x16x32_bf16 v[86:89], v[138:141], v[178:181], v[86:89]
	ds_read_b128 v[244:247], v160 offset:18432
	v_mfma_f32_16x16x32_bf16 v[82:85], v[138:141], v[182:185], v[82:85]
	v_mfma_f32_16x16x32_bf16 v[78:81], v[142:145], v[170:173], v[78:81]
	ds_read_b128 v[248:251], v160 offset:19456
	v_mfma_f32_16x16x32_bf16 v[74:77], v[142:145], v[174:177], v[74:77]
	v_mfma_f32_16x16x32_bf16 v[70:73], v[142:145], v[178:181], v[70:73]
	ds_read_b128 v[186:189], v161
	v_mfma_f32_16x16x32_bf16 v[66:69], v[142:145], v[182:185], v[66:69]
	v_mfma_f32_16x16x32_bf16 v[62:65], v[146:149], v[170:173], v[62:65]
	ds_read_b128 v[190:193], v161 offset:1024
	v_mfma_f32_16x16x32_bf16 v[58:61], v[146:149], v[174:177], v[58:61]
	v_mfma_f32_16x16x32_bf16 v[54:57], v[146:149], v[178:181], v[54:57]
	ds_read_b128 v[212:215], v161 offset:2048
	v_mfma_f32_16x16x32_bf16 v[50:53], v[146:149], v[182:185], v[50:53]
	v_mfma_f32_16x16x32_bf16 v[46:49], v[150:153], v[170:173], v[46:49]
	ds_read_b128 v[216:219], v161 offset:3072
	v_mfma_f32_16x16x32_bf16 v[42:45], v[150:153], v[174:177], v[42:45]
	v_mfma_f32_16x16x32_bf16 v[38:41], v[150:153], v[178:181], v[38:41]
	ds_read_b128 v[220:223], v161 offset:4096
	v_mfma_f32_16x16x32_bf16 v[34:37], v[150:153], v[182:185], v[34:37]
	v_mfma_f32_16x16x32_bf16 v[30:33], v[162:165], v[170:173], v[30:33]
	ds_read_b128 v[224:227], v161 offset:5120
	v_mfma_f32_16x16x32_bf16 v[26:29], v[162:165], v[174:177], v[26:29]
	v_mfma_f32_16x16x32_bf16 v[22:25], v[162:165], v[178:181], v[22:25]
	ds_read_b128 v[228:231], v161 offset:6144
	v_mfma_f32_16x16x32_bf16 v[18:21], v[162:165], v[182:185], v[18:21]
	v_mfma_f32_16x16x32_bf16 v[14:17], v[166:169], v[170:173], v[14:17]
	ds_read_b128 v[232:235], v161 offset:7168
	v_mfma_f32_16x16x32_bf16 v[10:13], v[166:169], v[174:177], v[10:13]
	v_mfma_f32_16x16x32_bf16 v[6:9], v[166:169], v[178:181], v[6:9]
	v_mfma_f32_16x16x32_bf16 v[2:5], v[166:169], v[182:185], v[2:5]
	s_setprio 0
	s_addk_i32 s7, 0x80
	s_mov_b32 s8, s9
	s_waitcnt vmcnt(0) lgkmcnt(0)
	s_barrier
	s_cbranch_vccnz .LBB0_81
	s_lshl_b32 s39, s6, 6
	s_mulk_i32 s4, 0xfc
	s_mul_i32 s6, s5, 0x41f4
	s_sub_i32 s48, s4, s6
	s_mul_hi_i32 s4, s5, 0xb4c8000
	s_mul_i32 s5, s5, 0xb4c8000
	s_add_u32 s8, s34, s5
	s_addc_u32 s9, s38, s4
	s_mov_b32 s6, 0
	s_mov_b64 s[10:11], -1
	s_branch .LBB0_84

; DI int tidx() { int t = __builtin_amdgcn_workitem_id_x(); asm volatile("" : "+v"(t)); return t; }
; DI brsrc_t make_rsrc(const void* p) { return __builtin_amdgcn_make_buffer_rsrc((void*)p, 0, 0x7fffffff, 0x00020000); }
; DI void cfence() { asm volatile("" ::: "memory"); }
; DI int swz4(int row) { const int g = (row >> 2) & 3; return ((g << 1) ^ ((g >> 1) * 3)) & 3; }
; #define LSTORE2(RA, RB, P)                                       \
;   {                                                              \
;     char* dA_ = smem + (P) * 24576 + wofs;                       \
;     _Pragma("unroll") for (int j = 0; j < 4; ++j) *(u32x4*)(dA_ + j * 4096) = RA[j]; \
;     _Pragma("unroll") for (int j = 0; j < 2; ++j) *(u32x4*)(dA_ + 16384 + j * 4096) = RB[j]; \
;   }
; DI void gemm256_kloop(f32x4 (&acc)[8][4], const bf16_t* __restrict__ A, int lda, const bf16_t* __restrict__ Bt, int ldb,
;                       int K, int b, int s0, int col0, char* smem) {
;   const int tid = tidx(), lane = tid & 63, wid = tid >> 6;
;   const int wr = wid >> 1, wc = wid & 1, fr = lane & 15, fq = lane >> 4;
;   const int lrow = tid >> 2, lkc = tid & 3;
;   const brsrc_t rA = make_rsrc(A), rB = make_rsrc(Bt);
;   unsigned aoff[4];
; #pragma unroll
;   for (int j = 0; j < 4; ++j) {
;     int s = s0 + lrow + 64 * j;
;     s = s < 0 ? 0 : (s > SB - 1 ? SB - 1 : s);
;     aoff[j] = ((unsigned)(b * SB + s) * (unsigned)lda + lkc * 8) * 2u;
;   }
;   const unsigned boff = ((unsigned)(col0 + lrow) * (unsigned)ldb + lkc * 8) * 2u;
;   const unsigned bstep = 64u * (unsigned)ldb * 2u;
;   const int wofs = lrow * 64 + ((lkc ^ swz4(lrow)) << 4);
;   const int nk = K >> 5;
;   u32x4 xa[4], xb[2], ya[4], yb[2];
;     ...
;   GLOAD2(xa, xb, 0);
;   GLOAD2(ya, yb, 1);
;   cfence();
;   LSTORE2(xa, xb, 0);
;   __syncthreads();
;   const int co = ((fq ^ swz4(fr)) << 4);
;   const int aofs = (wr * 128 + fr) * 64 + co, bofs = (wc * 64 + fr) * 64 + co;
; template <class Epi>
; DI void gemm256_item_plain(const bf16_t* A, int lda, const bf16_t* Bt, int ldb, int K, int ntn, char* smem, const Epi& epi, int it) {
;   int mt = it / ntn, nt = it - mt * ntn;
;   int b = mt / 65, s0 = (mt - b * 65) * 256;
;   gemm256_tile(A, lda, Bt, ldb, K, b, s0, nt * 128, smem, epi, 128);
.LBB0_275:
	s_ashr_i32 s2, s17, 31
	s_mul_hi_i32 s3, s17, 0x7e07e07f
	s_lshr_b32 s2, s2, 28
	s_lshr_b32 s4, s3, 31
	s_ashr_i32 s18, s3, 9
	s_add_i32 s2, s17, s2
	s_add_i32 s18, s18, s4
	s_ashr_i32 s2, s2, 4
	s_mul_i32 s3, s18, 0xffffffbf
	s_waitcnt vmcnt(0)
	v_mov_b32_e32 v7, v194
	s_add_i32 s3, s3, s2
	s_lshl_b32 s4, s2, 11
	v_ashrrev_i32_e32 v32, 2, v7
	v_lshl_add_u32 v2, s3, 8, v32
	v_max_i32_e32 v4, 0xffffffc0, v2
	v_add_u32_e32 v4, 64, v4
	s_lshl_b32 s5, s17, 7
	s_mul_i32 s3, s18, 0x4100
	v_min_u32_e32 v4, 0x40ff, v4
	s_sub_i32 s19, s5, s4
	v_and_b32_e32 v33, 3, v7
	s_movk_i32 s4, 0x1080
	v_add_u32_e32 v4, s3, v4
	v_lshlrev_b32_e32 v3, 4, v33
	v_mul_lo_u32 v4, v4, s4
	v_med3_i32 v0, v2, 0, v201
	v_or_b32_e32 v154, v4, v3
	v_max_i32_e32 v4, 0xffffff80, v2
	v_max_i32_e32 v2, 0xffffff40, v2
	v_add_u32_e32 v2, 0xc0, v2
	v_min_u32_e32 v2, 0x40ff, v2
	v_add_u32_e32 v2, s3, v2
	v_mul_lo_u32 v2, v2, s4
	v_add_u32_e32 v4, 0x80, v4
	v_or_b32_e32 v156, v2, v3
	v_add_u32_e32 v2, s19, v32
	v_add_u32_e32 v0, s3, v0
	v_min_u32_e32 v4, 0x40ff, v4
	v_mul_lo_u32 v2, v2, s4
	v_mul_lo_u32 v0, v0, s4
	v_add_u32_e32 v4, s3, v4
	v_or_b32_e32 v157, v2, v3
	v_or_b32_e32 v0, v0, v3
	v_mul_lo_u32 v4, v4, s4
	s_mov_b32 s14, s22
	s_mov_b32 s15, s23
	v_add_u32_e32 v158, 0x42000, v157
	v_or_b32_e32 v155, v4, v3
	v_bfe_u32 v162, v194, 4, 2
	v_lshlrev_b32_e32 v162, 2, v162
	v_mov_b32_e32 v163, 0x1320
	v_lshrrev_b32_e32 v162, v162, v163
	v_and_b32_e32 v162, 3, v162
	v_lshlrev_b32_e32 v162, 4, v162
	v_xor_b32_e32 v0, v0, v162
	v_xor_b32_e32 v154, v154, v162
	v_xor_b32_e32 v155, v155, v162
	v_xor_b32_e32 v156, v156, v162
	v_xor_b32_e32 v157, v157, v162
	v_xor_b32_e32 v158, v158, v162
	v_lshrrev_b32_e32 v163, 6, v194
	s_nop 0
	v_readfirstlane_b32 s98, v163
	s_lshl_b32 s98, s98, 10
	s_mov_b32 m0, s98
	s_nop 0
	buffer_load_dwordx4 v0, s[20:23], 0 offen lds
	s_add_u32 m0, m0, 0x1000
	s_nop 0
	buffer_load_dwordx4 v154, s[20:23], 0 offen lds
	s_add_u32 m0, m0, 0x1000
	s_nop 0
	buffer_load_dwordx4 v155, s[20:23], 0 offen lds
	s_add_u32 m0, m0, 0x1000
	s_nop 0
	buffer_load_dwordx4 v156, s[20:23], 0 offen lds
	s_add_u32 m0, m0, 0x1000
	s_nop 0
	buffer_load_dwordx4 v157, s[12:15], 0 offen lds
	s_add_u32 m0, m0, 0x1000
	s_nop 0
	buffer_load_dwordx4 v158, s[12:15], 0 offen lds
	s_add_u32 m0, s98, 0x6000
	s_nop 0
	buffer_load_dwordx4 v0, s[20:23], 64 offen lds
	s_add_u32 m0, m0, 0x1000
	s_nop 0
	buffer_load_dwordx4 v154, s[20:23], 64 offen lds
	s_add_u32 m0, m0, 0x1000
	s_nop 0
	buffer_load_dwordx4 v155, s[20:23], 64 offen lds
	s_add_u32 m0, m0, 0x1000
	s_nop 0
	buffer_load_dwordx4 v156, s[20:23], 64 offen lds
	s_add_u32 m0, m0, 0x1000
	s_nop 0
	buffer_load_dwordx4 v157, s[12:15], 64 offen lds
	s_add_u32 m0, m0, 0x1000
	s_nop 0
	buffer_load_dwordx4 v158, s[12:15], 64 offen lds
	v_lshrrev_b32_e32 v36, 1, v7
	v_bfe_i32 v35, v7, 3, 1
	v_lshlrev_b32_e32 v38, 6, v32
	v_lshrrev_b32_e32 v32, 1, v32
	v_and_b32_e32 v36, 2, v36
	v_bfe_i32 v34, v7, 5, 1
	v_and_b32_e32 v32, 2, v32
	v_bitop3_b32 v35, v35, v36, 3 bitop3:0x6c
	v_bitop3_b32 v32, v34, v32, 3 bitop3:0x6c
	v_lshlrev_b32_e32 v34, 4, v35
	v_lshlrev_b32_e32 v37, 6, v7
	v_xor_b32_e32 v32, v32, v33
	v_bitop3_b32 v7, v34, v7, 48 bitop3:0x78
	s_movk_i32 s6, 0x13c0
	v_mov_b32_e32 v2, 0
	v_lshl_or_b32 v159, v32, 4, v38
	v_and_or_b32 v160, v37, s6, v7
	s_movk_i32 s6, 0xe3c0
	s_mov_b32 s5, 0
	s_movk_i32 s4, 0x80
	v_mov_b32_e32 v3, v2
	v_mov_b32_e32 v4, v2
	v_mov_b32_e32 v5, v2
	v_mov_b32_e32 v6, v2
	v_and_or_b32 v161, v37, s6, v7
	v_mov_b32_e32 v7, v2
	v_mov_b32_e32 v32, v2
	v_mov_b32_e32 v33, v2
	v_mov_b32_e32 v34, v2
	v_mov_b32_e32 v35, v2
	v_mov_b32_e32 v36, v2
	v_mov_b32_e32 v37, v2
	v_mov_b32_e32 v38, v2
	v_mov_b32_e32 v39, v2
	v_mov_b32_e32 v40, v2
	v_mov_b32_e32 v41, v2
	v_mov_b32_e32 v42, v2
	v_mov_b32_e32 v43, v2
	v_mov_b32_e32 v44, v2
	v_mov_b32_e32 v45, v2
	v_mov_b32_e32 v46, v2
	v_mov_b32_e32 v47, v2
	v_mov_b32_e32 v48, v2
	v_mov_b32_e32 v49, v2
	v_mov_b32_e32 v50, v2
	v_mov_b32_e32 v51, v2
	v_mov_b32_e32 v8, v2
	v_mov_b32_e32 v9, v2
	v_mov_b32_e32 v10, v2
	v_mov_b32_e32 v11, v2
	v_mov_b32_e32 v12, v2
	v_mov_b32_e32 v13, v2
	v_mov_b32_e32 v14, v2
	v_mov_b32_e32 v15, v2
	v_mov_b32_e32 v16, v2
	v_mov_b32_e32 v17, v2
	v_mov_b32_e32 v18, v2
	v_mov_b32_e32 v19, v2
	v_mov_b32_e32 v20, v2
	v_mov_b32_e32 v21, v2
	v_mov_b32_e32 v22, v2
	v_mov_b32_e32 v23, v2
	v_mov_b32_e32 v24, v2
	v_mov_b32_e32 v25, v2
	v_mov_b32_e32 v26, v2
	v_mov_b32_e32 v27, v2
	v_mov_b32_e32 v28, v2
	v_mov_b32_e32 v29, v2
	v_mov_b32_e32 v30, v2
	v_mov_b32_e32 v31, v2
	v_mov_b32_e32 v52, v2
	v_mov_b32_e32 v53, v2
	v_mov_b32_e32 v54, v2
	v_mov_b32_e32 v55, v2
	v_mov_b32_e32 v56, v2
	v_mov_b32_e32 v57, v2
	v_mov_b32_e32 v58, v2
	v_mov_b32_e32 v59, v2
	v_mov_b32_e32 v60, v2
	v_mov_b32_e32 v61, v2
	v_mov_b32_e32 v62, v2
	v_mov_b32_e32 v63, v2
	v_mov_b32_e32 v64, v2
	v_mov_b32_e32 v65, v2
	v_mov_b32_e32 v66, v2
	v_mov_b32_e32 v67, v2
	v_mov_b32_e32 v68, v2
	v_mov_b32_e32 v69, v2
	v_mov_b32_e32 v70, v2
	v_mov_b32_e32 v71, v2
	v_mov_b32_e32 v72, v2
	v_mov_b32_e32 v73, v2
	v_mov_b32_e32 v74, v2
	v_mov_b32_e32 v75, v2
	v_mov_b32_e32 v76, v2
	v_mov_b32_e32 v77, v2
	v_mov_b32_e32 v78, v2
	v_mov_b32_e32 v79, v2
	v_mov_b32_e32 v80, v2
	v_mov_b32_e32 v81, v2
	v_mov_b32_e32 v82, v2
	v_mov_b32_e32 v83, v2
	v_mov_b32_e32 v84, v2
	v_mov_b32_e32 v85, v2
	v_mov_b32_e32 v86, v2
	v_mov_b32_e32 v87, v2
	v_mov_b32_e32 v88, v2
	v_mov_b32_e32 v89, v2
	v_mov_b32_e32 v90, v2
	v_mov_b32_e32 v91, v2
	v_mov_b32_e32 v92, v2
	v_mov_b32_e32 v93, v2
	v_mov_b32_e32 v94, v2
	v_mov_b32_e32 v95, v2
	v_mov_b32_e32 v96, v2
	v_mov_b32_e32 v97, v2
	v_mov_b32_e32 v98, v2
	v_mov_b32_e32 v99, v2
	v_mov_b32_e32 v100, v2
	v_mov_b32_e32 v101, v2
	v_mov_b32_e32 v102, v2
	v_mov_b32_e32 v103, v2
	v_mov_b32_e32 v104, v2
	v_mov_b32_e32 v105, v2
	v_mov_b32_e32 v106, v2
	v_mov_b32_e32 v107, v2
	v_mov_b32_e32 v108, v2
	v_mov_b32_e32 v109, v2
	v_mov_b32_e32 v110, v2
	v_mov_b32_e32 v111, v2
	v_mov_b32_e32 v112, v2
	v_mov_b32_e32 v113, v2
	v_mov_b32_e32 v114, v2
	v_mov_b32_e32 v115, v2
	v_mov_b32_e32 v116, v2
	v_mov_b32_e32 v117, v2
	v_mov_b32_e32 v118, v2
	v_mov_b32_e32 v119, v2
	v_mov_b32_e32 v120, v2
	v_mov_b32_e32 v121, v2
	v_mov_b32_e32 v122, v2
	v_mov_b32_e32 v123, v2
	v_mov_b32_e32 v124, v2
	v_mov_b32_e32 v125, v2
	v_mov_b32_e32 v126, v2
	v_mov_b32_e32 v127, v2
	v_mov_b32_e32 v128, v2
	v_mov_b32_e32 v129, v2
	s_waitcnt vmcnt(6) lgkmcnt(0)
	s_barrier
	ds_read_b128 v[236:239], v160 offset:16384
	ds_read_b128 v[240:243], v160 offset:17408
	ds_read_b128 v[244:247], v160 offset:18432
	ds_read_b128 v[248:251], v160 offset:19456
	ds_read_b128 v[186:189], v161
	ds_read_b128 v[190:193], v161 offset:1024
	ds_read_b128 v[212:215], v161 offset:2048
	ds_read_b128 v[216:219], v161 offset:3072
	ds_read_b128 v[220:223], v161 offset:4096
	ds_read_b128 v[224:227], v161 offset:5120
	ds_read_b128 v[228:231], v161 offset:6144
	ds_read_b128 v[232:235], v161 offset:7168
	s_waitcnt vmcnt(0) lgkmcnt(0)
	s_barrier
; DI void cfence() { asm volatile("" ::: "memory"); }
; DI int swz4(int row) { const int g = (row >> 2) & 3; return ((g << 1) ^ ((g >> 1) * 3)) & 3; }
; #define LSTORE2(RA, RB, P)                                       \
;   {                                                              \
;     char* dA_ = smem + (P) * 24576 + wofs;                       \
;     _Pragma("unroll") for (int j = 0; j < 4; ++j) *(u32x4*)(dA_ + j * 4096) = RA[j]; \
;     _Pragma("unroll") for (int j = 0; j < 2; ++j) *(u32x4*)(dA_ + 16384 + j * 4096) = RB[j]; \
;   }
; DI void gemm256_kloop(f32x4 (&acc)[8][4], const bf16_t* __restrict__ A, int lda, const bf16_t* __restrict__ Bt, int ldb,
;                       int K, int b, int s0, int col0, char* smem) {
;     ...
;   GLOAD2(xa, xb, 0);
;   GLOAD2(ya, yb, 1);
;   cfence();
;   LSTORE2(xa, xb, 0);
;   __syncthreads();
;   const int co = ((fq ^ swz4(fr)) << 4);
;   const int aofs = (wr * 128 + fr) * 64 + co, bofs = (wc * 64 + fr) * 64 + co;
;   for (int kt = 0; kt < nk; kt += 2) {
;     GLOAD2(xa, xb, kt + 2);
;     cfence();
;     COMPUTE2(0);
;     LSTORE2(ya, yb, 1);
;     __syncthreads();
;     if (kt + 1 < nk) {
;       GLOAD2(ya, yb, kt + 3);
;       cfence();
;       COMPUTE2(1);
;       LSTORE2(xa, xb, 0);
;       __syncthreads();
;     }
;   }
.LBB0_276:
	s_add_i32 s6, s5, 2
	s_cmp_lt_u32 s5, 62
	s_cselect_b64 s[8:9], -1, 0
	s_and_b64 vcc, s[8:9], exec
	s_cselect_b32 s7, s4, 0xfc0
	s_setprio 1
	s_mov_b32 m0, s98
	v_mfma_f32_16x16x32_bf16 v[126:129], v[186:189], v[236:239], v[126:129]
	buffer_load_dwordx4 v0, s[20:23], s7 offen lds
	s_add_u32 m0, m0, 0x1000
	v_mfma_f32_16x16x32_bf16 v[122:125], v[186:189], v[240:243], v[122:125]
	buffer_load_dwordx4 v154, s[20:23], s7 offen lds
	s_add_u32 m0, m0, 0x1000
	v_mfma_f32_16x16x32_bf16 v[118:121], v[186:189], v[244:247], v[118:121]
	buffer_load_dwordx4 v155, s[20:23], s7 offen lds
	s_add_u32 m0, m0, 0x1000
	v_mfma_f32_16x16x32_bf16 v[114:117], v[186:189], v[248:251], v[114:117]
	buffer_load_dwordx4 v156, s[20:23], s7 offen lds
	s_add_u32 m0, m0, 0x1000
	v_mfma_f32_16x16x32_bf16 v[110:113], v[190:193], v[236:239], v[110:113]
	buffer_load_dwordx4 v157, s[12:15], s7 offen lds
	s_add_u32 m0, m0, 0x1000
	v_mfma_f32_16x16x32_bf16 v[106:109], v[190:193], v[240:243], v[106:109]
	buffer_load_dwordx4 v158, s[12:15], s7 offen lds
	v_mfma_f32_16x16x32_bf16 v[102:105], v[190:193], v[244:247], v[102:105]
	ds_read_b128 v[170:173], v160 offset:40960
	v_mfma_f32_16x16x32_bf16 v[98:101], v[190:193], v[248:251], v[98:101]
	v_mfma_f32_16x16x32_bf16 v[94:97], v[212:215], v[236:239], v[94:97]
	ds_read_b128 v[174:177], v160 offset:41984
	v_mfma_f32_16x16x32_bf16 v[90:93], v[212:215], v[240:243], v[90:93]
	v_mfma_f32_16x16x32_bf16 v[86:89], v[212:215], v[244:247], v[86:89]
	ds_read_b128 v[178:181], v160 offset:43008
	v_mfma_f32_16x16x32_bf16 v[82:85], v[212:215], v[248:251], v[82:85]
	v_mfma_f32_16x16x32_bf16 v[78:81], v[216:219], v[236:239], v[78:81]
	ds_read_b128 v[182:185], v160 offset:44032
	v_mfma_f32_16x16x32_bf16 v[74:77], v[216:219], v[240:243], v[74:77]
	v_mfma_f32_16x16x32_bf16 v[70:73], v[216:219], v[244:247], v[70:73]
	ds_read_b128 v[130:133], v161 offset:24576
	v_mfma_f32_16x16x32_bf16 v[66:69], v[216:219], v[248:251], v[66:69]
	v_mfma_f32_16x16x32_bf16 v[62:65], v[220:223], v[236:239], v[62:65]
	ds_read_b128 v[134:137], v161 offset:25600
	v_mfma_f32_16x16x32_bf16 v[58:61], v[220:223], v[240:243], v[58:61]
	v_mfma_f32_16x16x32_bf16 v[54:57], v[220:223], v[244:247], v[54:57]
	ds_read_b128 v[138:141], v161 offset:26624
	v_mfma_f32_16x16x32_bf16 v[50:53], v[220:223], v[248:251], v[50:53]
	v_mfma_f32_16x16x32_bf16 v[46:49], v[224:227], v[236:239], v[46:49]
	ds_read_b128 v[142:145], v161 offset:27648
	v_mfma_f32_16x16x32_bf16 v[42:45], v[224:227], v[240:243], v[42:45]
	v_mfma_f32_16x16x32_bf16 v[38:41], v[224:227], v[244:247], v[38:41]
	ds_read_b128 v[146:149], v161 offset:28672
	v_mfma_f32_16x16x32_bf16 v[34:37], v[224:227], v[248:251], v[34:37]
	v_mfma_f32_16x16x32_bf16 v[30:33], v[228:231], v[236:239], v[30:33]
	ds_read_b128 v[150:153], v161 offset:29696
	v_mfma_f32_16x16x32_bf16 v[26:29], v[228:231], v[240:243], v[26:29]
	v_mfma_f32_16x16x32_bf16 v[22:25], v[228:231], v[244:247], v[22:25]
	ds_read_b128 v[162:165], v161 offset:30720
	v_mfma_f32_16x16x32_bf16 v[18:21], v[228:231], v[248:251], v[18:21]
	v_mfma_f32_16x16x32_bf16 v[14:17], v[232:235], v[236:239], v[14:17]
	ds_read_b128 v[166:169], v161 offset:31744
	v_mfma_f32_16x16x32_bf16 v[10:13], v[232:235], v[240:243], v[10:13]
	v_mfma_f32_16x16x32_bf16 v[6:9], v[232:235], v[244:247], v[6:9]
	v_mfma_f32_16x16x32_bf16 v[2:5], v[232:235], v[248:251], v[2:5]
	s_setprio 0
	s_min_u32 s5, s5, 60
	s_lshl_b32 s5, s5, 6
	s_addk_i32 s5, 0xc0
	s_waitcnt vmcnt(0) lgkmcnt(0)
	s_barrier
	s_setprio 1
	s_add_u32 m0, s98, 0x6000
	v_mfma_f32_16x16x32_bf16 v[126:129], v[130:133], v[170:173], v[126:129]
	buffer_load_dwordx4 v0, s[20:23], s5 offen lds
	s_add_u32 m0, m0, 0x1000
	v_mfma_f32_16x16x32_bf16 v[122:125], v[130:133], v[174:177], v[122:125]
	buffer_load_dwordx4 v154, s[20:23], s5 offen lds
	s_add_u32 m0, m0, 0x1000
	v_mfma_f32_16x16x32_bf16 v[118:121], v[130:133], v[178:181], v[118:121]
	buffer_load_dwordx4 v155, s[20:23], s5 offen lds
	s_add_u32 m0, m0, 0x1000
	v_mfma_f32_16x16x32_bf16 v[114:117], v[130:133], v[182:185], v[114:117]
	buffer_load_dwordx4 v156, s[20:23], s5 offen lds
	s_add_u32 m0, m0, 0x1000
	v_mfma_f32_16x16x32_bf16 v[110:113], v[134:137], v[170:173], v[110:113]
	buffer_load_dwordx4 v157, s[12:15], s5 offen lds
	s_add_u32 m0, m0, 0x1000
	v_mfma_f32_16x16x32_bf16 v[106:109], v[134:137], v[174:177], v[106:109]
	buffer_load_dwordx4 v158, s[12:15], s5 offen lds
	v_mfma_f32_16x16x32_bf16 v[102:105], v[134:137], v[178:181], v[102:105]
	ds_read_b128 v[236:239], v160 offset:16384
	v_mfma_f32_16x16x32_bf16 v[98:101], v[134:137], v[182:185], v[98:101]
	v_mfma_f32_16x16x32_bf16 v[94:97], v[138:141], v[170:173], v[94:97]
	ds_read_b128 v[240:243], v160 offset:17408
	v_mfma_f32_16x16x32_bf16 v[90:93], v[138:141], v[174:177], v[90:93]
	v_mfma_f32_16x16x32_bf16 v[86:89], v[138:141], v[178:181], v[86:89]
	ds_read_b128 v[244:247], v160 offset:18432
	v_mfma_f32_16x16x32_bf16 v[82:85], v[138:141], v[182:185], v[82:85]
	v_mfma_f32_16x16x32_bf16 v[78:81], v[142:145], v[170:173], v[78:81]
	ds_read_b128 v[248:251], v160 offset:19456
	v_mfma_f32_16x16x32_bf16 v[74:77], v[142:145], v[174:177], v[74:77]
	v_mfma_f32_16x16x32_bf16 v[70:73], v[142:145], v[178:181], v[70:73]
	ds_read_b128 v[186:189], v161
	v_mfma_f32_16x16x32_bf16 v[66:69], v[142:145], v[182:185], v[66:69]
	v_mfma_f32_16x16x32_bf16 v[62:65], v[146:149], v[170:173], v[62:65]
	ds_read_b128 v[190:193], v161 offset:1024
	v_mfma_f32_16x16x32_bf16 v[58:61], v[146:149], v[174:177], v[58:61]
	v_mfma_f32_16x16x32_bf16 v[54:57], v[146:149], v[178:181], v[54:57]
	ds_read_b128 v[212:215], v161 offset:2048
	v_mfma_f32_16x16x32_bf16 v[50:53], v[146:149], v[182:185], v[50:53]
	v_mfma_f32_16x16x32_bf16 v[46:49], v[150:153], v[170:173], v[46:49]
	ds_read_b128 v[216:219], v161 offset:3072
	v_mfma_f32_16x16x32_bf16 v[42:45], v[150:153], v[174:177], v[42:45]
	v_mfma_f32_16x16x32_bf16 v[38:41], v[150:153], v[178:181], v[38:41]
	ds_read_b128 v[220:223], v161 offset:4096
	v_mfma_f32_16x16x32_bf16 v[34:37], v[150:153], v[182:185], v[34:37]
	v_mfma_f32_16x16x32_bf16 v[30:33], v[162:165], v[170:173], v[30:33]
	ds_read_b128 v[224:227], v161 offset:5120
	v_mfma_f32_16x16x32_bf16 v[26:29], v[162:165], v[174:177], v[26:29]
	v_mfma_f32_16x16x32_bf16 v[22:25], v[162:165], v[178:181], v[22:25]
	ds_read_b128 v[228:231], v161 offset:6144
	v_mfma_f32_16x16x32_bf16 v[18:21], v[162:165], v[182:185], v[18:21]
	v_mfma_f32_16x16x32_bf16 v[14:17], v[166:169], v[170:173], v[14:17]
	ds_read_b128 v[232:235], v161 offset:7168
	v_mfma_f32_16x16x32_bf16 v[10:13], v[166:169], v[174:177], v[10:13]
	v_mfma_f32_16x16x32_bf16 v[6:9], v[166:169], v[178:181], v[6:9]
	v_mfma_f32_16x16x32_bf16 v[2:5], v[166:169], v[182:185], v[2:5]
	s_setprio 0
	s_addk_i32 s4, 0x80
	s_mov_b32 s5, s6
	s_waitcnt vmcnt(0) lgkmcnt(0)
	s_barrier
	s_cbranch_vccnz .LBB0_276
	s_lshl_b32 s14, s2, 8
	s_sub_i32 s15, s14, s3
	s_mov_b32 s8, 0
	s_mov_b64 s[2:3], -1
	s_branch .LBB0_279

; DI int tidx() { int t = __builtin_amdgcn_workitem_id_x(); asm volatile("" : "+v"(t)); return t; }
; DI int bidx() { int t = __builtin_amdgcn_workgroup_id_x(); asm volatile("" : "+s"(t)); return t; }
; DI int gdim() { int t = (int)__ockl_get_num_groups(0); asm volatile("" : "+s"(t)); return t; }
; DI brsrc_t make_rsrc(const void* p) { return __builtin_amdgcn_make_buffer_rsrc((void*)p, 0, 0x7fffffff, 0x00020000); }
; DI void cfence() { asm volatile("" ::: "memory"); }
; DI int swz4(int row) { const int g = (row >> 2) & 3; return ((g << 1) ^ ((g >> 1) * 3)) & 3; }
; DI void gemm256_kloop(f32x4 (&acc)[8][4], const bf16_t* __restrict__ A, int lda, const bf16_t* __restrict__ Bt, int ldb,
;                       int K, int b, int s0, int col0, char* smem) {
;   const int tid = tidx(), lane = tid & 63, wid = tid >> 6;
;   const int wr = wid >> 1, wc = wid & 1, fr = lane & 15, fq = lane >> 4;
;   const int lrow = tid >> 2, lkc = tid & 3;
;   const brsrc_t rA = make_rsrc(A), rB = make_rsrc(Bt);
;   unsigned aoff[4];
; #pragma unroll
;   for (int j = 0; j < 4; ++j) {
;     int s = s0 + lrow + 64 * j;
;     s = s < 0 ? 0 : (s > SB - 1 ? SB - 1 : s);
;     aoff[j] = ((unsigned)(b * SB + s) * (unsigned)lda + lkc * 8) * 2u;
;   }
;   const unsigned boff = ((unsigned)(col0 + lrow) * (unsigned)ldb + lkc * 8) * 2u;
;   const unsigned bstep = 64u * (unsigned)ldb * 2u;
;   const int wofs = lrow * 64 + ((lkc ^ swz4(lrow)) << 4);
;   const int nk = K >> 5;
;   u32x4 xa[4], xb[2], ya[4], yb[2];
;     ...
;   GLOAD2(xa, xb, 0);
;   GLOAD2(ya, yb, 1);
;   cfence();
;   LSTORE2(xa, xb, 0);
;   __syncthreads();
;   const int co = ((fq ^ swz4(fr)) << 4);
;   const int aofs = (wr * 128 + fr) * 64 + co, bofs = (wc * 64 + fr) * 64 + co;
; template <class Epi>
; DI void gemm256_phase_plain(const bf16_t* A, int lda, const bf16_t* Bt, int ldb, int K, int ntn, char* smem, const Epi& epi,
;                             bool skip_ctx = false) {
;     ...
;     const int total = 128 * ntn;
;     for (int it = bidx(); it < total; it += gdim()) {
;       const int mt = it / ntn, nt = it - mt * ntn;
;       const int mt2 = mt + 1 + (mt >= 64 ? 1 : 0);
;       gemm256_item_plain(A, lda, Bt, ldb, K, ntn, smem, epi, mt2 * ntn + nt);
.LBB0_305:
	s_ashr_i32 s2, s17, 31
	s_lshr_b32 s2, s2, 28
	s_add_i32 s2, s17, s2
	s_lshr_b32 s4, s2, 4
	s_and_b32 s2, s2, -16
	s_sub_i32 s5, s17, s2
	s_cmpk_gt_i32 s17, 0x3ff
	s_cselect_b64 s[2:3], -1, 0
	s_cmp_lg_u64 s[2:3], 0
	s_addc_u32 s2, s4, 0
	s_lshl_b32 s2, s2, 4
	s_add_i32 s2, s2, s5
	s_add_i32 s3, s2, 16
	s_ashr_i32 s2, s3, 31
	s_mul_hi_i32 s4, s3, 0x7e07e07f
	s_lshr_b32 s2, s2, 28
	s_lshr_b32 s5, s4, 31
	s_ashr_i32 s16, s4, 9
	s_add_i32 s2, s3, s2
	s_add_i32 s16, s16, s5
	s_ashr_i32 s2, s2, 4
	s_mul_i32 s4, s16, 0xffffffbf
	s_waitcnt vmcnt(0)
	v_mov_b32_e32 v30, v194
	s_add_i32 s4, s4, s2
	s_lshl_b32 s5, s2, 11
	v_ashrrev_i32_e32 v31, 2, v30
	v_lshl_add_u32 v2, s4, 8, v31
	v_max_i32_e32 v4, 0xffffffc0, v2
	s_lshl_b32 s3, s3, 7
	v_add_u32_e32 v4, 64, v4
	s_sub_i32 s18, s3, s5
	s_mul_i32 s3, s16, 0x4100
	v_min_u32_e32 v4, 0x40ff, v4
	v_and_b32_e32 v32, 3, v30
	s_movk_i32 s4, 0x1080
	v_add_u32_e32 v4, s3, v4
	v_lshlrev_b32_e32 v3, 4, v32
	v_mul_lo_u32 v4, v4, s4
	v_med3_i32 v0, v2, 0, v201
	v_or_b32_e32 v154, v4, v3
	v_max_i32_e32 v4, 0xffffff80, v2
	v_max_i32_e32 v2, 0xffffff40, v2
	v_add_u32_e32 v2, 0xc0, v2
	v_min_u32_e32 v2, 0x40ff, v2
	v_add_u32_e32 v2, s3, v2
	v_mul_lo_u32 v2, v2, s4
	v_add_u32_e32 v4, 0x80, v4
	v_or_b32_e32 v156, v2, v3
	v_add_u32_e32 v2, s18, v31
	v_add_u32_e32 v0, s3, v0
	v_min_u32_e32 v4, 0x40ff, v4
	v_mul_lo_u32 v2, v2, s4
	v_mul_lo_u32 v0, v0, s4
	v_add_u32_e32 v4, s3, v4
	v_or_b32_e32 v157, v2, v3
	v_or_b32_e32 v0, v0, v3
	v_mul_lo_u32 v4, v4, s4
	s_mov_b32 s14, s22
	s_mov_b32 s15, s23
	v_add_u32_e32 v158, 0x42000, v157
	v_or_b32_e32 v155, v4, v3
	v_bfe_u32 v162, v194, 4, 2
	v_lshlrev_b32_e32 v162, 2, v162
	v_mov_b32_e32 v163, 0x1320
	v_lshrrev_b32_e32 v162, v162, v163
	v_and_b32_e32 v162, 3, v162
	v_lshlrev_b32_e32 v162, 4, v162
	v_xor_b32_e32 v0, v0, v162
	v_xor_b32_e32 v154, v154, v162
	v_xor_b32_e32 v155, v155, v162
	v_xor_b32_e32 v156, v156, v162
	v_xor_b32_e32 v157, v157, v162
	v_xor_b32_e32 v158, v158, v162
	v_lshrrev_b32_e32 v163, 6, v194
	s_nop 0
	v_readfirstlane_b32 s98, v163
	s_lshl_b32 s98, s98, 10
	s_mov_b32 m0, s98
	s_nop 0
	buffer_load_dwordx4 v0, s[20:23], 0 offen lds
	s_add_u32 m0, m0, 0x1000
	s_nop 0
	buffer_load_dwordx4 v154, s[20:23], 0 offen lds
	s_add_u32 m0, m0, 0x1000
	s_nop 0
	buffer_load_dwordx4 v155, s[20:23], 0 offen lds
	s_add_u32 m0, m0, 0x1000
	s_nop 0
	buffer_load_dwordx4 v156, s[20:23], 0 offen lds
	s_add_u32 m0, m0, 0x1000
	s_nop 0
	buffer_load_dwordx4 v157, s[12:15], 0 offen lds
	s_add_u32 m0, m0, 0x1000
	s_nop 0
	buffer_load_dwordx4 v158, s[12:15], 0 offen lds
	s_add_u32 m0, s98, 0x6000
	s_nop 0
	buffer_load_dwordx4 v0, s[20:23], 64 offen lds
	s_add_u32 m0, m0, 0x1000
	s_nop 0
	buffer_load_dwordx4 v154, s[20:23], 64 offen lds
	s_add_u32 m0, m0, 0x1000
	s_nop 0
	buffer_load_dwordx4 v155, s[20:23], 64 offen lds
	s_add_u32 m0, m0, 0x1000
	s_nop 0
	buffer_load_dwordx4 v156, s[20:23], 64 offen lds
	s_add_u32 m0, m0, 0x1000
	s_nop 0
	buffer_load_dwordx4 v157, s[12:15], 64 offen lds
	s_add_u32 m0, m0, 0x1000
	s_nop 0
	buffer_load_dwordx4 v158, s[12:15], 64 offen lds
	v_lshrrev_b32_e32 v35, 1, v30
	v_bfe_i32 v34, v30, 3, 1
	v_lshlrev_b32_e32 v37, 6, v31
	v_lshrrev_b32_e32 v31, 1, v31
	v_and_b32_e32 v35, 2, v35
	v_bfe_i32 v33, v30, 5, 1
	v_and_b32_e32 v31, 2, v31
	v_bitop3_b32 v34, v34, v35, 3 bitop3:0x6c
	v_bitop3_b32 v31, v33, v31, 3 bitop3:0x6c
	v_lshlrev_b32_e32 v33, 4, v34
	v_lshlrev_b32_e32 v36, 6, v30
	v_xor_b32_e32 v31, v31, v32
	v_bitop3_b32 v30, v33, v30, 48 bitop3:0x78
	s_movk_i32 s6, 0x13c0
	v_mov_b32_e32 v2, 0
	v_lshl_or_b32 v159, v31, 4, v37
	v_and_or_b32 v160, v36, s6, v30
	s_movk_i32 s6, 0xe3c0
	s_mov_b32 s5, 0
	s_movk_i32 s4, 0x80
	v_mov_b32_e32 v3, v2
	v_mov_b32_e32 v4, v2
	v_mov_b32_e32 v5, v2
	v_and_or_b32 v161, v36, s6, v30
	v_mov_b32_e32 v30, v2
	v_mov_b32_e32 v31, v2
	v_mov_b32_e32 v32, v2
	v_mov_b32_e32 v33, v2
	v_mov_b32_e32 v34, v2
	v_mov_b32_e32 v35, v2
	v_mov_b32_e32 v36, v2
	v_mov_b32_e32 v37, v2
	v_mov_b32_e32 v38, v2
	v_mov_b32_e32 v39, v2
	v_mov_b32_e32 v40, v2
	v_mov_b32_e32 v41, v2
	v_mov_b32_e32 v42, v2
	v_mov_b32_e32 v43, v2
	v_mov_b32_e32 v44, v2
	v_mov_b32_e32 v45, v2
	v_mov_b32_e32 v46, v2
	v_mov_b32_e32 v47, v2
	v_mov_b32_e32 v48, v2
	v_mov_b32_e32 v49, v2
	v_mov_b32_e32 v50, v2
	v_mov_b32_e32 v6, v2
	v_mov_b32_e32 v7, v2
	v_mov_b32_e32 v8, v2
	v_mov_b32_e32 v9, v2
	v_mov_b32_e32 v10, v2
	v_mov_b32_e32 v11, v2
	v_mov_b32_e32 v12, v2
	v_mov_b32_e32 v13, v2
	v_mov_b32_e32 v14, v2
	v_mov_b32_e32 v15, v2
	v_mov_b32_e32 v16, v2
	v_mov_b32_e32 v17, v2
	v_mov_b32_e32 v18, v2
	v_mov_b32_e32 v19, v2
	v_mov_b32_e32 v20, v2
	v_mov_b32_e32 v21, v2
	v_mov_b32_e32 v22, v2
	v_mov_b32_e32 v23, v2
	v_mov_b32_e32 v24, v2
	v_mov_b32_e32 v25, v2
	v_mov_b32_e32 v26, v2
	v_mov_b32_e32 v27, v2
	v_mov_b32_e32 v28, v2
	v_mov_b32_e32 v29, v2
	v_mov_b32_e32 v51, v2
	v_mov_b32_e32 v52, v2
	v_mov_b32_e32 v53, v2
	v_mov_b32_e32 v54, v2
	v_mov_b32_e32 v55, v2
	v_mov_b32_e32 v56, v2
	v_mov_b32_e32 v57, v2
	v_mov_b32_e32 v58, v2
	v_mov_b32_e32 v59, v2
	v_mov_b32_e32 v60, v2
	v_mov_b32_e32 v61, v2
	v_mov_b32_e32 v62, v2
	v_mov_b32_e32 v63, v2
	v_mov_b32_e32 v64, v2
	v_mov_b32_e32 v65, v2
	v_mov_b32_e32 v66, v2
	v_mov_b32_e32 v67, v2
	v_mov_b32_e32 v68, v2
	v_mov_b32_e32 v69, v2
	v_mov_b32_e32 v70, v2
	v_mov_b32_e32 v71, v2
	v_mov_b32_e32 v72, v2
	v_mov_b32_e32 v73, v2
	v_mov_b32_e32 v74, v2
	v_mov_b32_e32 v75, v2
	v_mov_b32_e32 v76, v2
	v_mov_b32_e32 v77, v2
	v_mov_b32_e32 v78, v2
	v_mov_b32_e32 v79, v2
	v_mov_b32_e32 v80, v2
	v_mov_b32_e32 v81, v2
	v_mov_b32_e32 v82, v2
	v_mov_b32_e32 v83, v2
	v_mov_b32_e32 v84, v2
	v_mov_b32_e32 v85, v2
	v_mov_b32_e32 v86, v2
	v_mov_b32_e32 v87, v2
	v_mov_b32_e32 v88, v2
	v_mov_b32_e32 v89, v2
	v_mov_b32_e32 v90, v2
	v_mov_b32_e32 v91, v2
	v_mov_b32_e32 v92, v2
	v_mov_b32_e32 v93, v2
	v_mov_b32_e32 v94, v2
	v_mov_b32_e32 v95, v2
	v_mov_b32_e32 v96, v2
	v_mov_b32_e32 v97, v2
	v_mov_b32_e32 v98, v2
	v_mov_b32_e32 v99, v2
	v_mov_b32_e32 v100, v2
	v_mov_b32_e32 v101, v2
	v_mov_b32_e32 v102, v2
	v_mov_b32_e32 v103, v2
	v_mov_b32_e32 v104, v2
	v_mov_b32_e32 v105, v2
	v_mov_b32_e32 v106, v2
	v_mov_b32_e32 v107, v2
	v_mov_b32_e32 v108, v2
	v_mov_b32_e32 v109, v2
	v_mov_b32_e32 v110, v2
	v_mov_b32_e32 v111, v2
	v_mov_b32_e32 v112, v2
	v_mov_b32_e32 v113, v2
	v_mov_b32_e32 v114, v2
	v_mov_b32_e32 v115, v2
	v_mov_b32_e32 v116, v2
	v_mov_b32_e32 v117, v2
	v_mov_b32_e32 v118, v2
	v_mov_b32_e32 v119, v2
	v_mov_b32_e32 v120, v2
	v_mov_b32_e32 v121, v2
	v_mov_b32_e32 v122, v2
	v_mov_b32_e32 v123, v2
	v_mov_b32_e32 v124, v2
	v_mov_b32_e32 v125, v2
	v_mov_b32_e32 v126, v2
	v_mov_b32_e32 v127, v2
	v_mov_b32_e32 v128, v2
	v_mov_b32_e32 v129, v2
	s_waitcnt vmcnt(6) lgkmcnt(0)
	s_barrier
; DI void cfence() { asm volatile("" ::: "memory"); }
; DI int swz4(int row) { const int g = (row >> 2) & 3; return ((g << 1) ^ ((g >> 1) * 3)) & 3; }
; #define LSTORE2(RA, RB, P)                                       \
;   {                                                              \
;     char* dA_ = smem + (P) * 24576 + wofs;                       \
;     _Pragma("unroll") for (int j = 0; j < 4; ++j) *(u32x4*)(dA_ + j * 4096) = RA[j]; \
;     _Pragma("unroll") for (int j = 0; j < 2; ++j) *(u32x4*)(dA_ + 16384 + j * 4096) = RB[j]; \
;   }
; DI void gemm256_kloop(f32x4 (&acc)[8][4], const bf16_t* __restrict__ A, int lda, const bf16_t* __restrict__ Bt, int ldb,
;                       int K, int b, int s0, int col0, char* smem) {
;     ...
;   GLOAD2(xa, xb, 0);
;   GLOAD2(ya, yb, 1);
;   cfence();
;   LSTORE2(xa, xb, 0);
;   __syncthreads();
;   const int co = ((fq ^ swz4(fr)) << 4);
;   const int aofs = (wr * 128 + fr) * 64 + co, bofs = (wc * 64 + fr) * 64 + co;
	ds_read_b128 v[236:239], v160 offset:16384
	ds_read_b128 v[240:243], v160 offset:17408
	ds_read_b128 v[244:247], v160 offset:18432
	ds_read_b128 v[248:251], v160 offset:19456
	ds_read_b128 v[186:189], v161
	ds_read_b128 v[190:193], v161 offset:1024
	ds_read_b128 v[212:215], v161 offset:2048
	ds_read_b128 v[216:219], v161 offset:3072
	ds_read_b128 v[220:223], v161 offset:4096
	ds_read_b128 v[224:227], v161 offset:5120
	ds_read_b128 v[228:231], v161 offset:6144
	ds_read_b128 v[232:235], v161 offset:7168
	s_waitcnt vmcnt(0) lgkmcnt(0)
	s_barrier

; DI int tidx() { int t = __builtin_amdgcn_workitem_id_x(); asm volatile("" : "+v"(t)); return t; }
; DI brsrc_t make_rsrc(const void* p) { return __builtin_amdgcn_make_buffer_rsrc((void*)p, 0, 0x7fffffff, 0x00020000); }
; DI void cfence() { asm volatile("" ::: "memory"); }
; DI int swz4(int row) { const int g = (row >> 2) & 3; return ((g << 1) ^ ((g >> 1) * 3)) & 3; }
; #define LSTORE2(RA, RB, P)                                       \
;   {                                                              \
;     char* dA_ = smem + (P) * 24576 + wofs;                       \
;     _Pragma("unroll") for (int j = 0; j < 4; ++j) *(u32x4*)(dA_ + j * 4096) = RA[j]; \
;     _Pragma("unroll") for (int j = 0; j < 2; ++j) *(u32x4*)(dA_ + 16384 + j * 4096) = RB[j]; \
;   }
; DI void gemm256_kloop(f32x4 (&acc)[8][4], const bf16_t* __restrict__ A, int lda, const bf16_t* __restrict__ Bt, int ldb,
;                       int K, int b, int s0, int col0, char* smem) {
;   const int tid = tidx(), lane = tid & 63, wid = tid >> 6;
;   const int wr = wid >> 1, wc = wid & 1, fr = lane & 15, fq = lane >> 4;
;   const int lrow = tid >> 2, lkc = tid & 3;
;   const brsrc_t rA = make_rsrc(A), rB = make_rsrc(Bt);
;   unsigned aoff[4];
; #pragma unroll
;   for (int j = 0; j < 4; ++j) {
;     int s = s0 + lrow + 64 * j;
;     s = s < 0 ? 0 : (s > SB - 1 ? SB - 1 : s);
;     aoff[j] = ((unsigned)(b * SB + s) * (unsigned)lda + lkc * 8) * 2u;
;   }
;   const unsigned boff = ((unsigned)(col0 + lrow) * (unsigned)ldb + lkc * 8) * 2u;
;   const unsigned bstep = 64u * (unsigned)ldb * 2u;
;   const int wofs = lrow * 64 + ((lkc ^ swz4(lrow)) << 4);
;   const int nk = K >> 5;
;   u32x4 xa[4], xb[2], ya[4], yb[2];
;     ...
;   GLOAD2(xa, xb, 0);
;   GLOAD2(ya, yb, 1);
;   cfence();
;   LSTORE2(xa, xb, 0);
;   __syncthreads();
;   const int co = ((fq ^ swz4(fr)) << 4);
;   const int aofs = (wr * 128 + fr) * 64 + co, bofs = (wc * 64 + fr) * 64 + co;
.LBB0_352:
	s_mul_hi_i32 s2, s11, 0x2aaaaaab
	s_lshr_b32 s3, s2, 31
	s_ashr_i32 s2, s2, 3
	s_add_i32 s2, s2, s3
	s_mul_i32 s3, s2, 0xffffffd0
	s_add_i32 s6, s3, s11
	s_mul_hi_i32 s3, s11, 0xa80a80a9
	s_add_i32 s3, s3, s11
	s_lshr_b32 s7, s3, 31
	s_ashr_i32 s3, s3, 11
	s_add_i32 s3, s3, s7
	s_mul_i32 s7, s3, 0xffffffbf
	s_waitcnt vmcnt(0)
	v_mov_b32_e32 v32, v194
	s_add_i32 s7, s7, s2
	s_mul_i32 s12, s3, 0x4100
	v_ashrrev_i32_e32 v33, 2, v32
	v_lshl_add_u32 v2, s7, 8, v33
	v_max_i32_e32 v4, 0xffffffc0, v2
	v_add_u32_e32 v4, 64, v4
	v_min_u32_e32 v4, 0x40ff, v4
	v_and_b32_e32 v34, 3, v32
	s_movk_i32 s7, 0x1080
	v_add_u32_e32 v4, s12, v4
	v_lshlrev_b32_e32 v3, 4, v34
	v_mul_lo_u32 v4, v4, s7
	v_med3_i32 v0, v2, 0, v201
	v_or_b32_e32 v154, v4, v3
	v_max_i32_e32 v4, 0xffffff80, v2
	v_max_i32_e32 v2, 0xffffff40, v2
	v_add_u32_e32 v2, 0xc0, v2
	v_min_u32_e32 v2, 0x40ff, v2
	v_add_u32_e32 v2, s12, v2
	v_mul_lo_u32 v2, v2, s7
	v_add_u32_e32 v4, 0x80, v4
	v_or_b32_e32 v156, v2, v3
	v_lshl_add_u32 v2, s6, 7, v33
	v_min_u32_e32 v4, 0x40ff, v4
	v_mul_lo_u32 v2, v2, s7
	v_add_u32_e32 v0, s12, v0
	v_add_u32_e32 v4, s12, v4
	v_or_b32_e32 v157, v2, v3
	v_mul_lo_u32 v0, v0, s7
	v_mul_lo_u32 v4, v4, s7
	s_mov_b32 s6, s22
	s_mov_b32 s7, s23
	v_add_u32_e32 v158, 0x42000, v157
	v_or_b32_e32 v0, v0, v3
	v_or_b32_e32 v155, v4, v3
	v_bfe_u32 v162, v194, 4, 2
	v_lshlrev_b32_e32 v162, 2, v162
	v_mov_b32_e32 v163, 0x1320
	v_lshrrev_b32_e32 v162, v162, v163
	v_and_b32_e32 v162, 3, v162
	v_lshlrev_b32_e32 v162, 4, v162
	v_xor_b32_e32 v0, v0, v162
	v_xor_b32_e32 v154, v154, v162
	v_xor_b32_e32 v155, v155, v162
	v_xor_b32_e32 v156, v156, v162
	v_xor_b32_e32 v157, v157, v162
	v_xor_b32_e32 v158, v158, v162
	v_lshrrev_b32_e32 v163, 6, v194
	s_nop 0
	v_readfirstlane_b32 s98, v163
	s_lshl_b32 s98, s98, 10
	s_mov_b32 m0, s98
	s_nop 0
	buffer_load_dwordx4 v0, s[20:23], 0 offen lds
	s_add_u32 m0, m0, 0x1000
	s_nop 0
	buffer_load_dwordx4 v154, s[20:23], 0 offen lds
	s_add_u32 m0, m0, 0x1000
	s_nop 0
	buffer_load_dwordx4 v155, s[20:23], 0 offen lds
	s_add_u32 m0, m0, 0x1000
	s_nop 0
	buffer_load_dwordx4 v156, s[20:23], 0 offen lds
	s_add_u32 m0, m0, 0x1000
	s_nop 0
	buffer_load_dwordx4 v157, s[4:7], 0 offen lds
	s_add_u32 m0, m0, 0x1000
	s_nop 0
	buffer_load_dwordx4 v158, s[4:7], 0 offen lds
	s_add_u32 m0, s98, 0x6000
	s_nop 0
	buffer_load_dwordx4 v0, s[20:23], 64 offen lds
	s_add_u32 m0, m0, 0x1000
	s_nop 0
	buffer_load_dwordx4 v154, s[20:23], 64 offen lds
	s_add_u32 m0, m0, 0x1000
	s_nop 0
	buffer_load_dwordx4 v155, s[20:23], 64 offen lds
	s_add_u32 m0, m0, 0x1000
	s_nop 0
	buffer_load_dwordx4 v156, s[20:23], 64 offen lds
	s_add_u32 m0, m0, 0x1000
	s_nop 0
	buffer_load_dwordx4 v157, s[4:7], 64 offen lds
	s_add_u32 m0, m0, 0x1000
	s_nop 0
	buffer_load_dwordx4 v158, s[4:7], 64 offen lds
	v_lshrrev_b32_e32 v37, 1, v32
	v_bfe_i32 v36, v32, 3, 1
	v_lshlrev_b32_e32 v39, 6, v33
	v_lshrrev_b32_e32 v33, 1, v33
	v_and_b32_e32 v37, 2, v37
	v_bfe_i32 v35, v32, 5, 1
	v_and_b32_e32 v33, 2, v33
	v_bitop3_b32 v36, v36, v37, 3 bitop3:0x6c
	v_bitop3_b32 v33, v35, v33, 3 bitop3:0x6c
	v_lshlrev_b32_e32 v35, 4, v36
	v_lshlrev_b32_e32 v38, 6, v32
	v_xor_b32_e32 v33, v33, v34
	v_bitop3_b32 v32, v35, v32, 48 bitop3:0x78
	s_movk_i32 s13, 0x13c0
	v_mov_b32_e32 v2, 0
	v_lshl_or_b32 v159, v33, 4, v39
	v_and_or_b32 v160, v38, s13, v32
	s_movk_i32 s13, 0xe3c0
	s_mov_b32 s9, 0
	s_movk_i32 s8, 0x80
	v_mov_b32_e32 v3, v2
	v_mov_b32_e32 v4, v2
	v_mov_b32_e32 v5, v2
	v_mov_b32_e32 v6, v2
	v_mov_b32_e32 v7, v2
	v_and_or_b32 v161, v38, s13, v32
	v_mov_b32_e32 v32, v2
	v_mov_b32_e32 v33, v2
	v_mov_b32_e32 v34, v2
	v_mov_b32_e32 v35, v2
	v_mov_b32_e32 v36, v2
	v_mov_b32_e32 v37, v2
	v_mov_b32_e32 v38, v2
	v_mov_b32_e32 v39, v2
	v_mov_b32_e32 v40, v2
	v_mov_b32_e32 v41, v2
	v_mov_b32_e32 v42, v2
	v_mov_b32_e32 v43, v2
	v_mov_b32_e32 v44, v2
	v_mov_b32_e32 v45, v2
	v_mov_b32_e32 v46, v2
	v_mov_b32_e32 v47, v2
	v_mov_b32_e32 v48, v2
	v_mov_b32_e32 v49, v2
	v_mov_b32_e32 v50, v2
	v_mov_b32_e32 v51, v2
	v_mov_b32_e32 v52, v2
	v_mov_b32_e32 v53, v2
	v_mov_b32_e32 v54, v2
	v_mov_b32_e32 v55, v2
	v_mov_b32_e32 v56, v2
	v_mov_b32_e32 v57, v2
	v_mov_b32_e32 v8, v2
	v_mov_b32_e32 v9, v2
	v_mov_b32_e32 v10, v2
	v_mov_b32_e32 v11, v2
	v_mov_b32_e32 v12, v2
	v_mov_b32_e32 v13, v2
	v_mov_b32_e32 v14, v2
	v_mov_b32_e32 v15, v2
	v_mov_b32_e32 v16, v2
	v_mov_b32_e32 v17, v2
	v_mov_b32_e32 v18, v2
	v_mov_b32_e32 v19, v2
	v_mov_b32_e32 v20, v2
	v_mov_b32_e32 v21, v2
	v_mov_b32_e32 v22, v2
	v_mov_b32_e32 v23, v2
	v_mov_b32_e32 v24, v2
	v_mov_b32_e32 v25, v2
	v_mov_b32_e32 v26, v2
	v_mov_b32_e32 v27, v2
	v_mov_b32_e32 v28, v2
	v_mov_b32_e32 v29, v2
	v_mov_b32_e32 v30, v2
	v_mov_b32_e32 v31, v2
	v_mov_b32_e32 v58, v2
	v_mov_b32_e32 v59, v2
	v_mov_b32_e32 v60, v2
	v_mov_b32_e32 v61, v2
	v_mov_b32_e32 v62, v2
	v_mov_b32_e32 v63, v2
	v_mov_b32_e32 v64, v2
	v_mov_b32_e32 v65, v2
	v_mov_b32_e32 v66, v2
	v_mov_b32_e32 v67, v2
	v_mov_b32_e32 v68, v2
	v_mov_b32_e32 v69, v2
	v_mov_b32_e32 v70, v2
	v_mov_b32_e32 v71, v2
	v_mov_b32_e32 v72, v2
	v_mov_b32_e32 v73, v2
	v_mov_b32_e32 v74, v2
	v_mov_b32_e32 v75, v2
	v_mov_b32_e32 v76, v2
	v_mov_b32_e32 v77, v2
	v_mov_b32_e32 v78, v2
	v_mov_b32_e32 v79, v2
	v_mov_b32_e32 v80, v2
	v_mov_b32_e32 v81, v2
	v_mov_b32_e32 v82, v2
	v_mov_b32_e32 v83, v2
	v_mov_b32_e32 v84, v2
	v_mov_b32_e32 v85, v2
	v_mov_b32_e32 v86, v2
	v_mov_b32_e32 v87, v2
	v_mov_b32_e32 v88, v2
	v_mov_b32_e32 v89, v2
	v_mov_b32_e32 v90, v2
	v_mov_b32_e32 v91, v2
	v_mov_b32_e32 v92, v2
	v_mov_b32_e32 v93, v2
	v_mov_b32_e32 v94, v2
	v_mov_b32_e32 v95, v2
	v_mov_b32_e32 v96, v2
	v_mov_b32_e32 v97, v2
	v_mov_b32_e32 v98, v2
	v_mov_b32_e32 v99, v2
	v_mov_b32_e32 v100, v2
	v_mov_b32_e32 v101, v2
	v_mov_b32_e32 v102, v2
	v_mov_b32_e32 v103, v2
	v_mov_b32_e32 v104, v2
	v_mov_b32_e32 v105, v2
	v_mov_b32_e32 v106, v2
	v_mov_b32_e32 v107, v2
	v_mov_b32_e32 v108, v2
	v_mov_b32_e32 v109, v2
	v_mov_b32_e32 v110, v2
	v_mov_b32_e32 v111, v2
	v_mov_b32_e32 v112, v2
	v_mov_b32_e32 v113, v2
	v_mov_b32_e32 v114, v2
	v_mov_b32_e32 v115, v2
	v_mov_b32_e32 v116, v2
	v_mov_b32_e32 v117, v2
	v_mov_b32_e32 v118, v2
	v_mov_b32_e32 v119, v2
	v_mov_b32_e32 v120, v2
	v_mov_b32_e32 v121, v2
	v_mov_b32_e32 v122, v2
	v_mov_b32_e32 v123, v2
	v_mov_b32_e32 v124, v2
	v_mov_b32_e32 v125, v2
	v_mov_b32_e32 v126, v2
	v_mov_b32_e32 v127, v2
	v_mov_b32_e32 v128, v2
	v_mov_b32_e32 v129, v2
	s_waitcnt vmcnt(6) lgkmcnt(0)
	s_barrier
	ds_read_b128 v[236:239], v160 offset:16384
	ds_read_b128 v[240:243], v160 offset:17408
	ds_read_b128 v[244:247], v160 offset:18432
	ds_read_b128 v[248:251], v160 offset:19456
	ds_read_b128 v[186:189], v161
	ds_read_b128 v[190:193], v161 offset:1024
	ds_read_b128 v[212:215], v161 offset:2048
	ds_read_b128 v[216:219], v161 offset:3072
	ds_read_b128 v[220:223], v161 offset:4096
	ds_read_b128 v[224:227], v161 offset:5120
	ds_read_b128 v[228:231], v161 offset:6144
	ds_read_b128 v[232:235], v161 offset:7168
	s_waitcnt vmcnt(0) lgkmcnt(0)
	s_barrier
; DI void cfence() { asm volatile("" ::: "memory"); }
; DI int swz4(int row) { const int g = (row >> 2) & 3; return ((g << 1) ^ ((g >> 1) * 3)) & 3; }
; #define LSTORE2(RA, RB, P)                                       \
;   {                                                              \
;     char* dA_ = smem + (P) * 24576 + wofs;                       \
;     _Pragma("unroll") for (int j = 0; j < 4; ++j) *(u32x4*)(dA_ + j * 4096) = RA[j]; \
;     _Pragma("unroll") for (int j = 0; j < 2; ++j) *(u32x4*)(dA_ + 16384 + j * 4096) = RB[j]; \
;   }
; DI void gemm256_kloop(f32x4 (&acc)[8][4], const bf16_t* __restrict__ A, int lda, const bf16_t* __restrict__ Bt, int ldb,
;                       int K, int b, int s0, int col0, char* smem) {
;     ...
;   GLOAD2(xa, xb, 0);
;   GLOAD2(ya, yb, 1);
;   cfence();
;   LSTORE2(xa, xb, 0);
;   __syncthreads();
;   const int co = ((fq ^ swz4(fr)) << 4);
;   const int aofs = (wr * 128 + fr) * 64 + co, bofs = (wc * 64 + fr) * 64 + co;
;   for (int kt = 0; kt < nk; kt += 2) {
;     GLOAD2(xa, xb, kt + 2);
;     cfence();
;     COMPUTE2(0);
;     LSTORE2(ya, yb, 1);
;     __syncthreads();
;     if (kt + 1 < nk) {
;       GLOAD2(ya, yb, kt + 3);
;       cfence();
;       COMPUTE2(1);
;       LSTORE2(xa, xb, 0);
;       __syncthreads();
;     }
;   }
.LBB0_353:
	s_add_i32 s13, s9, 2
	s_cmp_lt_u32 s9, 62
	s_cselect_b64 s[14:15], -1, 0
	s_and_b64 vcc, s[14:15], exec
	s_cselect_b32 s14, s8, 0xfc0
	s_setprio 1
	s_mov_b32 m0, s98
	v_mfma_f32_16x16x32_bf16 v[126:129], v[186:189], v[236:239], v[126:129]
	buffer_load_dwordx4 v0, s[20:23], s14 offen lds
	s_add_u32 m0, m0, 0x1000
	v_mfma_f32_16x16x32_bf16 v[122:125], v[186:189], v[240:243], v[122:125]
	buffer_load_dwordx4 v154, s[20:23], s14 offen lds
	s_add_u32 m0, m0, 0x1000
	v_mfma_f32_16x16x32_bf16 v[118:121], v[186:189], v[244:247], v[118:121]
	buffer_load_dwordx4 v155, s[20:23], s14 offen lds
	s_add_u32 m0, m0, 0x1000
	v_mfma_f32_16x16x32_bf16 v[114:117], v[186:189], v[248:251], v[114:117]
	buffer_load_dwordx4 v156, s[20:23], s14 offen lds
	s_add_u32 m0, m0, 0x1000
	v_mfma_f32_16x16x32_bf16 v[110:113], v[190:193], v[236:239], v[110:113]
	buffer_load_dwordx4 v157, s[4:7], s14 offen lds
	s_add_u32 m0, m0, 0x1000
	v_mfma_f32_16x16x32_bf16 v[106:109], v[190:193], v[240:243], v[106:109]
	buffer_load_dwordx4 v158, s[4:7], s14 offen lds
	v_mfma_f32_16x16x32_bf16 v[102:105], v[190:193], v[244:247], v[102:105]
	ds_read_b128 v[170:173], v160 offset:40960
	v_mfma_f32_16x16x32_bf16 v[98:101], v[190:193], v[248:251], v[98:101]
	v_mfma_f32_16x16x32_bf16 v[94:97], v[212:215], v[236:239], v[94:97]
	ds_read_b128 v[174:177], v160 offset:41984
	v_mfma_f32_16x16x32_bf16 v[90:93], v[212:215], v[240:243], v[90:93]
	v_mfma_f32_16x16x32_bf16 v[86:89], v[212:215], v[244:247], v[86:89]
	ds_read_b128 v[178:181], v160 offset:43008
	v_mfma_f32_16x16x32_bf16 v[82:85], v[212:215], v[248:251], v[82:85]
	v_mfma_f32_16x16x32_bf16 v[78:81], v[216:219], v[236:239], v[78:81]
	ds_read_b128 v[182:185], v160 offset:44032
	v_mfma_f32_16x16x32_bf16 v[74:77], v[216:219], v[240:243], v[74:77]
	v_mfma_f32_16x16x32_bf16 v[70:73], v[216:219], v[244:247], v[70:73]
	ds_read_b128 v[130:133], v161 offset:24576
	v_mfma_f32_16x16x32_bf16 v[66:69], v[216:219], v[248:251], v[66:69]
	v_mfma_f32_16x16x32_bf16 v[62:65], v[220:223], v[236:239], v[62:65]
	ds_read_b128 v[134:137], v161 offset:25600
	v_mfma_f32_16x16x32_bf16 v[58:61], v[220:223], v[240:243], v[58:61]
	v_mfma_f32_16x16x32_bf16 v[54:57], v[220:223], v[244:247], v[54:57]
	ds_read_b128 v[138:141], v161 offset:26624
	v_mfma_f32_16x16x32_bf16 v[50:53], v[220:223], v[248:251], v[50:53]
	v_mfma_f32_16x16x32_bf16 v[46:49], v[224:227], v[236:239], v[46:49]
	ds_read_b128 v[142:145], v161 offset:27648
	v_mfma_f32_16x16x32_bf16 v[42:45], v[224:227], v[240:243], v[42:45]
	v_mfma_f32_16x16x32_bf16 v[38:41], v[224:227], v[244:247], v[38:41]
	ds_read_b128 v[146:149], v161 offset:28672
	v_mfma_f32_16x16x32_bf16 v[34:37], v[224:227], v[248:251], v[34:37]
	v_mfma_f32_16x16x32_bf16 v[30:33], v[228:231], v[236:239], v[30:33]
	ds_read_b128 v[150:153], v161 offset:29696
	v_mfma_f32_16x16x32_bf16 v[26:29], v[228:231], v[240:243], v[26:29]
	v_mfma_f32_16x16x32_bf16 v[22:25], v[228:231], v[244:247], v[22:25]
	ds_read_b128 v[162:165], v161 offset:30720
	v_mfma_f32_16x16x32_bf16 v[18:21], v[228:231], v[248:251], v[18:21]
	v_mfma_f32_16x16x32_bf16 v[14:17], v[232:235], v[236:239], v[14:17]
	ds_read_b128 v[166:169], v161 offset:31744
	v_mfma_f32_16x16x32_bf16 v[10:13], v[232:235], v[240:243], v[10:13]
	v_mfma_f32_16x16x32_bf16 v[6:9], v[232:235], v[244:247], v[6:9]
	v_mfma_f32_16x16x32_bf16 v[2:5], v[232:235], v[248:251], v[2:5]
	s_setprio 0
	s_min_u32 s9, s9, 60
	s_lshl_b32 s9, s9, 6
	s_addk_i32 s9, 0xc0
	s_waitcnt vmcnt(0) lgkmcnt(0)
	s_barrier
	s_setprio 1
	s_add_u32 m0, s98, 0x6000
	v_mfma_f32_16x16x32_bf16 v[126:129], v[130:133], v[170:173], v[126:129]
	buffer_load_dwordx4 v0, s[20:23], s9 offen lds
	s_add_u32 m0, m0, 0x1000
	v_mfma_f32_16x16x32_bf16 v[122:125], v[130:133], v[174:177], v[122:125]
	buffer_load_dwordx4 v154, s[20:23], s9 offen lds
	s_add_u32 m0, m0, 0x1000
	v_mfma_f32_16x16x32_bf16 v[118:121], v[130:133], v[178:181], v[118:121]
	buffer_load_dwordx4 v155, s[20:23], s9 offen lds
	s_add_u32 m0, m0, 0x1000
	v_mfma_f32_16x16x32_bf16 v[114:117], v[130:133], v[182:185], v[114:117]
	buffer_load_dwordx4 v156, s[20:23], s9 offen lds
	s_add_u32 m0, m0, 0x1000
	v_mfma_f32_16x16x32_bf16 v[110:113], v[134:137], v[170:173], v[110:113]
	buffer_load_dwordx4 v157, s[4:7], s9 offen lds
	s_add_u32 m0, m0, 0x1000
	v_mfma_f32_16x16x32_bf16 v[106:109], v[134:137], v[174:177], v[106:109]
	buffer_load_dwordx4 v158, s[4:7], s9 offen lds
	v_mfma_f32_16x16x32_bf16 v[102:105], v[134:137], v[178:181], v[102:105]
	ds_read_b128 v[236:239], v160 offset:16384
	v_mfma_f32_16x16x32_bf16 v[98:101], v[134:137], v[182:185], v[98:101]
	v_mfma_f32_16x16x32_bf16 v[94:97], v[138:141], v[170:173], v[94:97]
	ds_read_b128 v[240:243], v160 offset:17408
	v_mfma_f32_16x16x32_bf16 v[90:93], v[138:141], v[174:177], v[90:93]
	v_mfma_f32_16x16x32_bf16 v[86:89], v[138:141], v[178:181], v[86:89]
	ds_read_b128 v[244:247], v160 offset:18432
	v_mfma_f32_16x16x32_bf16 v[82:85], v[138:141], v[182:185], v[82:85]
	v_mfma_f32_16x16x32_bf16 v[78:81], v[142:145], v[170:173], v[78:81]
	ds_read_b128 v[248:251], v160 offset:19456
	v_mfma_f32_16x16x32_bf16 v[74:77], v[142:145], v[174:177], v[74:77]
	v_mfma_f32_16x16x32_bf16 v[70:73], v[142:145], v[178:181], v[70:73]
	ds_read_b128 v[186:189], v161
	v_mfma_f32_16x16x32_bf16 v[66:69], v[142:145], v[182:185], v[66:69]
	v_mfma_f32_16x16x32_bf16 v[62:65], v[146:149], v[170:173], v[62:65]
	ds_read_b128 v[190:193], v161 offset:1024
	v_mfma_f32_16x16x32_bf16 v[58:61], v[146:149], v[174:177], v[58:61]
	v_mfma_f32_16x16x32_bf16 v[54:57], v[146:149], v[178:181], v[54:57]
	ds_read_b128 v[212:215], v161 offset:2048
	v_mfma_f32_16x16x32_bf16 v[50:53], v[146:149], v[182:185], v[50:53]
	v_mfma_f32_16x16x32_bf16 v[46:49], v[150:153], v[170:173], v[46:49]
	ds_read_b128 v[216:219], v161 offset:3072
	v_mfma_f32_16x16x32_bf16 v[42:45], v[150:153], v[174:177], v[42:45]
	v_mfma_f32_16x16x32_bf16 v[38:41], v[150:153], v[178:181], v[38:41]
	ds_read_b128 v[220:223], v161 offset:4096
	v_mfma_f32_16x16x32_bf16 v[34:37], v[150:153], v[182:185], v[34:37]
	v_mfma_f32_16x16x32_bf16 v[30:33], v[162:165], v[170:173], v[30:33]
	ds_read_b128 v[224:227], v161 offset:5120
	v_mfma_f32_16x16x32_bf16 v[26:29], v[162:165], v[174:177], v[26:29]
	v_mfma_f32_16x16x32_bf16 v[22:25], v[162:165], v[178:181], v[22:25]
	ds_read_b128 v[228:231], v161 offset:6144
	v_mfma_f32_16x16x32_bf16 v[18:21], v[162:165], v[182:185], v[18:21]
	v_mfma_f32_16x16x32_bf16 v[14:17], v[166:169], v[170:173], v[14:17]
	ds_read_b128 v[232:235], v161 offset:7168
	v_mfma_f32_16x16x32_bf16 v[10:13], v[166:169], v[174:177], v[10:13]
	v_mfma_f32_16x16x32_bf16 v[6:9], v[166:169], v[178:181], v[6:9]
	v_mfma_f32_16x16x32_bf16 v[2:5], v[166:169], v[182:185], v[2:5]
	s_setprio 0
	s_addk_i32 s8, 0x80
	s_mov_b32 s9, s13
	s_waitcnt vmcnt(0) lgkmcnt(0)
	s_barrier
	s_cbranch_vccnz .LBB0_353
	s_mul_hi_i32 s13, s3, 0x4100
	s_lshl_b32 s3, s2, 8
	s_sub_i32 s14, s3, s12
	s_lshl_b32 s3, s11, 7
	s_mulk_i32 s2, 0x1800
	s_sub_i32 s15, s3, s2
	s_mov_b32 s8, 0
	s_mov_b64 s[2:3], -1
	s_waitcnt vmcnt(0)
	s_branch .LBB0_356

; DI int tidx() { int t = __builtin_amdgcn_workitem_id_x(); asm volatile("" : "+v"(t)); return t; }
; DI int bidx() { int t = __builtin_amdgcn_workgroup_id_x(); asm volatile("" : "+s"(t)); return t; }
; DI int gdim() { int t = (int)__ockl_get_num_groups(0); asm volatile("" : "+s"(t)); return t; }
; DI brsrc_t make_rsrc(const void* p) { return __builtin_amdgcn_make_buffer_rsrc((void*)p, 0, 0x7fffffff, 0x00020000); }
; DI void cfence() { asm volatile("" ::: "memory"); }
; DI int swz4(int row) { const int g = (row >> 2) & 3; return ((g << 1) ^ ((g >> 1) * 3)) & 3; }
; DI void gemm256_kloop(f32x4 (&acc)[8][4], const bf16_t* __restrict__ A, int lda, const bf16_t* __restrict__ Bt, int ldb,
;                       int K, int b, int s0, int col0, char* smem) {
;   const int tid = tidx(), lane = tid & 63, wid = tid >> 6;
;   const int wr = wid >> 1, wc = wid & 1, fr = lane & 15, fq = lane >> 4;
;   const int lrow = tid >> 2, lkc = tid & 3;
;   const brsrc_t rA = make_rsrc(A), rB = make_rsrc(Bt);
;   unsigned aoff[4];
; #pragma unroll
;   for (int j = 0; j < 4; ++j) {
;     int s = s0 + lrow + 64 * j;
;     s = s < 0 ? 0 : (s > SB - 1 ? SB - 1 : s);
;     aoff[j] = ((unsigned)(b * SB + s) * (unsigned)lda + lkc * 8) * 2u;
;   }
;   const unsigned boff = ((unsigned)(col0 + lrow) * (unsigned)ldb + lkc * 8) * 2u;
;   const unsigned bstep = 64u * (unsigned)ldb * 2u;
;   const int wofs = lrow * 64 + ((lkc ^ swz4(lrow)) << 4);
;   const int nk = K >> 5;
;   u32x4 xa[4], xb[2], ya[4], yb[2];
;     ...
;   GLOAD2(xa, xb, 0);
;   GLOAD2(ya, yb, 1);
;   cfence();
;   LSTORE2(xa, xb, 0);
;   __syncthreads();
;   const int co = ((fq ^ swz4(fr)) << 4);
;   const int aofs = (wr * 128 + fr) * 64 + co, bofs = (wc * 64 + fr) * 64 + co;
; template <class Epi>
; DI void gemm256_phase_plain(const bf16_t* A, int lda, const bf16_t* Bt, int ldb, int K, int ntn, char* smem, const Epi& epi,
;                             bool skip_ctx = false) {
;     ...
;     const int total = 128 * ntn;
;     for (int it = bidx(); it < total; it += gdim()) {
;       const int mt = it / ntn, nt = it - mt * ntn;
;       const int mt2 = mt + 1 + (mt >= 64 ? 1 : 0);
;       gemm256_item_plain(A, lda, Bt, ldb, K, ntn, smem, epi, mt2 * ntn + nt);
.LBB0_366:
	s_cmpk_gt_i32 s11, 0xbff
	s_cselect_b32 s2, 0x60, 48
	s_add_i32 s3, s2, s11
	s_mul_hi_i32 s2, s3, 0x2aaaaaab
	s_lshr_b32 s6, s2, 31
	s_ashr_i32 s2, s2, 3
	s_add_i32 s2, s2, s6
	s_mul_hi_i32 s7, s3, 0xa80a80a9
	s_mul_i32 s6, s2, 0xffffffd0
	s_add_i32 s7, s7, s3
	s_add_i32 s6, s6, s3
	s_lshr_b32 s3, s7, 31
	s_ashr_i32 s7, s7, 11
	s_add_i32 s3, s7, s3
	s_mul_i32 s7, s3, 0xffffffbf
	s_waitcnt vmcnt(0)
	v_mov_b32_e32 v7, v194
	s_add_i32 s7, s7, s2
	s_mul_i32 s12, s3, 0x4100
	v_ashrrev_i32_e32 v32, 2, v7
	v_lshl_add_u32 v2, s7, 8, v32
	v_max_i32_e32 v4, 0xffffffc0, v2
	v_add_u32_e32 v4, 64, v4
	v_min_u32_e32 v4, 0x40ff, v4
	s_lshl_b32 s10, s6, 7
	v_and_b32_e32 v33, 3, v7
	s_movk_i32 s6, 0x1080
	v_add_u32_e32 v4, s12, v4
	v_lshlrev_b32_e32 v3, 4, v33
	v_mul_lo_u32 v4, v4, s6
	v_med3_i32 v0, v2, 0, v201
	v_or_b32_e32 v154, v4, v3
	v_max_i32_e32 v4, 0xffffff80, v2
	v_max_i32_e32 v2, 0xffffff40, v2
	v_add_u32_e32 v2, 0xc0, v2
	v_min_u32_e32 v2, 0x40ff, v2
	v_add_u32_e32 v2, s12, v2
	v_mul_lo_u32 v2, v2, s6
	v_add_u32_e32 v4, 0x80, v4
	v_or_b32_e32 v156, v2, v3
	v_add_u32_e32 v2, s10, v32
	v_min_u32_e32 v4, 0x40ff, v4
	v_mul_lo_u32 v2, v2, s6
	v_add_u32_e32 v0, s12, v0
	v_add_u32_e32 v4, s12, v4
	v_or_b32_e32 v157, v2, v3
	v_mul_lo_u32 v0, v0, s6
	v_mul_lo_u32 v4, v4, s6
	s_mov_b32 s6, s22
	s_mov_b32 s7, s23
	v_add_u32_e32 v158, 0x42000, v157
	v_or_b32_e32 v0, v0, v3
	v_or_b32_e32 v155, v4, v3
	v_bfe_u32 v162, v194, 4, 2
	v_lshlrev_b32_e32 v162, 2, v162
	v_mov_b32_e32 v163, 0x1320
	v_lshrrev_b32_e32 v162, v162, v163
	v_and_b32_e32 v162, 3, v162
	v_lshlrev_b32_e32 v162, 4, v162
	v_xor_b32_e32 v0, v0, v162
	v_xor_b32_e32 v154, v154, v162
	v_xor_b32_e32 v155, v155, v162
	v_xor_b32_e32 v156, v156, v162
	v_xor_b32_e32 v157, v157, v162
	v_xor_b32_e32 v158, v158, v162
	v_lshrrev_b32_e32 v163, 6, v194
	s_nop 0
	v_readfirstlane_b32 s98, v163
	s_lshl_b32 s98, s98, 10
	s_mov_b32 m0, s98
	s_nop 0
	buffer_load_dwordx4 v0, s[20:23], 0 offen lds
	s_add_u32 m0, m0, 0x1000
	s_nop 0
	buffer_load_dwordx4 v154, s[20:23], 0 offen lds
	s_add_u32 m0, m0, 0x1000
	s_nop 0
	buffer_load_dwordx4 v155, s[20:23], 0 offen lds
	s_add_u32 m0, m0, 0x1000
	s_nop 0
	buffer_load_dwordx4 v156, s[20:23], 0 offen lds
	s_add_u32 m0, m0, 0x1000
	s_nop 0
	buffer_load_dwordx4 v157, s[4:7], 0 offen lds
	s_add_u32 m0, m0, 0x1000
	s_nop 0
	buffer_load_dwordx4 v158, s[4:7], 0 offen lds
	s_add_u32 m0, s98, 0x6000
	s_nop 0
	buffer_load_dwordx4 v0, s[20:23], 64 offen lds
	s_add_u32 m0, m0, 0x1000
	s_nop 0
	buffer_load_dwordx4 v154, s[20:23], 64 offen lds
	s_add_u32 m0, m0, 0x1000
	s_nop 0
	buffer_load_dwordx4 v155, s[20:23], 64 offen lds
	s_add_u32 m0, m0, 0x1000
	s_nop 0
	buffer_load_dwordx4 v156, s[20:23], 64 offen lds
	s_add_u32 m0, m0, 0x1000
	s_nop 0
	buffer_load_dwordx4 v157, s[4:7], 64 offen lds
	s_add_u32 m0, m0, 0x1000
	s_nop 0
	buffer_load_dwordx4 v158, s[4:7], 64 offen lds
	v_lshrrev_b32_e32 v36, 1, v7
	v_bfe_i32 v35, v7, 3, 1
	v_lshlrev_b32_e32 v38, 6, v32
	v_lshrrev_b32_e32 v32, 1, v32
	v_and_b32_e32 v36, 2, v36
	v_bfe_i32 v34, v7, 5, 1
	v_and_b32_e32 v32, 2, v32
	v_bitop3_b32 v35, v35, v36, 3 bitop3:0x6c
	v_bitop3_b32 v32, v34, v32, 3 bitop3:0x6c
	v_lshlrev_b32_e32 v34, 4, v35
	v_lshlrev_b32_e32 v37, 6, v7
	v_xor_b32_e32 v32, v32, v33
	v_bitop3_b32 v7, v34, v7, 48 bitop3:0x78
	s_movk_i32 s13, 0x13c0
	v_mov_b32_e32 v2, 0
	v_lshl_or_b32 v159, v32, 4, v38
	v_and_or_b32 v160, v37, s13, v7
	s_movk_i32 s13, 0xe3c0
	s_mov_b32 s9, 0
	s_movk_i32 s8, 0x80
	v_mov_b32_e32 v3, v2
	v_mov_b32_e32 v4, v2
	v_mov_b32_e32 v5, v2
	v_mov_b32_e32 v6, v2
	v_and_or_b32 v161, v37, s13, v7
	v_mov_b32_e32 v7, v2
	v_mov_b32_e32 v32, v2
	v_mov_b32_e32 v33, v2
	v_mov_b32_e32 v34, v2
	v_mov_b32_e32 v35, v2
	v_mov_b32_e32 v36, v2
	v_mov_b32_e32 v37, v2
	v_mov_b32_e32 v38, v2
	v_mov_b32_e32 v39, v2
	v_mov_b32_e32 v40, v2
	v_mov_b32_e32 v41, v2
	v_mov_b32_e32 v42, v2
	v_mov_b32_e32 v43, v2
	v_mov_b32_e32 v44, v2
	v_mov_b32_e32 v45, v2
	v_mov_b32_e32 v46, v2
	v_mov_b32_e32 v47, v2
	v_mov_b32_e32 v48, v2
	v_mov_b32_e32 v49, v2
	v_mov_b32_e32 v50, v2
	v_mov_b32_e32 v51, v2
	v_mov_b32_e32 v52, v2
	v_mov_b32_e32 v53, v2
	v_mov_b32_e32 v54, v2
	v_mov_b32_e32 v8, v2
	v_mov_b32_e32 v9, v2
	v_mov_b32_e32 v10, v2
	v_mov_b32_e32 v11, v2
	v_mov_b32_e32 v12, v2
	v_mov_b32_e32 v13, v2
	v_mov_b32_e32 v14, v2
	v_mov_b32_e32 v15, v2
	v_mov_b32_e32 v16, v2
	v_mov_b32_e32 v17, v2
	v_mov_b32_e32 v18, v2
	v_mov_b32_e32 v19, v2
	v_mov_b32_e32 v20, v2
	v_mov_b32_e32 v21, v2
	v_mov_b32_e32 v22, v2
	v_mov_b32_e32 v23, v2
	v_mov_b32_e32 v24, v2
	v_mov_b32_e32 v25, v2
	v_mov_b32_e32 v26, v2
	v_mov_b32_e32 v27, v2
	v_mov_b32_e32 v28, v2
	v_mov_b32_e32 v29, v2
	v_mov_b32_e32 v30, v2
	v_mov_b32_e32 v31, v2
	v_mov_b32_e32 v55, v2
	v_mov_b32_e32 v56, v2
	v_mov_b32_e32 v57, v2
	v_mov_b32_e32 v58, v2
	v_mov_b32_e32 v59, v2
	v_mov_b32_e32 v60, v2
	v_mov_b32_e32 v61, v2
	v_mov_b32_e32 v62, v2
	v_mov_b32_e32 v63, v2
	v_mov_b32_e32 v64, v2
	v_mov_b32_e32 v65, v2
	v_mov_b32_e32 v66, v2
	v_mov_b32_e32 v67, v2
	v_mov_b32_e32 v68, v2
	v_mov_b32_e32 v69, v2
	v_mov_b32_e32 v70, v2
	v_mov_b32_e32 v71, v2
	v_mov_b32_e32 v72, v2
	v_mov_b32_e32 v73, v2
	v_mov_b32_e32 v74, v2
	v_mov_b32_e32 v75, v2
	v_mov_b32_e32 v76, v2
	v_mov_b32_e32 v77, v2
	v_mov_b32_e32 v78, v2
	v_mov_b32_e32 v79, v2
	v_mov_b32_e32 v80, v2
	v_mov_b32_e32 v81, v2
	v_mov_b32_e32 v82, v2
	v_mov_b32_e32 v83, v2
	v_mov_b32_e32 v84, v2
	v_mov_b32_e32 v85, v2
	v_mov_b32_e32 v86, v2
	v_mov_b32_e32 v87, v2
	v_mov_b32_e32 v88, v2
	v_mov_b32_e32 v89, v2
	v_mov_b32_e32 v90, v2
	v_mov_b32_e32 v91, v2
	v_mov_b32_e32 v92, v2
	v_mov_b32_e32 v93, v2
	v_mov_b32_e32 v94, v2
	v_mov_b32_e32 v95, v2
	v_mov_b32_e32 v96, v2
	v_mov_b32_e32 v97, v2
	v_mov_b32_e32 v98, v2
	v_mov_b32_e32 v99, v2
	v_mov_b32_e32 v100, v2
	v_mov_b32_e32 v101, v2
	v_mov_b32_e32 v102, v2
	v_mov_b32_e32 v103, v2
	v_mov_b32_e32 v104, v2
	v_mov_b32_e32 v105, v2
	v_mov_b32_e32 v106, v2
	v_mov_b32_e32 v107, v2
	v_mov_b32_e32 v108, v2
	v_mov_b32_e32 v109, v2
	v_mov_b32_e32 v110, v2
	v_mov_b32_e32 v111, v2
	v_mov_b32_e32 v112, v2
	v_mov_b32_e32 v113, v2
	v_mov_b32_e32 v114, v2
	v_mov_b32_e32 v115, v2
	v_mov_b32_e32 v116, v2
	v_mov_b32_e32 v117, v2
	v_mov_b32_e32 v118, v2
	v_mov_b32_e32 v119, v2
	v_mov_b32_e32 v120, v2
	v_mov_b32_e32 v121, v2
	v_mov_b32_e32 v122, v2
	v_mov_b32_e32 v123, v2
	v_mov_b32_e32 v124, v2
	v_mov_b32_e32 v125, v2
	v_mov_b32_e32 v126, v2
	v_mov_b32_e32 v127, v2
	v_mov_b32_e32 v128, v2
	v_mov_b32_e32 v129, v2
	s_waitcnt vmcnt(6) lgkmcnt(0)
	s_barrier
	ds_read_b128 v[236:239], v160 offset:16384
	ds_read_b128 v[240:243], v160 offset:17408
	ds_read_b128 v[244:247], v160 offset:18432
	ds_read_b128 v[248:251], v160 offset:19456
	ds_read_b128 v[186:189], v161
	ds_read_b128 v[190:193], v161 offset:1024
	ds_read_b128 v[212:215], v161 offset:2048
	ds_read_b128 v[216:219], v161 offset:3072
	ds_read_b128 v[220:223], v161 offset:4096
	ds_read_b128 v[224:227], v161 offset:5120
	ds_read_b128 v[228:231], v161 offset:6144
	ds_read_b128 v[232:235], v161 offset:7168
	s_waitcnt vmcnt(0) lgkmcnt(0)
	s_barrier
; DI void cfence() { asm volatile("" ::: "memory"); }
; DI int swz4(int row) { const int g = (row >> 2) & 3; return ((g << 1) ^ ((g >> 1) * 3)) & 3; }
; #define LSTORE2(RA, RB, P)                                       \
;   {                                                              \
;     char* dA_ = smem + (P) * 24576 + wofs;                       \
;     _Pragma("unroll") for (int j = 0; j < 4; ++j) *(u32x4*)(dA_ + j * 4096) = RA[j]; \
;     _Pragma("unroll") for (int j = 0; j < 2; ++j) *(u32x4*)(dA_ + 16384 + j * 4096) = RB[j]; \
;   }
; DI void gemm256_kloop(f32x4 (&acc)[8][4], const bf16_t* __restrict__ A, int lda, const bf16_t* __restrict__ Bt, int ldb,
;                       int K, int b, int s0, int col0, char* smem) {
;     ...
;   GLOAD2(xa, xb, 0);
;   GLOAD2(ya, yb, 1);
;   cfence();
;   LSTORE2(xa, xb, 0);
;   __syncthreads();
;   const int co = ((fq ^ swz4(fr)) << 4);
;   const int aofs = (wr * 128 + fr) * 64 + co, bofs = (wc * 64 + fr) * 64 + co;
;   for (int kt = 0; kt < nk; kt += 2) {
;     GLOAD2(xa, xb, kt + 2);
;     cfence();
;     COMPUTE2(0);
;     LSTORE2(ya, yb, 1);
;     __syncthreads();
;     if (kt + 1 < nk) {
;       GLOAD2(ya, yb, kt + 3);
;       cfence();
;       COMPUTE2(1);
;       LSTORE2(xa, xb, 0);
;       __syncthreads();
;     }
;   }
.LBB0_367:
	s_add_i32 s13, s9, 2
	s_cmp_lt_u32 s9, 62
	s_cselect_b64 s[14:15], -1, 0
	s_and_b64 vcc, s[14:15], exec
	s_cselect_b32 s14, s8, 0xfc0
	s_setprio 1
	s_mov_b32 m0, s98
	v_mfma_f32_16x16x32_bf16 v[126:129], v[186:189], v[236:239], v[126:129]
	buffer_load_dwordx4 v0, s[20:23], s14 offen lds
	s_add_u32 m0, m0, 0x1000
	v_mfma_f32_16x16x32_bf16 v[122:125], v[186:189], v[240:243], v[122:125]
	buffer_load_dwordx4 v154, s[20:23], s14 offen lds
	s_add_u32 m0, m0, 0x1000
	v_mfma_f32_16x16x32_bf16 v[118:121], v[186:189], v[244:247], v[118:121]
	buffer_load_dwordx4 v155, s[20:23], s14 offen lds
	s_add_u32 m0, m0, 0x1000
	v_mfma_f32_16x16x32_bf16 v[114:117], v[186:189], v[248:251], v[114:117]
	buffer_load_dwordx4 v156, s[20:23], s14 offen lds
	s_add_u32 m0, m0, 0x1000
	v_mfma_f32_16x16x32_bf16 v[110:113], v[190:193], v[236:239], v[110:113]
	buffer_load_dwordx4 v157, s[4:7], s14 offen lds
	s_add_u32 m0, m0, 0x1000
	v_mfma_f32_16x16x32_bf16 v[106:109], v[190:193], v[240:243], v[106:109]
	buffer_load_dwordx4 v158, s[4:7], s14 offen lds
	v_mfma_f32_16x16x32_bf16 v[102:105], v[190:193], v[244:247], v[102:105]
	ds_read_b128 v[170:173], v160 offset:40960
	v_mfma_f32_16x16x32_bf16 v[98:101], v[190:193], v[248:251], v[98:101]
	v_mfma_f32_16x16x32_bf16 v[94:97], v[212:215], v[236:239], v[94:97]
	ds_read_b128 v[174:177], v160 offset:41984
	v_mfma_f32_16x16x32_bf16 v[90:93], v[212:215], v[240:243], v[90:93]
	v_mfma_f32_16x16x32_bf16 v[86:89], v[212:215], v[244:247], v[86:89]
	ds_read_b128 v[178:181], v160 offset:43008
	v_mfma_f32_16x16x32_bf16 v[82:85], v[212:215], v[248:251], v[82:85]
	v_mfma_f32_16x16x32_bf16 v[78:81], v[216:219], v[236:239], v[78:81]
	ds_read_b128 v[182:185], v160 offset:44032
	v_mfma_f32_16x16x32_bf16 v[74:77], v[216:219], v[240:243], v[74:77]
	v_mfma_f32_16x16x32_bf16 v[70:73], v[216:219], v[244:247], v[70:73]
	ds_read_b128 v[130:133], v161 offset:24576
	v_mfma_f32_16x16x32_bf16 v[66:69], v[216:219], v[248:251], v[66:69]
	v_mfma_f32_16x16x32_bf16 v[62:65], v[220:223], v[236:239], v[62:65]
	ds_read_b128 v[134:137], v161 offset:25600
	v_mfma_f32_16x16x32_bf16 v[58:61], v[220:223], v[240:243], v[58:61]
	v_mfma_f32_16x16x32_bf16 v[54:57], v[220:223], v[244:247], v[54:57]
	ds_read_b128 v[138:141], v161 offset:26624
	v_mfma_f32_16x16x32_bf16 v[50:53], v[220:223], v[248:251], v[50:53]
	v_mfma_f32_16x16x32_bf16 v[46:49], v[224:227], v[236:239], v[46:49]
	ds_read_b128 v[142:145], v161 offset:27648
	v_mfma_f32_16x16x32_bf16 v[42:45], v[224:227], v[240:243], v[42:45]
	v_mfma_f32_16x16x32_bf16 v[38:41], v[224:227], v[244:247], v[38:41]
	ds_read_b128 v[146:149], v161 offset:28672
	v_mfma_f32_16x16x32_bf16 v[34:37], v[224:227], v[248:251], v[34:37]
	v_mfma_f32_16x16x32_bf16 v[30:33], v[228:231], v[236:239], v[30:33]
	ds_read_b128 v[150:153], v161 offset:29696
	v_mfma_f32_16x16x32_bf16 v[26:29], v[228:231], v[240:243], v[26:29]
	v_mfma_f32_16x16x32_bf16 v[22:25], v[228:231], v[244:247], v[22:25]
	ds_read_b128 v[162:165], v161 offset:30720
	v_mfma_f32_16x16x32_bf16 v[18:21], v[228:231], v[248:251], v[18:21]
	v_mfma_f32_16x16x32_bf16 v[14:17], v[232:235], v[236:239], v[14:17]
	ds_read_b128 v[166:169], v161 offset:31744
	v_mfma_f32_16x16x32_bf16 v[10:13], v[232:235], v[240:243], v[10:13]
	v_mfma_f32_16x16x32_bf16 v[6:9], v[232:235], v[244:247], v[6:9]
	v_mfma_f32_16x16x32_bf16 v[2:5], v[232:235], v[248:251], v[2:5]
	s_setprio 0
	s_min_u32 s9, s9, 60
	s_lshl_b32 s9, s9, 6
	s_addk_i32 s9, 0xc0
	s_waitcnt vmcnt(0) lgkmcnt(0)
	s_barrier
	s_setprio 1
	s_add_u32 m0, s98, 0x6000
	v_mfma_f32_16x16x32_bf16 v[126:129], v[130:133], v[170:173], v[126:129]
	buffer_load_dwordx4 v0, s[20:23], s9 offen lds
	s_add_u32 m0, m0, 0x1000
	v_mfma_f32_16x16x32_bf16 v[122:125], v[130:133], v[174:177], v[122:125]
	buffer_load_dwordx4 v154, s[20:23], s9 offen lds
	s_add_u32 m0, m0, 0x1000
	v_mfma_f32_16x16x32_bf16 v[118:121], v[130:133], v[178:181], v[118:121]
	buffer_load_dwordx4 v155, s[20:23], s9 offen lds
	s_add_u32 m0, m0, 0x1000
	v_mfma_f32_16x16x32_bf16 v[114:117], v[130:133], v[182:185], v[114:117]
	buffer_load_dwordx4 v156, s[20:23], s9 offen lds
	s_add_u32 m0, m0, 0x1000
	v_mfma_f32_16x16x32_bf16 v[110:113], v[134:137], v[170:173], v[110:113]
	buffer_load_dwordx4 v157, s[4:7], s9 offen lds
	s_add_u32 m0, m0, 0x1000
	v_mfma_f32_16x16x32_bf16 v[106:109], v[134:137], v[174:177], v[106:109]
	buffer_load_dwordx4 v158, s[4:7], s9 offen lds
	v_mfma_f32_16x16x32_bf16 v[102:105], v[134:137], v[178:181], v[102:105]
	ds_read_b128 v[236:239], v160 offset:16384
	v_mfma_f32_16x16x32_bf16 v[98:101], v[134:137], v[182:185], v[98:101]
	v_mfma_f32_16x16x32_bf16 v[94:97], v[138:141], v[170:173], v[94:97]
	ds_read_b128 v[240:243], v160 offset:17408
	v_mfma_f32_16x16x32_bf16 v[90:93], v[138:141], v[174:177], v[90:93]
	v_mfma_f32_16x16x32_bf16 v[86:89], v[138:141], v[178:181], v[86:89]
	ds_read_b128 v[244:247], v160 offset:18432
	v_mfma_f32_16x16x32_bf16 v[82:85], v[138:141], v[182:185], v[82:85]
	v_mfma_f32_16x16x32_bf16 v[78:81], v[142:145], v[170:173], v[78:81]
	ds_read_b128 v[248:251], v160 offset:19456
	v_mfma_f32_16x16x32_bf16 v[74:77], v[142:145], v[174:177], v[74:77]
	v_mfma_f32_16x16x32_bf16 v[70:73], v[142:145], v[178:181], v[70:73]
	ds_read_b128 v[186:189], v161
	v_mfma_f32_16x16x32_bf16 v[66:69], v[142:145], v[182:185], v[66:69]
	v_mfma_f32_16x16x32_bf16 v[62:65], v[146:149], v[170:173], v[62:65]
	ds_read_b128 v[190:193], v161 offset:1024
	v_mfma_f32_16x16x32_bf16 v[58:61], v[146:149], v[174:177], v[58:61]
	v_mfma_f32_16x16x32_bf16 v[54:57], v[146:149], v[178:181], v[54:57]
	ds_read_b128 v[212:215], v161 offset:2048
	v_mfma_f32_16x16x32_bf16 v[50:53], v[146:149], v[182:185], v[50:53]
	v_mfma_f32_16x16x32_bf16 v[46:49], v[150:153], v[170:173], v[46:49]
	ds_read_b128 v[216:219], v161 offset:3072
	v_mfma_f32_16x16x32_bf16 v[42:45], v[150:153], v[174:177], v[42:45]
	v_mfma_f32_16x16x32_bf16 v[38:41], v[150:153], v[178:181], v[38:41]
	ds_read_b128 v[220:223], v161 offset:4096
	v_mfma_f32_16x16x32_bf16 v[34:37], v[150:153], v[182:185], v[34:37]
	v_mfma_f32_16x16x32_bf16 v[30:33], v[162:165], v[170:173], v[30:33]
	ds_read_b128 v[224:227], v161 offset:5120
	v_mfma_f32_16x16x32_bf16 v[26:29], v[162:165], v[174:177], v[26:29]
	v_mfma_f32_16x16x32_bf16 v[22:25], v[162:165], v[178:181], v[22:25]
	ds_read_b128 v[228:231], v161 offset:6144
	v_mfma_f32_16x16x32_bf16 v[18:21], v[162:165], v[182:185], v[18:21]
	v_mfma_f32_16x16x32_bf16 v[14:17], v[166:169], v[170:173], v[14:17]
	ds_read_b128 v[232:235], v161 offset:7168
	v_mfma_f32_16x16x32_bf16 v[10:13], v[166:169], v[174:177], v[10:13]
	v_mfma_f32_16x16x32_bf16 v[6:9], v[166:169], v[178:181], v[6:9]
	v_mfma_f32_16x16x32_bf16 v[2:5], v[166:169], v[182:185], v[2:5]
	s_setprio 0
	s_addk_i32 s8, 0x80
	s_mov_b32 s9, s13
	s_waitcnt vmcnt(0) lgkmcnt(0)
	s_barrier
	s_cbranch_vccnz .LBB0_367
	s_lshl_b32 s2, s2, 8
	s_mul_hi_i32 s13, s3, 0x4100
	s_sub_i32 s14, s2, s12
	s_mov_b32 s8, 0
	s_mov_b64 s[2:3], -1
	s_waitcnt vmcnt(0)
	s_branch .LBB0_370

; DI int tidx() { int t = __builtin_amdgcn_workitem_id_x(); asm volatile("" : "+v"(t)); return t; }
; DI brsrc_t make_rsrc(const void* p) { return __builtin_amdgcn_make_buffer_rsrc((void*)p, 0, 0x7fffffff, 0x00020000); }
; template <int DQK, int DV>
; DI void attn_tile(const bf16_t* Q, int ldq, const bf16_t* Kb, int ldk, const bf16_t* Vt, bf16_t* O, int ldo, int b, int sq0,
;                   int r0a, int r0b, int r1a, int r1b, float m_init, float l_init, char* smem) {
;   const int tid = tidx(), lane = tid & 63, wid = tid >> 6;
;   const int ql = lane & 31, hh = lane >> 5;
;   constexpr int NS = DQK / 16, NB = DV / 32;
;   constexpr int KB = 32 * DQK * 2, VB = DV * 64, BUF = KB + VB;
;   const int qs = sq0 + wid * 32 + ql;
;   bf16x8 qf[NS];
;   {
;     const bf16_t* qp = Q + (size_t)(b * SB + qs) * ldq + 8 * hh;
; #pragma unroll
;     for (int s = 0; s < NS; ++s) qf[s] = *(const bf16x8*)(qp + 16 * s);
;   }
;   f32x16 acc[NB];
; #pragma unroll
;   for (int i = 0; i < NB; ++i)
; #pragma unroll
;     for (int r = 0; r < 16; ++r) acc[i][r] = 0.f;
;   float m = m_init, lsum = l_init;
;   const int n0 = (r0b - r0a) >> 5, n1 = (r1b > r1a) ? ((r1b - r1a) >> 5) : 0;
;   const int nt = n0 + n1;
;   const brsrc_t Kbase = make_rsrc(Kb + (size_t)b * SB * ldk);
;   const brsrc_t Vbase = make_rsrc(Vt);
;   AttnMap<DQK, DV> mp;
;   mp.init(ldk);
;   u32x4 rk[DQK / 64], rv[DV / 64];
;   attn_load<DQK, DV>(rk, rv, mp, Kbase, ldk, Vbase, r0a);
;   attn_store<DQK, DV>(rk, rv, mp, smem, smem + KB);
;   __syncthreads();
.LBB0_406:
	s_and_b32 s3, s1, 7
	s_mul_i32 s1, s3, 0x180
	s_add_u32 s6, s14, s1
	s_addc_u32 s7, s15, 0
	s_add_u32 s34, s16, s1
	s_addc_u32 s38, s17, 0
	s_ashr_i32 s1, s0, 31
	s_lshl_b64 s[20:21], s[0:1], 10
	s_lshl_b32 s1, s3, 7
	s_or_b32 s3, s20, s1
	s_mul_i32 s4, s3, 0x8200
	s_mul_hi_u32 s3, s3, 0x8200
	s_mul_i32 s20, s21, 0x8200
	s_add_i32 s3, s3, s20
	s_waitcnt vmcnt(3)
	v_mov_b32_e32 v28, v194
	s_add_u32 s4, s18, s4
	s_mul_i32 s20, s0, 0x4100
	v_ashrrev_i32_e32 v0, 1, v28
	s_addc_u32 s3, s19, s3
	v_and_b32_e32 v29, 31, v28
	v_and_b32_e32 v0, 0xffffffe0, v0
	s_add_i32 s20, s20, s5
	v_bfe_u32 v154, v28, 5, 1
	v_add3_u32 v152, s20, v29, v0
	s_waitcnt vmcnt(1)
	v_mov_b64_e32 v[2:3], s[6:7]
	v_mad_i64_i32 v[2:3], s[6:7], v152, s66, v[2:3]
	v_lshlrev_b32_e32 v0, 4, v154
	v_lshl_add_u64 v[2:3], v[2:3], 0, v[0:1]
	v_mov_b32_e32 v0, v194
	global_load_dwordx4 v[140:143], v[2:3], off
	global_load_dwordx4 v[136:139], v[2:3], off offset:32
	global_load_dwordx4 v[132:135], v[2:3], off offset:64
	global_load_dwordx4 v[128:131], v[2:3], off offset:96
	global_load_dwordx4 v[124:127], v[2:3], off offset:128
	global_load_dwordx4 v[120:123], v[2:3], off offset:160
	global_load_dwordx4 v[116:119], v[2:3], off offset:192
	global_load_dwordx4 v[112:115], v[2:3], off offset:224
	global_load_dwordx4 v[108:111], v[2:3], off offset:256
	global_load_dwordx4 v[104:107], v[2:3], off offset:288
	global_load_dwordx4 v[100:103], v[2:3], off offset:320
	global_load_dwordx4 v[96:99], v[2:3], off offset:352
	s_mul_hi_i32 s5, s0, 0x32c8000
	v_mul_hi_i32 v2, v0, s69
	s_mul_i32 s0, s0, 0x32c8000
	v_lshrrev_b32_e32 v3, 31, v2
	v_ashrrev_i32_e32 v2, 2, v2
	s_add_u32 s20, s34, s0
	s_waitcnt vmcnt(12)
	v_add_u32_e32 v30, v2, v3
	s_addc_u32 s0, s38, s5
	v_mad_u64_u32 v[22:23], s[38:39], v30, s50, v[0:1]
	v_mul_lo_u32 v2, v30, s66
	v_lshl_add_u32 v165, v22, 4, v2
	v_add_u32_e32 v2, 0x100, v0
	v_mul_hi_i32 v3, v2, s69
	v_lshrrev_b32_e32 v4, 31, v3
	v_ashrrev_i32_e32 v3, 2, v3
	v_add_u32_e32 v23, v3, v4
	v_mad_u64_u32 v[24:25], s[38:39], v23, s50, v[2:3]
	v_mul_lo_u32 v3, v23, s66
	v_add_u32_e32 v4, 0x200, v0
	v_lshl_add_u32 v166, v24, 4, v3
	v_mul_hi_i32 v3, v4, s69
	v_lshrrev_b32_e32 v5, 31, v3
	v_ashrrev_i32_e32 v3, 2, v3
	v_add_u32_e32 v25, v3, v5
	v_mad_u64_u32 v[26:27], s[38:39], v25, s50, v[4:5]
	v_mul_lo_u32 v3, v25, s66
	s_and_b32 s21, s0, 0xffff
	v_lshl_add_u32 v167, v26, 4, v3
	v_lshlrev_b32_e32 v3, 4, v0
	v_ashrrev_i32_e32 v27, 2, v0
	s_mov_b32 s0, 0x8200
	v_and_b32_e32 v18, 48, v3
	v_mul_lo_u32 v3, v27, s0
	s_and_b32 s5, s3, 0xffff
	s_mov_b32 s6, s22
	s_mov_b32 s7, s23
	v_or_b32_e32 v168, v3, v18
	v_ashrrev_i32_e32 v31, 2, v2
	buffer_load_dwordx4 v[2:5], v165, s[20:23], 0 offen
	buffer_load_dwordx4 v[6:9], v166, s[20:23], 0 offen
	buffer_load_dwordx4 v[10:13], v167, s[20:23], 0 offen
	buffer_load_dwordx4 v[14:17], v168, s[4:7], 0 offen
	v_mul_lo_u32 v19, v31, s0
	v_or_b32_e32 v169, v19, v18
	buffer_load_dwordx4 v[18:21], v169, s[4:7], 0 offen
	v_lshrrev_b32_e32 v33, 1, v30
	v_bitop3_b32 v33, v33, 7, v0 bitop3:0x48
	v_and_or_b32 v22, v22, s48, v33
	v_mul_lo_u32 v30, v30, s79
	v_lshl_add_u32 v155, v22, 4, v30
	v_lshrrev_b32_e32 v22, 1, v23
	v_bitop3_b32 v22, v22, 7, v0 bitop3:0x48
	v_and_or_b32 v22, v24, s48, v22
	v_mul_lo_u32 v23, v23, s79
	v_lshl_add_u32 v156, v22, 4, v23
	v_lshrrev_b32_e32 v22, 1, v25
	v_bitop3_b32 v22, v22, 7, v0 bitop3:0x48
	v_and_or_b32 v22, v26, s48, v22
	v_mul_lo_u32 v23, v25, s79
	v_lshl_add_u32 v157, v22, 4, v23
	v_bfe_i32 v22, v0, 6, 1
	v_and_b32_e32 v23, 2, v0
	v_lshrrev_b32_e32 v25, 2, v27
	v_or_b32_e32 v24, 1, v23
	v_bitop3_b32 v25, v25, v22, 3 bitop3:0x28
	v_lshlrev_b32_e32 v0, 3, v0
	v_lshlrev_b32_e32 v26, 6, v27
	v_xor_b32_e32 v27, v25, v23
	v_xor_b32_e32 v25, v25, v24
	v_and_b32_e32 v0, 8, v0
	v_lshlrev_b32_e32 v25, 4, v25
	v_or3_b32 v161, v25, v26, v0
	v_lshrrev_b32_e32 v25, 2, v31
	v_bitop3_b32 v22, v25, v22, 3 bitop3:0x28
	v_xor_b32_e32 v23, v22, v23
	v_xor_b32_e32 v22, v22, v24
	v_lshlrev_b32_e32 v27, 4, v27
	v_lshlrev_b32_e32 v25, 6, v31
	v_lshlrev_b32_e32 v23, 4, v23
	v_lshlrev_b32_e32 v22, 4, v22
	v_or3_b32 v160, v27, v26, v0
	v_or3_b32 v158, v23, v25, v0
	v_or3_b32 v159, v22, v25, v0
	v_bfe_u32 v0, v28, 1, 3
	v_lshrrev_b32_e32 v32, 5, v28
	s_waitcnt vmcnt(4)
	ds_write_b128 v155, v[2:5]
	s_waitcnt vmcnt(3)
	ds_write_b128 v156, v[6:9]
	s_waitcnt vmcnt(2)
	ds_write_b128 v157, v[10:13]
	s_waitcnt vmcnt(1)
	ds_write_b64 v160, v[14:15] offset:12288
	ds_write_b64 v161, v[16:17] offset:12288
	s_waitcnt vmcnt(0)
	ds_write_b64 v158, v[18:19] offset:12288
	ds_write_b64 v159, v[20:21] offset:12288
	v_lshrrev_b32_e32 v2, 2, v28
	v_bfe_i32 v3, v28, 4, 1
	v_bitop3_b32 v4, v154, v0, 2 bitop3:0x36
	v_xor_b32_e32 v2, v3, v2
	v_bitop3_b32 v3, v32, v0, 1 bitop3:0x6c
	v_lshlrev_b32_e32 v174, 4, v4
	v_bitop3_b32 v4, v154, v0, 4 bitop3:0x36
	v_bitop3_b32 v0, v154, v0, 6 bitop3:0x36
	v_lshlrev_b32_e32 v173, 4, v3
	v_or_b32_e32 v3, 2, v154
	v_lshlrev_b32_e32 v171, 4, v0
	v_bitop3_b32 v0, v2, v154, 3 bitop3:0x6c
	v_lshlrev_b32_e32 v164, 4, v0
	v_bitop3_b32 v0, v2, v3, 3 bitop3:0x6c
	v_mov_b32_e32 v14, v1
	v_mov_b32_e32 v15, v1
	v_mul_u32_u24_e32 v170, 0x180, v29
	v_lshlrev_b32_e32 v163, 6, v29
	v_lshlrev_b32_e32 v172, 4, v4
	v_lshlrev_b32_e32 v162, 4, v0
	v_mov_b32_e32 v0, v1
	v_mov_b32_e32 v2, v1
	v_mov_b32_e32 v3, v1
	v_mov_b32_e32 v4, v1
	v_mov_b32_e32 v5, v1
	v_mov_b32_e32 v6, v1
	v_mov_b32_e32 v7, v1
	v_mov_b32_e32 v8, v1
	v_mov_b32_e32 v9, v1
	v_mov_b32_e32 v10, v1
	v_mov_b32_e32 v11, v1
	v_mov_b32_e32 v12, v1
	v_mov_b32_e32 v13, v1
	v_mov_b64_e32 v[30:31], v[14:15]
	v_mov_b64_e32 v[46:47], v[14:15]
	v_mov_b64_e32 v[62:63], v[14:15]
	v_mov_b64_e32 v[78:79], v[14:15]
	v_ashrrev_i32_e32 v153, 31, v152
	s_mov_b32 s0, 0
	s_add_i32 s2, s2, 1
	v_mov_b32_e32 v176, 0
	v_mov_b32_e32 v175, 0xf149f2ca
	s_mov_b32 s3, 0
	v_mov_b64_e32 v[28:29], v[12:13]
	v_mov_b64_e32 v[26:27], v[10:11]
	v_mov_b64_e32 v[24:25], v[8:9]
	v_mov_b64_e32 v[22:23], v[6:7]
	v_mov_b64_e32 v[20:21], v[4:5]
	v_mov_b64_e32 v[18:19], v[2:3]
	v_mov_b64_e32 v[16:17], v[0:1]
	v_mov_b64_e32 v[44:45], v[12:13]
	v_mov_b64_e32 v[42:43], v[10:11]
	v_mov_b64_e32 v[40:41], v[8:9]
	v_mov_b64_e32 v[38:39], v[6:7]
	v_mov_b64_e32 v[36:37], v[4:5]
	v_mov_b64_e32 v[34:35], v[2:3]
	v_mov_b64_e32 v[32:33], v[0:1]
	v_mov_b64_e32 v[60:61], v[12:13]
	v_mov_b64_e32 v[58:59], v[10:11]
	v_mov_b64_e32 v[56:57], v[8:9]
	v_mov_b64_e32 v[54:55], v[6:7]
	v_mov_b64_e32 v[52:53], v[4:5]
	v_mov_b64_e32 v[50:51], v[2:3]
	v_mov_b64_e32 v[48:49], v[0:1]
	v_mov_b64_e32 v[76:77], v[12:13]
	v_mov_b64_e32 v[74:75], v[10:11]
	v_mov_b64_e32 v[72:73], v[8:9]
	v_mov_b64_e32 v[70:71], v[6:7]
	v_mov_b64_e32 v[68:69], v[4:5]
	v_mov_b64_e32 v[66:67], v[2:3]
	v_mov_b64_e32 v[64:65], v[0:1]
	v_readlane_b32 s101, v253, 0
	s_nop 3
	s_bitcmp1_b32 s101, 8
	s_cbranch_scc0 .Lmla_prio_lo
	s_setprio 3

; DI int tidx() { int t = __builtin_amdgcn_workitem_id_x(); asm volatile("" : "+v"(t)); return t; }
; DI brsrc_t make_rsrc(const void* p) { return __builtin_amdgcn_make_buffer_rsrc((void*)p, 0, 0x7fffffff, 0x00020000); }
; DI void cfence() { asm volatile("" ::: "memory"); }
; DI int swz4(int row) { const int g = (row >> 2) & 3; return ((g << 1) ^ ((g >> 1) * 3)) & 3; }
; #define LSTORE2(RA, RB, P)                                       \
;   {                                                              \
;     char* dA_ = smem + (P) * 24576 + wofs;                       \
;     _Pragma("unroll") for (int j = 0; j < 4; ++j) *(u32x4*)(dA_ + j * 4096) = RA[j]; \
;     _Pragma("unroll") for (int j = 0; j < 2; ++j) *(u32x4*)(dA_ + 16384 + j * 4096) = RB[j]; \
;   }
; DI void gemm256_kloop(f32x4 (&acc)[8][4], const bf16_t* __restrict__ A, int lda, const bf16_t* __restrict__ Bt, int ldb,
;                       int K, int b, int s0, int col0, char* smem) {
;   const int tid = tidx(), lane = tid & 63, wid = tid >> 6;
;   const int wr = wid >> 1, wc = wid & 1, fr = lane & 15, fq = lane >> 4;
;   const int lrow = tid >> 2, lkc = tid & 3;
;   const brsrc_t rA = make_rsrc(A), rB = make_rsrc(Bt);
;   unsigned aoff[4];
; #pragma unroll
;   for (int j = 0; j < 4; ++j) {
;     int s = s0 + lrow + 64 * j;
;     s = s < 0 ? 0 : (s > SB - 1 ? SB - 1 : s);
;     aoff[j] = ((unsigned)(b * SB + s) * (unsigned)lda + lkc * 8) * 2u;
;   }
;   const unsigned boff = ((unsigned)(col0 + lrow) * (unsigned)ldb + lkc * 8) * 2u;
;   const unsigned bstep = 64u * (unsigned)ldb * 2u;
;   const int wofs = lrow * 64 + ((lkc ^ swz4(lrow)) << 4);
;   const int nk = K >> 5;
;   u32x4 xa[4], xb[2], ya[4], yb[2];
;     ...
;   GLOAD2(xa, xb, 0);
;   GLOAD2(ya, yb, 1);
;   cfence();
;   LSTORE2(xa, xb, 0);
;   __syncthreads();
;   const int co = ((fq ^ swz4(fr)) << 4);
;   const int aofs = (wr * 128 + fr) * 64 + co, bofs = (wc * 64 + fr) * 64 + co;
; DI void phase_uproj(const Params& P, int l, char* smem) {
;     ...
;     } else {
;       EpiUKV e{Kd, (bf16_t*)(Bg + B_VTMLA), ssq};
;       gemm256_item_plain(Z + 512, 1088, (const bf16_t*)(W + W_UKV), LDUQ, 512, 16, smem, e, it - nq);
;     }
.LBB0_423:
	s_cmpk_gt_i32 s34, 0x617
	s_mov_b64 s[2:3], -1
	s_cbranch_scc0 .LBB0_438
	s_add_i32 s10, s34, 0xfffff9e8
	s_lshr_b32 s9, s10, 4
	s_cmpk_gt_u32 s10, 0x40f
	s_cselect_b64 s[2:3], -1, 0
	s_and_b64 s[4:5], s[2:3], exec
	s_cselect_b32 s4, 0xffffffbf, 0
	s_cselect_b32 s8, 0x4100, 0
	s_add_i32 s4, s4, s9
	v_mov_b32_e32 v11, v194
	s_lshl_b32 s9, s4, 8
	s_lshl_b32 s4, s10, 7
	v_ashrrev_i32_e32 v36, 2, v11
	v_add_u32_e32 v2, s9, v36
	v_max_i32_e32 v4, 0xffffffc0, v2
	v_add_u32_e32 v4, 64, v4
	v_min_u32_e32 v4, 0x40ff, v4
	v_and_b32_e32 v37, 3, v11
	v_add_u32_e32 v4, s8, v4
	v_lshlrev_b32_e32 v3, 4, v37
	v_mul_u32_u24_e32 v4, 0x880, v4
	v_med3_i32 v0, v2, 0, v201
	v_or_b32_e32 v154, v4, v3
	v_max_i32_e32 v4, 0xffffff80, v2
	v_max_i32_e32 v2, 0xffffff40, v2
	v_add_u32_e32 v2, 0xc0, v2
	v_min_u32_e32 v2, 0x40ff, v2
	v_add_u32_e32 v2, s8, v2
	s_and_b32 s5, s4, 0x780
	v_mul_u32_u24_e32 v2, 0x880, v2
	v_add_u32_e32 v4, 0x80, v4
	v_or_b32_e32 v156, v2, v3
	v_add_u32_e32 v2, s5, v36
	s_movk_i32 s10, 0x480
	v_min_u32_e32 v4, 0x40ff, v4
	v_mul_lo_u32 v2, v2, s10
	v_add_u32_e32 v0, s8, v0
	v_add_u32_e32 v4, s8, v4
	v_or_b32_e32 v157, v2, v3
	v_mul_u32_u24_e32 v0, 0x880, v0
	v_mul_u32_u24_e32 v4, 0x880, v4
	s_mov_b32 s18, s22
	s_mov_b32 s19, s23
	v_add_u32_e32 v158, 0x12000, v157
	v_or_b32_e32 v0, v0, v3
	v_or_b32_e32 v155, v4, v3
	s_mov_b32 s14, s22
	s_mov_b32 s15, s23
	v_bfe_u32 v162, v194, 4, 2
	v_lshlrev_b32_e32 v162, 2, v162
	v_mov_b32_e32 v163, 0x1320
	v_lshrrev_b32_e32 v162, v162, v163
	v_and_b32_e32 v162, 3, v162
	v_lshlrev_b32_e32 v162, 4, v162
	v_xor_b32_e32 v0, v0, v162
	v_xor_b32_e32 v154, v154, v162
	v_xor_b32_e32 v155, v155, v162
	v_xor_b32_e32 v156, v156, v162
	v_xor_b32_e32 v157, v157, v162
	v_xor_b32_e32 v158, v158, v162
	v_lshrrev_b32_e32 v163, 6, v194
	s_nop 0
	v_readfirstlane_b32 s98, v163
	s_lshl_b32 s98, s98, 10
	s_mov_b32 m0, s98
	s_nop 0
	buffer_load_dwordx4 v0, s[12:15], 0 offen lds
	s_add_u32 m0, m0, 0x1000
	s_nop 0
	buffer_load_dwordx4 v154, s[12:15], 0 offen lds
	s_add_u32 m0, m0, 0x1000
	s_nop 0
	buffer_load_dwordx4 v155, s[12:15], 0 offen lds
	s_add_u32 m0, m0, 0x1000
	s_nop 0
	buffer_load_dwordx4 v156, s[12:15], 0 offen lds
	s_add_u32 m0, m0, 0x1000
	s_nop 0
	buffer_load_dwordx4 v157, s[16:19], 0 offen lds
	s_add_u32 m0, m0, 0x1000
	s_nop 0
	buffer_load_dwordx4 v158, s[16:19], 0 offen lds
	s_add_u32 m0, s98, 0x6000
	s_nop 0
	buffer_load_dwordx4 v0, s[12:15], 64 offen lds
	s_add_u32 m0, m0, 0x1000
	s_nop 0
	buffer_load_dwordx4 v154, s[12:15], 64 offen lds
	s_add_u32 m0, m0, 0x1000
	s_nop 0
	buffer_load_dwordx4 v155, s[12:15], 64 offen lds
	s_add_u32 m0, m0, 0x1000
	s_nop 0
	buffer_load_dwordx4 v156, s[12:15], 64 offen lds
	s_add_u32 m0, m0, 0x1000
	s_nop 0
	buffer_load_dwordx4 v157, s[16:19], 64 offen lds
	s_add_u32 m0, m0, 0x1000
	s_nop 0
	buffer_load_dwordx4 v158, s[16:19], 64 offen lds
	v_lshrrev_b32_e32 v40, 1, v11
	v_bfe_i32 v39, v11, 3, 1
	v_lshlrev_b32_e32 v42, 6, v36
	v_lshrrev_b32_e32 v36, 1, v36
	v_and_b32_e32 v40, 2, v40
	v_bfe_i32 v38, v11, 5, 1
	v_and_b32_e32 v36, 2, v36
	v_bitop3_b32 v39, v39, v40, 3 bitop3:0x6c
	v_bitop3_b32 v36, v38, v36, 3 bitop3:0x6c
	v_lshlrev_b32_e32 v38, 4, v39
	v_lshlrev_b32_e32 v41, 6, v11
	v_xor_b32_e32 v36, v36, v37
	v_bitop3_b32 v11, v38, v11, 48 bitop3:0x78
	s_movk_i32 s26, 0x13c0
	v_mov_b32_e32 v2, 0
	v_lshl_or_b32 v159, v36, 4, v42
	v_and_or_b32 v160, v41, s26, v11
	s_movk_i32 s26, 0xe3c0
	s_mov_b32 s11, 0
	s_movk_i32 s10, 0x80
	v_mov_b32_e32 v3, v2
	v_mov_b32_e32 v4, v2
	v_mov_b32_e32 v5, v2
	s_waitcnt vmcnt(12)
	v_mov_b32_e32 v6, v2
	v_mov_b32_e32 v7, v2
	v_mov_b32_e32 v8, v2
	v_mov_b32_e32 v9, v2
	v_mov_b32_e32 v10, v2
	v_and_or_b32 v161, v41, s26, v11
	v_mov_b32_e32 v11, v2
	v_mov_b32_e32 v36, v2
	v_mov_b32_e32 v37, v2
	v_mov_b32_e32 v38, v2
	v_mov_b32_e32 v39, v2
	v_mov_b32_e32 v40, v2
	v_mov_b32_e32 v41, v2
	v_mov_b32_e32 v42, v2
	v_mov_b32_e32 v43, v2
	v_mov_b32_e32 v44, v2
	v_mov_b32_e32 v45, v2
	v_mov_b32_e32 v46, v2
	v_mov_b32_e32 v47, v2
	v_mov_b32_e32 v48, v2
	v_mov_b32_e32 v49, v2
	v_mov_b32_e32 v50, v2
	v_mov_b32_e32 v51, v2
	v_mov_b32_e32 v52, v2
	v_mov_b32_e32 v53, v2
	v_mov_b32_e32 v54, v2
	v_mov_b32_e32 v55, v2
	v_mov_b32_e32 v56, v2
	v_mov_b32_e32 v12, v2
	v_mov_b32_e32 v13, v2
	v_mov_b32_e32 v14, v2
	v_mov_b32_e32 v15, v2
	v_mov_b32_e32 v16, v2
	v_mov_b32_e32 v17, v2
	v_mov_b32_e32 v18, v2
	v_mov_b32_e32 v19, v2
	v_mov_b32_e32 v20, v2
	v_mov_b32_e32 v21, v2
	v_mov_b32_e32 v22, v2
	v_mov_b32_e32 v23, v2
	v_mov_b32_e32 v24, v2
	v_mov_b32_e32 v25, v2
	v_mov_b32_e32 v26, v2
	v_mov_b32_e32 v27, v2
	v_mov_b32_e32 v28, v2
	v_mov_b32_e32 v29, v2
	v_mov_b32_e32 v30, v2
	v_mov_b32_e32 v31, v2
	v_mov_b32_e32 v32, v2
	v_mov_b32_e32 v33, v2
	v_mov_b32_e32 v34, v2
	v_mov_b32_e32 v35, v2
	v_mov_b32_e32 v57, v2
	v_mov_b32_e32 v58, v2
	v_mov_b32_e32 v59, v2
	v_mov_b32_e32 v60, v2
	v_mov_b32_e32 v61, v2
	v_mov_b32_e32 v62, v2
	v_mov_b32_e32 v63, v2
	v_mov_b32_e32 v64, v2
	v_mov_b32_e32 v65, v2
	v_mov_b32_e32 v66, v2
	v_mov_b32_e32 v67, v2
	v_mov_b32_e32 v68, v2
	v_mov_b32_e32 v69, v2
	v_mov_b32_e32 v70, v2
	v_mov_b32_e32 v71, v2
	v_mov_b32_e32 v72, v2
	v_mov_b32_e32 v73, v2
	v_mov_b32_e32 v74, v2
	v_mov_b32_e32 v75, v2
	v_mov_b32_e32 v76, v2
	v_mov_b32_e32 v77, v2
	v_mov_b32_e32 v78, v2
	v_mov_b32_e32 v79, v2
	v_mov_b32_e32 v80, v2
	v_mov_b32_e32 v81, v2
	v_mov_b32_e32 v82, v2
	v_mov_b32_e32 v83, v2
	v_mov_b32_e32 v84, v2
	v_mov_b32_e32 v85, v2
	v_mov_b32_e32 v86, v2
	v_mov_b32_e32 v87, v2
	v_mov_b32_e32 v88, v2
	v_mov_b32_e32 v89, v2
	v_mov_b32_e32 v90, v2
	v_mov_b32_e32 v91, v2
	v_mov_b32_e32 v92, v2
	v_mov_b32_e32 v93, v2
	v_mov_b32_e32 v94, v2
	v_mov_b32_e32 v95, v2
	v_mov_b32_e32 v96, v2
	v_mov_b32_e32 v97, v2
	v_mov_b32_e32 v98, v2
	v_mov_b32_e32 v99, v2
	v_mov_b32_e32 v100, v2
	v_mov_b32_e32 v101, v2
	v_mov_b32_e32 v102, v2
	v_mov_b32_e32 v103, v2
	v_mov_b32_e32 v104, v2
	v_mov_b32_e32 v105, v2
	v_mov_b32_e32 v106, v2
	v_mov_b32_e32 v107, v2
	v_mov_b32_e32 v108, v2
	v_mov_b32_e32 v109, v2
	v_mov_b32_e32 v110, v2
	v_mov_b32_e32 v111, v2
	v_mov_b32_e32 v112, v2
	v_mov_b32_e32 v113, v2
	v_mov_b32_e32 v114, v2
	v_mov_b32_e32 v115, v2
	v_mov_b32_e32 v116, v2
	v_mov_b32_e32 v117, v2
	v_mov_b32_e32 v118, v2
	v_mov_b32_e32 v119, v2
	v_mov_b32_e32 v120, v2
	v_mov_b32_e32 v121, v2
	v_mov_b32_e32 v122, v2
	v_mov_b32_e32 v123, v2
	v_mov_b32_e32 v124, v2
	v_mov_b32_e32 v125, v2
	v_mov_b32_e32 v126, v2
	v_mov_b32_e32 v127, v2
	v_mov_b32_e32 v128, v2
	v_mov_b32_e32 v129, v2
	s_waitcnt vmcnt(6) lgkmcnt(0)
	s_barrier
	ds_read_b128 v[236:239], v160 offset:16384
	ds_read_b128 v[240:243], v160 offset:17408
	ds_read_b128 v[244:247], v160 offset:18432
	ds_read_b128 v[248:251], v160 offset:19456
	ds_read_b128 v[186:189], v161
	ds_read_b128 v[190:193], v161 offset:1024
	ds_read_b128 v[212:215], v161 offset:2048
	ds_read_b128 v[216:219], v161 offset:3072
	ds_read_b128 v[220:223], v161 offset:4096
	ds_read_b128 v[224:227], v161 offset:5120
	ds_read_b128 v[228:231], v161 offset:6144
	ds_read_b128 v[232:235], v161 offset:7168
	s_waitcnt vmcnt(0) lgkmcnt(0)
	s_barrier
; DI void cfence() { asm volatile("" ::: "memory"); }
; DI int swz4(int row) { const int g = (row >> 2) & 3; return ((g << 1) ^ ((g >> 1) * 3)) & 3; }
; #define LSTORE2(RA, RB, P)                                       \
;   {                                                              \
;     char* dA_ = smem + (P) * 24576 + wofs;                       \
;     _Pragma("unroll") for (int j = 0; j < 4; ++j) *(u32x4*)(dA_ + j * 4096) = RA[j]; \
;     _Pragma("unroll") for (int j = 0; j < 2; ++j) *(u32x4*)(dA_ + 16384 + j * 4096) = RB[j]; \
;   }
; DI void gemm256_kloop(f32x4 (&acc)[8][4], const bf16_t* __restrict__ A, int lda, const bf16_t* __restrict__ Bt, int ldb,
;                       int K, int b, int s0, int col0, char* smem) {
;     ...
;   GLOAD2(xa, xb, 0);
;   GLOAD2(ya, yb, 1);
;   cfence();
;   LSTORE2(xa, xb, 0);
;   __syncthreads();
;   const int co = ((fq ^ swz4(fr)) << 4);
;   const int aofs = (wr * 128 + fr) * 64 + co, bofs = (wc * 64 + fr) * 64 + co;
;   for (int kt = 0; kt < nk; kt += 2) {
;     GLOAD2(xa, xb, kt + 2);
;     cfence();
;     COMPUTE2(0);
;     LSTORE2(ya, yb, 1);
;     __syncthreads();
.LBB0_425:
	s_add_i32 s26, s11, 2
	s_cmp_lt_u32 s11, 14
	s_cselect_b64 s[50:51], -1, 0
	s_and_b64 vcc, s[50:51], exec
	s_cselect_b32 s27, s10, 0x3c0
	s_setprio 1
	s_mov_b32 m0, s98
	v_mfma_f32_16x16x32_bf16 v[126:129], v[186:189], v[236:239], v[126:129]
	buffer_load_dwordx4 v0, s[12:15], s27 offen lds
	s_add_u32 m0, m0, 0x1000
	v_mfma_f32_16x16x32_bf16 v[122:125], v[186:189], v[240:243], v[122:125]
	buffer_load_dwordx4 v154, s[12:15], s27 offen lds
	s_add_u32 m0, m0, 0x1000
	v_mfma_f32_16x16x32_bf16 v[118:121], v[186:189], v[244:247], v[118:121]
	buffer_load_dwordx4 v155, s[12:15], s27 offen lds
	s_add_u32 m0, m0, 0x1000
	v_mfma_f32_16x16x32_bf16 v[114:117], v[186:189], v[248:251], v[114:117]
	buffer_load_dwordx4 v156, s[12:15], s27 offen lds
	s_add_u32 m0, m0, 0x1000
	v_mfma_f32_16x16x32_bf16 v[110:113], v[190:193], v[236:239], v[110:113]
	buffer_load_dwordx4 v157, s[16:19], s27 offen lds
	s_add_u32 m0, m0, 0x1000
	v_mfma_f32_16x16x32_bf16 v[106:109], v[190:193], v[240:243], v[106:109]
	buffer_load_dwordx4 v158, s[16:19], s27 offen lds
	v_mfma_f32_16x16x32_bf16 v[102:105], v[190:193], v[244:247], v[102:105]
	ds_read_b128 v[170:173], v160 offset:40960
	v_mfma_f32_16x16x32_bf16 v[98:101], v[190:193], v[248:251], v[98:101]
	v_mfma_f32_16x16x32_bf16 v[94:97], v[212:215], v[236:239], v[94:97]
	ds_read_b128 v[174:177], v160 offset:41984
	v_mfma_f32_16x16x32_bf16 v[90:93], v[212:215], v[240:243], v[90:93]
	v_mfma_f32_16x16x32_bf16 v[86:89], v[212:215], v[244:247], v[86:89]
	ds_read_b128 v[178:181], v160 offset:43008
	v_mfma_f32_16x16x32_bf16 v[82:85], v[212:215], v[248:251], v[82:85]
	v_mfma_f32_16x16x32_bf16 v[78:81], v[216:219], v[236:239], v[78:81]
	ds_read_b128 v[182:185], v160 offset:44032
	v_mfma_f32_16x16x32_bf16 v[74:77], v[216:219], v[240:243], v[74:77]
	v_mfma_f32_16x16x32_bf16 v[70:73], v[216:219], v[244:247], v[70:73]
	ds_read_b128 v[130:133], v161 offset:24576
	v_mfma_f32_16x16x32_bf16 v[66:69], v[216:219], v[248:251], v[66:69]
	v_mfma_f32_16x16x32_bf16 v[62:65], v[220:223], v[236:239], v[62:65]
	ds_read_b128 v[134:137], v161 offset:25600
	v_mfma_f32_16x16x32_bf16 v[58:61], v[220:223], v[240:243], v[58:61]
	v_mfma_f32_16x16x32_bf16 v[54:57], v[220:223], v[244:247], v[54:57]
	ds_read_b128 v[138:141], v161 offset:26624
	v_mfma_f32_16x16x32_bf16 v[50:53], v[220:223], v[248:251], v[50:53]
	v_mfma_f32_16x16x32_bf16 v[46:49], v[224:227], v[236:239], v[46:49]
	ds_read_b128 v[142:145], v161 offset:27648
	v_mfma_f32_16x16x32_bf16 v[42:45], v[224:227], v[240:243], v[42:45]
	v_mfma_f32_16x16x32_bf16 v[38:41], v[224:227], v[244:247], v[38:41]
	ds_read_b128 v[146:149], v161 offset:28672
	v_mfma_f32_16x16x32_bf16 v[34:37], v[224:227], v[248:251], v[34:37]
	v_mfma_f32_16x16x32_bf16 v[30:33], v[228:231], v[236:239], v[30:33]
	ds_read_b128 v[150:153], v161 offset:29696
	v_mfma_f32_16x16x32_bf16 v[26:29], v[228:231], v[240:243], v[26:29]
	v_mfma_f32_16x16x32_bf16 v[22:25], v[228:231], v[244:247], v[22:25]
	ds_read_b128 v[162:165], v161 offset:30720
	v_mfma_f32_16x16x32_bf16 v[18:21], v[228:231], v[248:251], v[18:21]
	v_mfma_f32_16x16x32_bf16 v[14:17], v[232:235], v[236:239], v[14:17]
	ds_read_b128 v[166:169], v161 offset:31744
	v_mfma_f32_16x16x32_bf16 v[10:13], v[232:235], v[240:243], v[10:13]
	v_mfma_f32_16x16x32_bf16 v[6:9], v[232:235], v[244:247], v[6:9]
	v_mfma_f32_16x16x32_bf16 v[2:5], v[232:235], v[248:251], v[2:5]
	s_setprio 0
	s_min_u32 s11, s11, 12
	s_lshl_b32 s11, s11, 6
	s_addk_i32 s11, 0xc0
	s_waitcnt vmcnt(0) lgkmcnt(0)
	s_barrier
; DI void cfence() { asm volatile("" ::: "memory"); }
; #define LSTORE2(RA, RB, P)                                       \
;   {                                                              \
;     char* dA_ = smem + (P) * 24576 + wofs;                       \
;     _Pragma("unroll") for (int j = 0; j < 4; ++j) *(u32x4*)(dA_ + j * 4096) = RA[j]; \
;     _Pragma("unroll") for (int j = 0; j < 2; ++j) *(u32x4*)(dA_ + 16384 + j * 4096) = RB[j]; \
;   }
; DI void gemm256_kloop(f32x4 (&acc)[8][4], const bf16_t* __restrict__ A, int lda, const bf16_t* __restrict__ Bt, int ldb,
;                       int K, int b, int s0, int col0, char* smem) {
;     ...
;   for (int kt = 0; kt < nk; kt += 2) {
;     GLOAD2(xa, xb, kt + 2);
;     cfence();
;     COMPUTE2(0);
;     LSTORE2(ya, yb, 1);
;     __syncthreads();
;     if (kt + 1 < nk) {
;       GLOAD2(ya, yb, kt + 3);
;       cfence();
;       COMPUTE2(1);
;       LSTORE2(xa, xb, 0);
;       __syncthreads();
;     }
;   }
	s_setprio 1
	s_add_u32 m0, s98, 0x6000
	v_mfma_f32_16x16x32_bf16 v[126:129], v[130:133], v[170:173], v[126:129]
	buffer_load_dwordx4 v0, s[12:15], s11 offen lds
	s_add_u32 m0, m0, 0x1000
	v_mfma_f32_16x16x32_bf16 v[122:125], v[130:133], v[174:177], v[122:125]
	buffer_load_dwordx4 v154, s[12:15], s11 offen lds
	s_add_u32 m0, m0, 0x1000
	v_mfma_f32_16x16x32_bf16 v[118:121], v[130:133], v[178:181], v[118:121]
	buffer_load_dwordx4 v155, s[12:15], s11 offen lds
	s_add_u32 m0, m0, 0x1000
	v_mfma_f32_16x16x32_bf16 v[114:117], v[130:133], v[182:185], v[114:117]
	buffer_load_dwordx4 v156, s[12:15], s11 offen lds
	s_add_u32 m0, m0, 0x1000
	v_mfma_f32_16x16x32_bf16 v[110:113], v[134:137], v[170:173], v[110:113]
	buffer_load_dwordx4 v157, s[16:19], s11 offen lds
	s_add_u32 m0, m0, 0x1000
	v_mfma_f32_16x16x32_bf16 v[106:109], v[134:137], v[174:177], v[106:109]
	buffer_load_dwordx4 v158, s[16:19], s11 offen lds
	v_mfma_f32_16x16x32_bf16 v[102:105], v[134:137], v[178:181], v[102:105]
	ds_read_b128 v[236:239], v160 offset:16384
	v_mfma_f32_16x16x32_bf16 v[98:101], v[134:137], v[182:185], v[98:101]
	v_mfma_f32_16x16x32_bf16 v[94:97], v[138:141], v[170:173], v[94:97]
	ds_read_b128 v[240:243], v160 offset:17408
	v_mfma_f32_16x16x32_bf16 v[90:93], v[138:141], v[174:177], v[90:93]
	v_mfma_f32_16x16x32_bf16 v[86:89], v[138:141], v[178:181], v[86:89]
	ds_read_b128 v[244:247], v160 offset:18432
	v_mfma_f32_16x16x32_bf16 v[82:85], v[138:141], v[182:185], v[82:85]
	v_mfma_f32_16x16x32_bf16 v[78:81], v[142:145], v[170:173], v[78:81]
	ds_read_b128 v[248:251], v160 offset:19456
	v_mfma_f32_16x16x32_bf16 v[74:77], v[142:145], v[174:177], v[74:77]
	v_mfma_f32_16x16x32_bf16 v[70:73], v[142:145], v[178:181], v[70:73]
	ds_read_b128 v[186:189], v161
	v_mfma_f32_16x16x32_bf16 v[66:69], v[142:145], v[182:185], v[66:69]
	v_mfma_f32_16x16x32_bf16 v[62:65], v[146:149], v[170:173], v[62:65]
	ds_read_b128 v[190:193], v161 offset:1024
	v_mfma_f32_16x16x32_bf16 v[58:61], v[146:149], v[174:177], v[58:61]
	v_mfma_f32_16x16x32_bf16 v[54:57], v[146:149], v[178:181], v[54:57]
	ds_read_b128 v[212:215], v161 offset:2048
	v_mfma_f32_16x16x32_bf16 v[50:53], v[146:149], v[182:185], v[50:53]
	v_mfma_f32_16x16x32_bf16 v[46:49], v[150:153], v[170:173], v[46:49]
	ds_read_b128 v[216:219], v161 offset:3072
	v_mfma_f32_16x16x32_bf16 v[42:45], v[150:153], v[174:177], v[42:45]
	v_mfma_f32_16x16x32_bf16 v[38:41], v[150:153], v[178:181], v[38:41]
	ds_read_b128 v[220:223], v161 offset:4096
	v_mfma_f32_16x16x32_bf16 v[34:37], v[150:153], v[182:185], v[34:37]
	v_mfma_f32_16x16x32_bf16 v[30:33], v[162:165], v[170:173], v[30:33]
	ds_read_b128 v[224:227], v161 offset:5120
	v_mfma_f32_16x16x32_bf16 v[26:29], v[162:165], v[174:177], v[26:29]
	v_mfma_f32_16x16x32_bf16 v[22:25], v[162:165], v[178:181], v[22:25]
	ds_read_b128 v[228:231], v161 offset:6144
	v_mfma_f32_16x16x32_bf16 v[18:21], v[162:165], v[182:185], v[18:21]
	v_mfma_f32_16x16x32_bf16 v[14:17], v[166:169], v[170:173], v[14:17]
	ds_read_b128 v[232:235], v161 offset:7168
	v_mfma_f32_16x16x32_bf16 v[10:13], v[166:169], v[174:177], v[10:13]
	v_mfma_f32_16x16x32_bf16 v[6:9], v[166:169], v[178:181], v[6:9]
	v_mfma_f32_16x16x32_bf16 v[2:5], v[166:169], v[182:185], v[2:5]
	s_setprio 0
	s_addk_i32 s10, 0x80
	s_mov_b32 s11, s26
	s_waitcnt vmcnt(0) lgkmcnt(0)
	s_barrier
	s_cbranch_vccnz .LBB0_425
	s_bitcmp1_b32 s34, 0
	s_cselect_b64 s[14:15], -1, 0
	s_and_b64 s[10:11], s[2:3], exec
	s_cselect_b32 s10, 0x400, 0
	s_lshr_b32 s5, s5, 1
	s_and_b32 s5, s5, 0x380
	s_or_b32 s10, s10, s5
	s_and_b64 s[2:3], s[2:3], exec
	s_cselect_b32 s11, 0x4100, 0
	s_bfe_u32 s2, s4, 0x30008
	s_mulk_i32 s2, 0x180
	s_add_u32 s18, s48, s2
	s_mov_b32 s50, 0
	s_addc_u32 s19, s49, 0
	s_mov_b64 s[26:27], -1
	s_branch .LBB0_429

; DI int tidx() { int t = __builtin_amdgcn_workitem_id_x(); asm volatile("" : "+v"(t)); return t; }
; DI int bidx() { int t = __builtin_amdgcn_workgroup_id_x(); asm volatile("" : "+s"(t)); return t; }
; DI int gdim() { int t = (int)__ockl_get_num_groups(0); asm volatile("" : "+s"(t)); return t; }
; DI brsrc_t make_rsrc(const void* p) { return __builtin_amdgcn_make_buffer_rsrc((void*)p, 0, 0x7fffffff, 0x00020000); }
; DI void cfence() { asm volatile("" ::: "memory"); }
; DI int swz4(int row) { const int g = (row >> 2) & 3; return ((g << 1) ^ ((g >> 1) * 3)) & 3; }
; DI void gemm256_kloop(f32x4 (&acc)[8][4], const bf16_t* __restrict__ A, int lda, const bf16_t* __restrict__ Bt, int ldb,
;                       int K, int b, int s0, int col0, char* smem) {
;   const int tid = tidx(), lane = tid & 63, wid = tid >> 6;
;   const int wr = wid >> 1, wc = wid & 1, fr = lane & 15, fq = lane >> 4;
;   const int lrow = tid >> 2, lkc = tid & 3;
;   const brsrc_t rA = make_rsrc(A), rB = make_rsrc(Bt);
;   unsigned aoff[4];
; #pragma unroll
;   for (int j = 0; j < 4; ++j) {
;     int s = s0 + lrow + 64 * j;
;     s = s < 0 ? 0 : (s > SB - 1 ? SB - 1 : s);
;     aoff[j] = ((unsigned)(b * SB + s) * (unsigned)lda + lkc * 8) * 2u;
;   }
;   const unsigned boff = ((unsigned)(col0 + lrow) * (unsigned)ldb + lkc * 8) * 2u;
;   const unsigned bstep = 64u * (unsigned)ldb * 2u;
;   const int wofs = lrow * 64 + ((lkc ^ swz4(lrow)) << 4);
;   const int nk = K >> 5;
;   u32x4 xa[4], xb[2], ya[4], yb[2];
;     ...
;   GLOAD2(xa, xb, 0);
;   GLOAD2(ya, yb, 1);
;   cfence();
;   LSTORE2(xa, xb, 0);
;   __syncthreads();
;   const int co = ((fq ^ swz4(fr)) << 4);
;   const int aofs = (wr * 128 + fr) * 64 + co, bofs = (wc * 64 + fr) * 64 + co;
; DI void phase_uproj(const Params& P, int l, char* smem) {
;     ...
;   for (int it = bidx(); it < nq + nkv; it += gdim()) {
;     if (it < nq) {
;       EpiUQ e{(bf16_t*)(Bg + B_QMLA), ssq, cs, sn};
;       gemm256_item_plain(Z, 1088, (const bf16_t*)(W + W_UQ), LDUQ, 512, 12, smem, e, it);
.LBB0_438:
	s_and_b64 vcc, exec, s[2:3]
	s_cbranch_vccz .LBB0_422
	s_mul_hi_i32 s2, s34, 0x2aaaaaab
	s_lshr_b32 s3, s2, 31
	s_ashr_i32 s10, s2, 1
	s_mul_hi_i32 s2, s34, 0xa80a80a9
	s_add_i32 s2, s2, s34
	s_lshr_b32 s4, s2, 31
	s_ashr_i32 s5, s2, 9
	s_add_i32 s5, s5, s4
	s_add_i32 s10, s10, s3
	s_mul_i32 s2, s5, 0xffffffbf
	s_waitcnt vmcnt(0)
	v_mov_b32_e32 v7, v194
	s_add_i32 s2, s2, s10
	s_movk_i32 s8, 0x880
	v_ashrrev_i32_e32 v32, 2, v7
	v_lshl_add_u32 v2, s2, 8, v32
	v_max_i32_e32 v4, 0xffffffc0, v2
	v_add_u32_e32 v4, 64, v4
	s_mul_i32 s2, s5, 0x4100
	v_min_u32_e32 v4, 0x40ff, v4
	v_and_b32_e32 v33, 3, v7
	v_add_u32_e32 v4, s2, v4
	v_lshlrev_b32_e32 v3, 4, v33
	v_mul_lo_u32 v4, v4, s8
	v_med3_i32 v0, v2, 0, v201
	v_or_b32_e32 v154, v4, v3
	v_max_i32_e32 v4, 0xffffff80, v2
	v_max_i32_e32 v2, 0xffffff40, v2
	v_add_u32_e32 v2, 0xc0, v2
	s_mul_i32 s3, s10, -12
	v_add_u32_e32 v4, 0x80, v4
	v_min_u32_e32 v2, 0x40ff, v2
	s_add_i32 s3, s3, s34
	v_min_u32_e32 v4, 0x40ff, v4
	v_add_u32_e32 v2, s2, v2
	s_lshl_b32 s4, s3, 7
	v_add_u32_e32 v0, s2, v0
	v_add_u32_e32 v4, s2, v4
	v_mul_lo_u32 v2, v2, s8
	v_mul_lo_u32 v0, v0, s8
	v_mul_lo_u32 v4, v4, s8
	v_or_b32_e32 v156, v2, v3
	v_add_u32_e32 v2, s4, v32
	s_movk_i32 s8, 0x480
	v_mul_lo_u32 v2, v2, s8
	v_or_b32_e32 v157, v2, v3
	s_mov_b32 s26, s22
	s_mov_b32 s27, s23
	v_add_u32_e32 v158, 0x12000, v157
	v_or_b32_e32 v0, v0, v3
	v_or_b32_e32 v155, v4, v3
	v_bfe_u32 v162, v194, 4, 2
	v_lshlrev_b32_e32 v162, 2, v162
	v_mov_b32_e32 v163, 0x1320
	v_lshrrev_b32_e32 v162, v162, v163
	v_and_b32_e32 v162, 3, v162
	v_lshlrev_b32_e32 v162, 4, v162
	v_xor_b32_e32 v0, v0, v162
	v_xor_b32_e32 v154, v154, v162
	v_xor_b32_e32 v155, v155, v162
	v_xor_b32_e32 v156, v156, v162
	v_xor_b32_e32 v157, v157, v162
	v_xor_b32_e32 v158, v158, v162
	v_lshrrev_b32_e32 v163, 6, v194
	s_nop 0
	v_readfirstlane_b32 s98, v163
	s_lshl_b32 s98, s98, 10
	s_mov_b32 m0, s98
	s_nop 0
	buffer_load_dwordx4 v0, s[20:23], 0 offen lds
	s_add_u32 m0, m0, 0x1000
	s_nop 0
	buffer_load_dwordx4 v154, s[20:23], 0 offen lds
	s_add_u32 m0, m0, 0x1000
	s_nop 0
	buffer_load_dwordx4 v155, s[20:23], 0 offen lds
	s_add_u32 m0, m0, 0x1000
	s_nop 0
	buffer_load_dwordx4 v156, s[20:23], 0 offen lds
	s_add_u32 m0, m0, 0x1000
	s_nop 0
	buffer_load_dwordx4 v157, s[24:27], 0 offen lds
	s_add_u32 m0, m0, 0x1000
	s_nop 0
	buffer_load_dwordx4 v158, s[24:27], 0 offen lds
	s_add_u32 m0, s98, 0x6000
	s_nop 0
	buffer_load_dwordx4 v0, s[20:23], 64 offen lds
	s_add_u32 m0, m0, 0x1000
	s_nop 0
	buffer_load_dwordx4 v154, s[20:23], 64 offen lds
	s_add_u32 m0, m0, 0x1000
	s_nop 0
	buffer_load_dwordx4 v155, s[20:23], 64 offen lds
	s_add_u32 m0, m0, 0x1000
	s_nop 0
	buffer_load_dwordx4 v156, s[20:23], 64 offen lds
	s_add_u32 m0, m0, 0x1000
	s_nop 0
	buffer_load_dwordx4 v157, s[24:27], 64 offen lds
	s_add_u32 m0, m0, 0x1000
	s_nop 0
	buffer_load_dwordx4 v158, s[24:27], 64 offen lds
	v_lshrrev_b32_e32 v36, 1, v7
	v_bfe_i32 v35, v7, 3, 1
	v_lshlrev_b32_e32 v38, 6, v32
	v_lshrrev_b32_e32 v32, 1, v32
	v_and_b32_e32 v36, 2, v36
	v_bfe_i32 v34, v7, 5, 1
	v_and_b32_e32 v32, 2, v32
	v_bitop3_b32 v35, v35, v36, 3 bitop3:0x6c
	v_bitop3_b32 v32, v34, v32, 3 bitop3:0x6c
	v_lshlrev_b32_e32 v34, 4, v35
	v_lshlrev_b32_e32 v37, 6, v7
	v_xor_b32_e32 v32, v32, v33
	v_bitop3_b32 v7, v34, v7, 48 bitop3:0x78
	s_movk_i32 s11, 0x13c0
	v_mov_b32_e32 v2, 0
	v_lshl_or_b32 v159, v32, 4, v38
	v_and_or_b32 v160, v37, s11, v7
	s_movk_i32 s11, 0xe3c0
	s_mov_b32 s9, 0
	s_movk_i32 s8, 0x80
	v_mov_b32_e32 v3, v2
	v_mov_b32_e32 v4, v2
	v_mov_b32_e32 v5, v2
	v_mov_b32_e32 v6, v2
	v_and_or_b32 v161, v37, s11, v7
	v_mov_b32_e32 v7, v2
	v_mov_b32_e32 v32, v2
	v_mov_b32_e32 v33, v2
	v_mov_b32_e32 v34, v2
	v_mov_b32_e32 v35, v2
	v_mov_b32_e32 v36, v2
	v_mov_b32_e32 v37, v2
	v_mov_b32_e32 v38, v2
	v_mov_b32_e32 v39, v2
	v_mov_b32_e32 v40, v2
	v_mov_b32_e32 v41, v2
	v_mov_b32_e32 v42, v2
	v_mov_b32_e32 v43, v2
	v_mov_b32_e32 v44, v2
	v_mov_b32_e32 v45, v2
	v_mov_b32_e32 v46, v2
	v_mov_b32_e32 v47, v2
	v_mov_b32_e32 v48, v2
	v_mov_b32_e32 v49, v2
	v_mov_b32_e32 v50, v2
	v_mov_b32_e32 v51, v2
	v_mov_b32_e32 v52, v2
	v_mov_b32_e32 v8, v2
	v_mov_b32_e32 v9, v2
	v_mov_b32_e32 v10, v2
	v_mov_b32_e32 v11, v2
	v_mov_b32_e32 v12, v2
	v_mov_b32_e32 v13, v2
	v_mov_b32_e32 v14, v2
	v_mov_b32_e32 v15, v2
	v_mov_b32_e32 v16, v2
	v_mov_b32_e32 v17, v2
	v_mov_b32_e32 v18, v2
	v_mov_b32_e32 v19, v2
	v_mov_b32_e32 v20, v2
	v_mov_b32_e32 v21, v2
	v_mov_b32_e32 v22, v2
	v_mov_b32_e32 v23, v2
	v_mov_b32_e32 v24, v2
	v_mov_b32_e32 v25, v2
	v_mov_b32_e32 v26, v2
	v_mov_b32_e32 v27, v2
	v_mov_b32_e32 v28, v2
	v_mov_b32_e32 v29, v2
	v_mov_b32_e32 v30, v2
	v_mov_b32_e32 v31, v2
	v_mov_b32_e32 v53, v2
	v_mov_b32_e32 v54, v2
	v_mov_b32_e32 v55, v2
	v_mov_b32_e32 v56, v2
	v_mov_b32_e32 v57, v2
	v_mov_b32_e32 v58, v2
	v_mov_b32_e32 v59, v2
	v_mov_b32_e32 v60, v2
	v_mov_b32_e32 v61, v2
	v_mov_b32_e32 v62, v2
	v_mov_b32_e32 v63, v2
	v_mov_b32_e32 v64, v2
	v_mov_b32_e32 v65, v2
	v_mov_b32_e32 v66, v2
	v_mov_b32_e32 v67, v2
	v_mov_b32_e32 v68, v2
	v_mov_b32_e32 v69, v2
	v_mov_b32_e32 v70, v2
	v_mov_b32_e32 v71, v2
	v_mov_b32_e32 v72, v2
	v_mov_b32_e32 v73, v2
	v_mov_b32_e32 v74, v2
	v_mov_b32_e32 v75, v2
	v_mov_b32_e32 v76, v2
	v_mov_b32_e32 v77, v2
	v_mov_b32_e32 v78, v2
	v_mov_b32_e32 v79, v2
	v_mov_b32_e32 v80, v2
	v_mov_b32_e32 v81, v2
	v_mov_b32_e32 v82, v2
	v_mov_b32_e32 v83, v2
	v_mov_b32_e32 v84, v2
	v_mov_b32_e32 v85, v2
	v_mov_b32_e32 v86, v2
	v_mov_b32_e32 v87, v2
	v_mov_b32_e32 v88, v2
	v_mov_b32_e32 v89, v2
	v_mov_b32_e32 v90, v2
	v_mov_b32_e32 v91, v2
	v_mov_b32_e32 v92, v2
	v_mov_b32_e32 v93, v2
	v_mov_b32_e32 v94, v2
	v_mov_b32_e32 v95, v2
	v_mov_b32_e32 v96, v2
	v_mov_b32_e32 v97, v2
	v_mov_b32_e32 v98, v2
	v_mov_b32_e32 v99, v2
	v_mov_b32_e32 v100, v2
	v_mov_b32_e32 v101, v2
	v_mov_b32_e32 v102, v2
	v_mov_b32_e32 v103, v2
	v_mov_b32_e32 v104, v2
	v_mov_b32_e32 v105, v2
	v_mov_b32_e32 v106, v2
	v_mov_b32_e32 v107, v2
	v_mov_b32_e32 v108, v2
	v_mov_b32_e32 v109, v2
	v_mov_b32_e32 v110, v2
	v_mov_b32_e32 v111, v2
	v_mov_b32_e32 v112, v2
	v_mov_b32_e32 v113, v2
	v_mov_b32_e32 v114, v2
	v_mov_b32_e32 v115, v2
	v_mov_b32_e32 v116, v2
	v_mov_b32_e32 v117, v2
	v_mov_b32_e32 v118, v2
	v_mov_b32_e32 v119, v2
	v_mov_b32_e32 v120, v2
	v_mov_b32_e32 v121, v2
	v_mov_b32_e32 v122, v2
	v_mov_b32_e32 v123, v2
	v_mov_b32_e32 v124, v2
	v_mov_b32_e32 v125, v2
	v_mov_b32_e32 v126, v2
	v_mov_b32_e32 v127, v2
	v_mov_b32_e32 v128, v2
	v_mov_b32_e32 v129, v2
	s_waitcnt vmcnt(6) lgkmcnt(0)
	s_barrier
	ds_read_b128 v[236:239], v160 offset:16384
	ds_read_b128 v[240:243], v160 offset:17408
	ds_read_b128 v[244:247], v160 offset:18432
	ds_read_b128 v[248:251], v160 offset:19456
	ds_read_b128 v[186:189], v161
	ds_read_b128 v[190:193], v161 offset:1024
	ds_read_b128 v[212:215], v161 offset:2048
	ds_read_b128 v[216:219], v161 offset:3072
	ds_read_b128 v[220:223], v161 offset:4096
	ds_read_b128 v[224:227], v161 offset:5120
	ds_read_b128 v[228:231], v161 offset:6144
	ds_read_b128 v[232:235], v161 offset:7168
	s_waitcnt vmcnt(0) lgkmcnt(0)
	s_barrier
; DI void cfence() { asm volatile("" ::: "memory"); }
; DI int swz4(int row) { const int g = (row >> 2) & 3; return ((g << 1) ^ ((g >> 1) * 3)) & 3; }
; #define LSTORE2(RA, RB, P)                                       \
;   {                                                              \
;     char* dA_ = smem + (P) * 24576 + wofs;                       \
;     _Pragma("unroll") for (int j = 0; j < 4; ++j) *(u32x4*)(dA_ + j * 4096) = RA[j]; \
;     _Pragma("unroll") for (int j = 0; j < 2; ++j) *(u32x4*)(dA_ + 16384 + j * 4096) = RB[j]; \
;   }
; DI void gemm256_kloop(f32x4 (&acc)[8][4], const bf16_t* __restrict__ A, int lda, const bf16_t* __restrict__ Bt, int ldb,
;                       int K, int b, int s0, int col0, char* smem) {
;     ...
;   GLOAD2(xa, xb, 0);
;   GLOAD2(ya, yb, 1);
;   cfence();
;   LSTORE2(xa, xb, 0);
;   __syncthreads();
;   const int co = ((fq ^ swz4(fr)) << 4);
;   const int aofs = (wr * 128 + fr) * 64 + co, bofs = (wc * 64 + fr) * 64 + co;
;   for (int kt = 0; kt < nk; kt += 2) {
;     GLOAD2(xa, xb, kt + 2);
;     cfence();
;     COMPUTE2(0);
;     LSTORE2(ya, yb, 1);
;     __syncthreads();
.LBB0_440:
	s_add_i32 s11, s9, 2
	s_cmp_lt_u32 s9, 14
	s_cselect_b64 s[14:15], -1, 0
	s_and_b64 vcc, s[14:15], exec
	s_cselect_b32 s14, s8, 0x3c0
	s_setprio 1
	s_mov_b32 m0, s98
	v_mfma_f32_16x16x32_bf16 v[126:129], v[186:189], v[236:239], v[126:129]
	buffer_load_dwordx4 v0, s[20:23], s14 offen lds
	s_add_u32 m0, m0, 0x1000
	v_mfma_f32_16x16x32_bf16 v[122:125], v[186:189], v[240:243], v[122:125]
	buffer_load_dwordx4 v154, s[20:23], s14 offen lds
	s_add_u32 m0, m0, 0x1000
	v_mfma_f32_16x16x32_bf16 v[118:121], v[186:189], v[244:247], v[118:121]
	buffer_load_dwordx4 v155, s[20:23], s14 offen lds
	s_add_u32 m0, m0, 0x1000
	v_mfma_f32_16x16x32_bf16 v[114:117], v[186:189], v[248:251], v[114:117]
	buffer_load_dwordx4 v156, s[20:23], s14 offen lds
	s_add_u32 m0, m0, 0x1000
	v_mfma_f32_16x16x32_bf16 v[110:113], v[190:193], v[236:239], v[110:113]
	buffer_load_dwordx4 v157, s[24:27], s14 offen lds
	s_add_u32 m0, m0, 0x1000
	v_mfma_f32_16x16x32_bf16 v[106:109], v[190:193], v[240:243], v[106:109]
	buffer_load_dwordx4 v158, s[24:27], s14 offen lds
	v_mfma_f32_16x16x32_bf16 v[102:105], v[190:193], v[244:247], v[102:105]
	ds_read_b128 v[170:173], v160 offset:40960
	v_mfma_f32_16x16x32_bf16 v[98:101], v[190:193], v[248:251], v[98:101]
	v_mfma_f32_16x16x32_bf16 v[94:97], v[212:215], v[236:239], v[94:97]
	ds_read_b128 v[174:177], v160 offset:41984
	v_mfma_f32_16x16x32_bf16 v[90:93], v[212:215], v[240:243], v[90:93]
	v_mfma_f32_16x16x32_bf16 v[86:89], v[212:215], v[244:247], v[86:89]
	ds_read_b128 v[178:181], v160 offset:43008
	v_mfma_f32_16x16x32_bf16 v[82:85], v[212:215], v[248:251], v[82:85]
	v_mfma_f32_16x16x32_bf16 v[78:81], v[216:219], v[236:239], v[78:81]
	ds_read_b128 v[182:185], v160 offset:44032
	v_mfma_f32_16x16x32_bf16 v[74:77], v[216:219], v[240:243], v[74:77]
	v_mfma_f32_16x16x32_bf16 v[70:73], v[216:219], v[244:247], v[70:73]
	ds_read_b128 v[130:133], v161 offset:24576
	v_mfma_f32_16x16x32_bf16 v[66:69], v[216:219], v[248:251], v[66:69]
	v_mfma_f32_16x16x32_bf16 v[62:65], v[220:223], v[236:239], v[62:65]
	ds_read_b128 v[134:137], v161 offset:25600
	v_mfma_f32_16x16x32_bf16 v[58:61], v[220:223], v[240:243], v[58:61]
	v_mfma_f32_16x16x32_bf16 v[54:57], v[220:223], v[244:247], v[54:57]
	ds_read_b128 v[138:141], v161 offset:26624
	v_mfma_f32_16x16x32_bf16 v[50:53], v[220:223], v[248:251], v[50:53]
	v_mfma_f32_16x16x32_bf16 v[46:49], v[224:227], v[236:239], v[46:49]
	ds_read_b128 v[142:145], v161 offset:27648
	v_mfma_f32_16x16x32_bf16 v[42:45], v[224:227], v[240:243], v[42:45]
	v_mfma_f32_16x16x32_bf16 v[38:41], v[224:227], v[244:247], v[38:41]
	ds_read_b128 v[146:149], v161 offset:28672
	v_mfma_f32_16x16x32_bf16 v[34:37], v[224:227], v[248:251], v[34:37]
	v_mfma_f32_16x16x32_bf16 v[30:33], v[228:231], v[236:239], v[30:33]
	ds_read_b128 v[150:153], v161 offset:29696
	v_mfma_f32_16x16x32_bf16 v[26:29], v[228:231], v[240:243], v[26:29]
	v_mfma_f32_16x16x32_bf16 v[22:25], v[228:231], v[244:247], v[22:25]
	ds_read_b128 v[162:165], v161 offset:30720
	v_mfma_f32_16x16x32_bf16 v[18:21], v[228:231], v[248:251], v[18:21]
	v_mfma_f32_16x16x32_bf16 v[14:17], v[232:235], v[236:239], v[14:17]
	ds_read_b128 v[166:169], v161 offset:31744
	v_mfma_f32_16x16x32_bf16 v[10:13], v[232:235], v[240:243], v[10:13]
	v_mfma_f32_16x16x32_bf16 v[6:9], v[232:235], v[244:247], v[6:9]
	v_mfma_f32_16x16x32_bf16 v[2:5], v[232:235], v[248:251], v[2:5]
	s_setprio 0
	s_min_u32 s9, s9, 12
	s_lshl_b32 s9, s9, 6
	s_addk_i32 s9, 0xc0
	s_waitcnt vmcnt(0) lgkmcnt(0)
	s_barrier
; DI void cfence() { asm volatile("" ::: "memory"); }
; DI int swz4(int row) { const int g = (row >> 2) & 3; return ((g << 1) ^ ((g >> 1) * 3)) & 3; }
; #define LSTORE2(RA, RB, P)                                       \
;   {                                                              \
;     char* dA_ = smem + (P) * 24576 + wofs;                       \
;     _Pragma("unroll") for (int j = 0; j < 4; ++j) *(u32x4*)(dA_ + j * 4096) = RA[j]; \
;     _Pragma("unroll") for (int j = 0; j < 2; ++j) *(u32x4*)(dA_ + 16384 + j * 4096) = RB[j]; \
;   }
; DI void gemm256_kloop(f32x4 (&acc)[8][4], const bf16_t* __restrict__ A, int lda, const bf16_t* __restrict__ Bt, int ldb,
;                       int K, int b, int s0, int col0, char* smem) {
;     ...
;   GLOAD2(xa, xb, 0);
;   GLOAD2(ya, yb, 1);
;   cfence();
;   LSTORE2(xa, xb, 0);
;   __syncthreads();
;   const int co = ((fq ^ swz4(fr)) << 4);
;   const int aofs = (wr * 128 + fr) * 64 + co, bofs = (wc * 64 + fr) * 64 + co;
;   for (int kt = 0; kt < nk; kt += 2) {
;     GLOAD2(xa, xb, kt + 2);
;     cfence();
;     COMPUTE2(0);
;     LSTORE2(ya, yb, 1);
;     __syncthreads();
;     if (kt + 1 < nk) {
;       GLOAD2(ya, yb, kt + 3);
;       cfence();
;       COMPUTE2(1);
;       LSTORE2(xa, xb, 0);
;       __syncthreads();
;     }
	s_setprio 1
	s_add_u32 m0, s98, 0x6000
	v_mfma_f32_16x16x32_bf16 v[126:129], v[130:133], v[170:173], v[126:129]
	buffer_load_dwordx4 v0, s[20:23], s9 offen lds
	s_add_u32 m0, m0, 0x1000
	v_mfma_f32_16x16x32_bf16 v[122:125], v[130:133], v[174:177], v[122:125]
	buffer_load_dwordx4 v154, s[20:23], s9 offen lds
	s_add_u32 m0, m0, 0x1000
	v_mfma_f32_16x16x32_bf16 v[118:121], v[130:133], v[178:181], v[118:121]
	buffer_load_dwordx4 v155, s[20:23], s9 offen lds
	s_add_u32 m0, m0, 0x1000
	v_mfma_f32_16x16x32_bf16 v[114:117], v[130:133], v[182:185], v[114:117]
	buffer_load_dwordx4 v156, s[20:23], s9 offen lds
	s_add_u32 m0, m0, 0x1000
	v_mfma_f32_16x16x32_bf16 v[110:113], v[134:137], v[170:173], v[110:113]
	buffer_load_dwordx4 v157, s[24:27], s9 offen lds
	s_add_u32 m0, m0, 0x1000
	v_mfma_f32_16x16x32_bf16 v[106:109], v[134:137], v[174:177], v[106:109]
	buffer_load_dwordx4 v158, s[24:27], s9 offen lds
	v_mfma_f32_16x16x32_bf16 v[102:105], v[134:137], v[178:181], v[102:105]
	ds_read_b128 v[236:239], v160 offset:16384
	v_mfma_f32_16x16x32_bf16 v[98:101], v[134:137], v[182:185], v[98:101]
	v_mfma_f32_16x16x32_bf16 v[94:97], v[138:141], v[170:173], v[94:97]
	ds_read_b128 v[240:243], v160 offset:17408
	v_mfma_f32_16x16x32_bf16 v[90:93], v[138:141], v[174:177], v[90:93]
	v_mfma_f32_16x16x32_bf16 v[86:89], v[138:141], v[178:181], v[86:89]
	ds_read_b128 v[244:247], v160 offset:18432
	v_mfma_f32_16x16x32_bf16 v[82:85], v[138:141], v[182:185], v[82:85]
	v_mfma_f32_16x16x32_bf16 v[78:81], v[142:145], v[170:173], v[78:81]
	ds_read_b128 v[248:251], v160 offset:19456
	v_mfma_f32_16x16x32_bf16 v[74:77], v[142:145], v[174:177], v[74:77]
	v_mfma_f32_16x16x32_bf16 v[70:73], v[142:145], v[178:181], v[70:73]
	ds_read_b128 v[186:189], v161
	v_mfma_f32_16x16x32_bf16 v[66:69], v[142:145], v[182:185], v[66:69]
	v_mfma_f32_16x16x32_bf16 v[62:65], v[146:149], v[170:173], v[62:65]
	ds_read_b128 v[190:193], v161 offset:1024
	v_mfma_f32_16x16x32_bf16 v[58:61], v[146:149], v[174:177], v[58:61]
	v_mfma_f32_16x16x32_bf16 v[54:57], v[146:149], v[178:181], v[54:57]
	ds_read_b128 v[212:215], v161 offset:2048
	v_mfma_f32_16x16x32_bf16 v[50:53], v[146:149], v[182:185], v[50:53]
	v_mfma_f32_16x16x32_bf16 v[46:49], v[150:153], v[170:173], v[46:49]
	ds_read_b128 v[216:219], v161 offset:3072
	v_mfma_f32_16x16x32_bf16 v[42:45], v[150:153], v[174:177], v[42:45]
	v_mfma_f32_16x16x32_bf16 v[38:41], v[150:153], v[178:181], v[38:41]
	ds_read_b128 v[220:223], v161 offset:4096
	v_mfma_f32_16x16x32_bf16 v[34:37], v[150:153], v[182:185], v[34:37]
	v_mfma_f32_16x16x32_bf16 v[30:33], v[162:165], v[170:173], v[30:33]
	ds_read_b128 v[224:227], v161 offset:5120
	v_mfma_f32_16x16x32_bf16 v[26:29], v[162:165], v[174:177], v[26:29]
	v_mfma_f32_16x16x32_bf16 v[22:25], v[162:165], v[178:181], v[22:25]
	ds_read_b128 v[228:231], v161 offset:6144
	v_mfma_f32_16x16x32_bf16 v[18:21], v[162:165], v[182:185], v[18:21]
	v_mfma_f32_16x16x32_bf16 v[14:17], v[166:169], v[170:173], v[14:17]
	ds_read_b128 v[232:235], v161 offset:7168
	v_mfma_f32_16x16x32_bf16 v[10:13], v[166:169], v[174:177], v[10:13]
	v_mfma_f32_16x16x32_bf16 v[6:9], v[166:169], v[178:181], v[6:9]
	v_mfma_f32_16x16x32_bf16 v[2:5], v[166:169], v[182:185], v[2:5]
	s_setprio 0
	s_addk_i32 s8, 0x80
	s_mov_b32 s9, s11
	s_waitcnt vmcnt(0) lgkmcnt(0)
	s_barrier
	s_cbranch_vccnz .LBB0_440
	s_lshl_b32 s26, s3, 1
	s_mul_hi_i32 s3, s5, 0x4100
	s_ashr_i32 s5, s4, 31
	s_lshl_b64 s[4:5], s[4:5], 1
	s_add_u32 s8, s38, s4
	s_addc_u32 s9, s39, s5
	s_lshl_b32 s4, s10, 8
	s_sub_i32 s27, s4, s2
	s_mov_b32 s18, 0
	s_mov_b64 s[10:11], -1
	s_branch .LBB0_443

; DI int tidx() { int t = __builtin_amdgcn_workitem_id_x(); asm volatile("" : "+v"(t)); return t; }
; DI brsrc_t make_rsrc(const void* p) { return __builtin_amdgcn_make_buffer_rsrc((void*)p, 0, 0x7fffffff, 0x00020000); }
; DI void cfence() { asm volatile("" ::: "memory"); }
; DI int swz4(int row) { const int g = (row >> 2) & 3; return ((g << 1) ^ ((g >> 1) * 3)) & 3; }
; #define LSTORE2(RA, RB, P)                                       \
;   {                                                              \
;     char* dA_ = smem + (P) * 24576 + wofs;                       \
;     _Pragma("unroll") for (int j = 0; j < 4; ++j) *(u32x4*)(dA_ + j * 4096) = RA[j]; \
;     _Pragma("unroll") for (int j = 0; j < 2; ++j) *(u32x4*)(dA_ + 16384 + j * 4096) = RB[j]; \
;   }
; DI void gemm256_kloop(f32x4 (&acc)[8][4], const bf16_t* __restrict__ A, int lda, const bf16_t* __restrict__ Bt, int ldb,
;                       int K, int b, int s0, int col0, char* smem) {
;   const int tid = tidx(), lane = tid & 63, wid = tid >> 6;
;   const int wr = wid >> 1, wc = wid & 1, fr = lane & 15, fq = lane >> 4;
;   const int lrow = tid >> 2, lkc = tid & 3;
;   const brsrc_t rA = make_rsrc(A), rB = make_rsrc(Bt);
;   unsigned aoff[4];
; #pragma unroll
;   for (int j = 0; j < 4; ++j) {
;     int s = s0 + lrow + 64 * j;
;     s = s < 0 ? 0 : (s > SB - 1 ? SB - 1 : s);
;     aoff[j] = ((unsigned)(b * SB + s) * (unsigned)lda + lkc * 8) * 2u;
;   }
;   const unsigned boff = ((unsigned)(col0 + lrow) * (unsigned)ldb + lkc * 8) * 2u;
;   const unsigned bstep = 64u * (unsigned)ldb * 2u;
;   const int wofs = lrow * 64 + ((lkc ^ swz4(lrow)) << 4);
;   const int nk = K >> 5;
;   u32x4 xa[4], xb[2], ya[4], yb[2];
;     ...
;   GLOAD2(xa, xb, 0);
;   GLOAD2(ya, yb, 1);
;   cfence();
;   LSTORE2(xa, xb, 0);
;   __syncthreads();
;   const int co = ((fq ^ swz4(fr)) << 4);
;   const int aofs = (wr * 128 + fr) * 64 + co, bofs = (wc * 64 + fr) * 64 + co;
; template <class Epi>
; DI void gemm256_tile(const bf16_t* A, int lda, const bf16_t* Bt, int ldb, int K, int b, int s0, int col0, char* smem,
;                      const Epi& epi, int rstep) {
;   f32x4 acc[8][4];
; #pragma unroll
;   for (int m = 0; m < 8; ++m)
; #pragma unroll
;     for (int n = 0; n < 4; ++n) acc[m][n] = f32x4{0.f, 0.f, 0.f, 0.f};
.LBB0_460:
	s_cmpk_gt_i32 s51, 0x617
	s_mov_b64 s[4:5], -1
	s_cbranch_scc0 .LBB0_477
	s_add_i32 s6, s51, 0xfffff9e8
	s_and_b32 s4, s6, 0xffff
	s_mul_i32 s4, s4, 0xe38f
	s_lshr_b32 s4, s4, 19
	s_mul_i32 s5, s4, -9
	s_add_i32 s5, s5, s6
	s_cmpk_gt_u32 s6, 0x248
	s_cselect_b32 s6, 0xffffffbf, 0
	s_cselect_b32 s34, 0x4100, 0
	s_add_i32 s6, s6, s4
	v_mov_b32_e32 v38, v194
	s_lshl_b32 s69, s6, 8
	s_lshl_b32 s70, s5, 7
	v_ashrrev_i32_e32 v39, 2, v38
	s_waitcnt vmcnt(1)
	v_add_u32_e32 v2, s69, v39
	v_max_i32_e32 v4, 0xffffffc0, v2
	v_add_u32_e32 v4, 64, v4
	v_min_u32_e32 v4, 0x40ff, v4
	v_and_b32_e32 v40, 3, v38
	v_add_u32_e32 v4, s34, v4
	v_lshlrev_b32_e32 v3, 4, v40
	v_mul_u32_u24_e32 v4, 0x1080, v4
	v_med3_i32 v0, v2, 0, v201
	v_or_b32_e32 v154, v4, v3
	v_max_i32_e32 v4, 0xffffff80, v2
	v_max_i32_e32 v2, 0xffffff40, v2
	v_add_u32_e32 v2, 0xc0, v2
	v_min_u32_e32 v2, 0x40ff, v2
	v_add_u32_e32 v2, s34, v2
	v_mul_u32_u24_e32 v2, 0x1080, v2
	v_add_u32_e32 v4, 0x80, v4
	v_or_b32_e32 v156, v2, v3
	v_add_u32_e32 v2, s70, v39
	s_movk_i32 s6, 0x1080
	v_min_u32_e32 v4, 0x40ff, v4
	v_mul_lo_u32 v2, v2, s6
	v_add_u32_e32 v0, s34, v0
	v_add_u32_e32 v4, s34, v4
	v_or_b32_e32 v157, v2, v3
	v_mul_u32_u24_e32 v0, 0x1080, v0
	v_mul_u32_u24_e32 v4, 0x1080, v4
	s_mov_b32 s14, s22
	s_mov_b32 s15, s23
	v_add_u32_e32 v158, 0x42000, v157
	v_or_b32_e32 v0, v0, v3
	v_or_b32_e32 v155, v4, v3
	v_bfe_u32 v162, v194, 4, 2
	v_lshlrev_b32_e32 v162, 2, v162
	v_mov_b32_e32 v163, 0x1320
	v_lshrrev_b32_e32 v162, v162, v163
	v_and_b32_e32 v162, 3, v162
	v_lshlrev_b32_e32 v162, 4, v162
	v_xor_b32_e32 v0, v0, v162
	v_xor_b32_e32 v154, v154, v162
	v_xor_b32_e32 v155, v155, v162
	v_xor_b32_e32 v156, v156, v162
	v_xor_b32_e32 v157, v157, v162
	v_xor_b32_e32 v158, v158, v162
	v_lshrrev_b32_e32 v163, 6, v194
	s_nop 0
	v_readfirstlane_b32 s98, v163
	s_lshl_b32 s98, s98, 10
	s_mov_b32 m0, s98
	s_nop 0
	buffer_load_dwordx4 v0, s[20:23], 0 offen lds
	s_add_u32 m0, m0, 0x1000
	s_nop 0
	buffer_load_dwordx4 v154, s[20:23], 0 offen lds
	s_add_u32 m0, m0, 0x1000
	s_nop 0
	buffer_load_dwordx4 v155, s[20:23], 0 offen lds
	s_add_u32 m0, m0, 0x1000
	s_nop 0
	buffer_load_dwordx4 v156, s[20:23], 0 offen lds
	s_add_u32 m0, m0, 0x1000
	s_nop 0
	buffer_load_dwordx4 v157, s[12:15], 0 offen lds
	s_add_u32 m0, m0, 0x1000
	s_nop 0
	buffer_load_dwordx4 v158, s[12:15], 0 offen lds
	s_add_u32 m0, s98, 0x6000
	s_nop 0
	buffer_load_dwordx4 v0, s[20:23], 64 offen lds
	s_add_u32 m0, m0, 0x1000
	s_nop 0
	buffer_load_dwordx4 v154, s[20:23], 64 offen lds
	s_add_u32 m0, m0, 0x1000
	s_nop 0
	buffer_load_dwordx4 v155, s[20:23], 64 offen lds
	s_add_u32 m0, m0, 0x1000
	s_nop 0
	buffer_load_dwordx4 v156, s[20:23], 64 offen lds
	s_add_u32 m0, m0, 0x1000
	s_nop 0
	buffer_load_dwordx4 v157, s[12:15], 64 offen lds
	s_add_u32 m0, m0, 0x1000
	s_nop 0
	buffer_load_dwordx4 v158, s[12:15], 64 offen lds
	v_lshrrev_b32_e32 v43, 1, v38
	v_bfe_i32 v42, v38, 3, 1
	v_lshlrev_b32_e32 v45, 6, v39
	v_lshrrev_b32_e32 v39, 1, v39
	v_and_b32_e32 v43, 2, v43
	v_bfe_i32 v41, v38, 5, 1
	v_and_b32_e32 v39, 2, v39
	v_bitop3_b32 v42, v42, v43, 3 bitop3:0x6c
	v_bitop3_b32 v39, v41, v39, 3 bitop3:0x6c
	v_lshlrev_b32_e32 v41, 4, v42
	v_lshlrev_b32_e32 v44, 6, v38
	v_xor_b32_e32 v39, v39, v40
	v_bitop3_b32 v38, v41, v38, 48 bitop3:0x78
	s_movk_i32 s8, 0x13c0
	v_mov_b32_e32 v2, 0
	v_lshl_or_b32 v159, v39, 4, v45
	v_and_or_b32 v160, v44, s8, v38
	s_movk_i32 s8, 0xe3c0
	s_mov_b32 s7, 0
	s_movk_i32 s6, 0x80
	v_mov_b32_e32 v3, v2
	v_mov_b32_e32 v4, v2
	v_mov_b32_e32 v5, v2
	s_waitcnt vmcnt(12)
	v_mov_b32_e32 v6, v2
	v_mov_b32_e32 v7, v2
	v_mov_b32_e32 v8, v2
	v_mov_b32_e32 v9, v2
	v_mov_b32_e32 v10, v2
	v_mov_b32_e32 v11, v2
	v_mov_b32_e32 v12, v2
	v_mov_b32_e32 v13, v2
	v_and_or_b32 v161, v44, s8, v38
	v_mov_b32_e32 v38, v2
	v_mov_b32_e32 v39, v2
	v_mov_b32_e32 v40, v2
	v_mov_b32_e32 v41, v2
	v_mov_b32_e32 v42, v2
	v_mov_b32_e32 v43, v2
	v_mov_b32_e32 v44, v2
	v_mov_b32_e32 v45, v2
	v_mov_b32_e32 v46, v2
	v_mov_b32_e32 v47, v2
	v_mov_b32_e32 v48, v2
	v_mov_b32_e32 v49, v2
	v_mov_b32_e32 v50, v2
	v_mov_b32_e32 v51, v2
	v_mov_b32_e32 v52, v2
	v_mov_b32_e32 v53, v2
	v_mov_b32_e32 v54, v2
	v_mov_b32_e32 v55, v2
	v_mov_b32_e32 v56, v2
	v_mov_b32_e32 v57, v2
	v_mov_b32_e32 v58, v2
	v_mov_b32_e32 v59, v2
	v_mov_b32_e32 v14, v2
	v_mov_b32_e32 v15, v2
	v_mov_b32_e32 v16, v2
	v_mov_b32_e32 v17, v2
	v_mov_b32_e32 v18, v2
	v_mov_b32_e32 v19, v2
	v_mov_b32_e32 v20, v2
	v_mov_b32_e32 v21, v2
	v_mov_b32_e32 v22, v2
	v_mov_b32_e32 v23, v2
	v_mov_b32_e32 v24, v2
	v_mov_b32_e32 v25, v2
	v_mov_b32_e32 v26, v2
	v_mov_b32_e32 v27, v2
	v_mov_b32_e32 v28, v2
	v_mov_b32_e32 v29, v2
	v_mov_b32_e32 v30, v2
	v_mov_b32_e32 v31, v2
	v_mov_b32_e32 v32, v2
	v_mov_b32_e32 v33, v2
	v_mov_b32_e32 v34, v2
	v_mov_b32_e32 v35, v2
	v_mov_b32_e32 v36, v2
	v_mov_b32_e32 v37, v2
	v_mov_b32_e32 v60, v2
	v_mov_b32_e32 v61, v2
	v_mov_b32_e32 v62, v2
	v_mov_b32_e32 v63, v2
	v_mov_b32_e32 v64, v2
	v_mov_b32_e32 v65, v2
	v_mov_b32_e32 v66, v2
	v_mov_b32_e32 v67, v2
	v_mov_b32_e32 v68, v2
	v_mov_b32_e32 v69, v2
	v_mov_b32_e32 v70, v2
	v_mov_b32_e32 v71, v2
	v_mov_b32_e32 v72, v2
	v_mov_b32_e32 v73, v2
	v_mov_b32_e32 v74, v2
	v_mov_b32_e32 v75, v2
	v_mov_b32_e32 v76, v2
	v_mov_b32_e32 v77, v2
	v_mov_b32_e32 v78, v2
	v_mov_b32_e32 v79, v2
	v_mov_b32_e32 v80, v2
	v_mov_b32_e32 v81, v2
	v_mov_b32_e32 v82, v2
	v_mov_b32_e32 v83, v2
	v_mov_b32_e32 v84, v2
	v_mov_b32_e32 v85, v2
	v_mov_b32_e32 v86, v2
	v_mov_b32_e32 v87, v2
	v_mov_b32_e32 v88, v2
	v_mov_b32_e32 v89, v2
	v_mov_b32_e32 v90, v2
	v_mov_b32_e32 v91, v2
	v_mov_b32_e32 v92, v2
	v_mov_b32_e32 v93, v2
	v_mov_b32_e32 v94, v2
	v_mov_b32_e32 v95, v2
	v_mov_b32_e32 v96, v2
	v_mov_b32_e32 v97, v2
	v_mov_b32_e32 v98, v2
	v_mov_b32_e32 v99, v2
	v_mov_b32_e32 v100, v2
	v_mov_b32_e32 v101, v2
	v_mov_b32_e32 v102, v2
	v_mov_b32_e32 v103, v2
	v_mov_b32_e32 v104, v2
	v_mov_b32_e32 v105, v2
	v_mov_b32_e32 v106, v2
	v_mov_b32_e32 v107, v2
	v_mov_b32_e32 v108, v2
	v_mov_b32_e32 v109, v2
	v_mov_b32_e32 v110, v2
	v_mov_b32_e32 v111, v2
	v_mov_b32_e32 v112, v2
	v_mov_b32_e32 v113, v2
	v_mov_b32_e32 v114, v2
	v_mov_b32_e32 v115, v2
	v_mov_b32_e32 v116, v2
	v_mov_b32_e32 v117, v2
	v_mov_b32_e32 v118, v2
	v_mov_b32_e32 v119, v2
	v_mov_b32_e32 v120, v2
	v_mov_b32_e32 v121, v2
	v_mov_b32_e32 v122, v2
	v_mov_b32_e32 v123, v2
	v_mov_b32_e32 v124, v2
	v_mov_b32_e32 v125, v2
	v_mov_b32_e32 v126, v2
	v_mov_b32_e32 v127, v2
	v_mov_b32_e32 v128, v2
	v_mov_b32_e32 v129, v2
	s_waitcnt vmcnt(6) lgkmcnt(0)
	s_barrier
	ds_read_b128 v[236:239], v160 offset:16384
	ds_read_b128 v[240:243], v160 offset:17408
	ds_read_b128 v[244:247], v160 offset:18432
	ds_read_b128 v[248:251], v160 offset:19456
	ds_read_b128 v[186:189], v161
	ds_read_b128 v[190:193], v161 offset:1024
	ds_read_b128 v[212:215], v161 offset:2048
	ds_read_b128 v[216:219], v161 offset:3072
	ds_read_b128 v[220:223], v161 offset:4096
	ds_read_b128 v[224:227], v161 offset:5120
	ds_read_b128 v[228:231], v161 offset:6144
	ds_read_b128 v[232:235], v161 offset:7168
	s_waitcnt vmcnt(0) lgkmcnt(0)
	s_barrier
; DI void cfence() { asm volatile("" ::: "memory"); }
; DI int swz4(int row) { const int g = (row >> 2) & 3; return ((g << 1) ^ ((g >> 1) * 3)) & 3; }
; #define LSTORE2(RA, RB, P)                                       \
;   {                                                              \
;     char* dA_ = smem + (P) * 24576 + wofs;                       \
;     _Pragma("unroll") for (int j = 0; j < 4; ++j) *(u32x4*)(dA_ + j * 4096) = RA[j]; \
;     _Pragma("unroll") for (int j = 0; j < 2; ++j) *(u32x4*)(dA_ + 16384 + j * 4096) = RB[j]; \
;   }
; DI void gemm256_kloop(f32x4 (&acc)[8][4], const bf16_t* __restrict__ A, int lda, const bf16_t* __restrict__ Bt, int ldb,
;                       int K, int b, int s0, int col0, char* smem) {
;     ...
;   GLOAD2(xa, xb, 0);
;   GLOAD2(ya, yb, 1);
;   cfence();
;   LSTORE2(xa, xb, 0);
;   __syncthreads();
;   const int co = ((fq ^ swz4(fr)) << 4);
;   const int aofs = (wr * 128 + fr) * 64 + co, bofs = (wc * 64 + fr) * 64 + co;
;   for (int kt = 0; kt < nk; kt += 2) {
;     GLOAD2(xa, xb, kt + 2);
;     cfence();
;     COMPUTE2(0);
;     LSTORE2(ya, yb, 1);
;     __syncthreads();
.LBB0_462:
	s_add_i32 s8, s7, 2
	s_cmp_lt_u32 s7, 62
	s_cselect_b64 s[10:11], -1, 0
	s_and_b64 vcc, s[10:11], exec
	s_cselect_b32 s9, s6, 0xfc0
	s_setprio 1
	s_mov_b32 m0, s98
	v_mfma_f32_16x16x32_bf16 v[126:129], v[186:189], v[236:239], v[126:129]
	buffer_load_dwordx4 v0, s[20:23], s9 offen lds
	s_add_u32 m0, m0, 0x1000
	v_mfma_f32_16x16x32_bf16 v[122:125], v[186:189], v[240:243], v[122:125]
	buffer_load_dwordx4 v154, s[20:23], s9 offen lds
	s_add_u32 m0, m0, 0x1000
	v_mfma_f32_16x16x32_bf16 v[118:121], v[186:189], v[244:247], v[118:121]
	buffer_load_dwordx4 v155, s[20:23], s9 offen lds
	s_add_u32 m0, m0, 0x1000
	v_mfma_f32_16x16x32_bf16 v[114:117], v[186:189], v[248:251], v[114:117]
	buffer_load_dwordx4 v156, s[20:23], s9 offen lds
	s_add_u32 m0, m0, 0x1000
	v_mfma_f32_16x16x32_bf16 v[110:113], v[190:193], v[236:239], v[110:113]
	buffer_load_dwordx4 v157, s[12:15], s9 offen lds
	s_add_u32 m0, m0, 0x1000
	v_mfma_f32_16x16x32_bf16 v[106:109], v[190:193], v[240:243], v[106:109]
	buffer_load_dwordx4 v158, s[12:15], s9 offen lds
	v_mfma_f32_16x16x32_bf16 v[102:105], v[190:193], v[244:247], v[102:105]
	ds_read_b128 v[170:173], v160 offset:40960
	v_mfma_f32_16x16x32_bf16 v[98:101], v[190:193], v[248:251], v[98:101]
	v_mfma_f32_16x16x32_bf16 v[94:97], v[212:215], v[236:239], v[94:97]
	ds_read_b128 v[174:177], v160 offset:41984
	v_mfma_f32_16x16x32_bf16 v[90:93], v[212:215], v[240:243], v[90:93]
	v_mfma_f32_16x16x32_bf16 v[86:89], v[212:215], v[244:247], v[86:89]
	ds_read_b128 v[178:181], v160 offset:43008
	v_mfma_f32_16x16x32_bf16 v[82:85], v[212:215], v[248:251], v[82:85]
	v_mfma_f32_16x16x32_bf16 v[78:81], v[216:219], v[236:239], v[78:81]
	ds_read_b128 v[182:185], v160 offset:44032
	v_mfma_f32_16x16x32_bf16 v[74:77], v[216:219], v[240:243], v[74:77]
	v_mfma_f32_16x16x32_bf16 v[70:73], v[216:219], v[244:247], v[70:73]
	ds_read_b128 v[130:133], v161 offset:24576
	v_mfma_f32_16x16x32_bf16 v[66:69], v[216:219], v[248:251], v[66:69]
	v_mfma_f32_16x16x32_bf16 v[62:65], v[220:223], v[236:239], v[62:65]
	ds_read_b128 v[134:137], v161 offset:25600
	v_mfma_f32_16x16x32_bf16 v[58:61], v[220:223], v[240:243], v[58:61]
	v_mfma_f32_16x16x32_bf16 v[54:57], v[220:223], v[244:247], v[54:57]
	ds_read_b128 v[138:141], v161 offset:26624
	v_mfma_f32_16x16x32_bf16 v[50:53], v[220:223], v[248:251], v[50:53]
	v_mfma_f32_16x16x32_bf16 v[46:49], v[224:227], v[236:239], v[46:49]
	ds_read_b128 v[142:145], v161 offset:27648
	v_mfma_f32_16x16x32_bf16 v[42:45], v[224:227], v[240:243], v[42:45]
	v_mfma_f32_16x16x32_bf16 v[38:41], v[224:227], v[244:247], v[38:41]
	ds_read_b128 v[146:149], v161 offset:28672
	v_mfma_f32_16x16x32_bf16 v[34:37], v[224:227], v[248:251], v[34:37]
	v_mfma_f32_16x16x32_bf16 v[30:33], v[228:231], v[236:239], v[30:33]
	ds_read_b128 v[150:153], v161 offset:29696
	v_mfma_f32_16x16x32_bf16 v[26:29], v[228:231], v[240:243], v[26:29]
	v_mfma_f32_16x16x32_bf16 v[22:25], v[228:231], v[244:247], v[22:25]
	ds_read_b128 v[162:165], v161 offset:30720
	v_mfma_f32_16x16x32_bf16 v[18:21], v[228:231], v[248:251], v[18:21]
	v_mfma_f32_16x16x32_bf16 v[14:17], v[232:235], v[236:239], v[14:17]
	ds_read_b128 v[166:169], v161 offset:31744
	v_mfma_f32_16x16x32_bf16 v[10:13], v[232:235], v[240:243], v[10:13]
	v_mfma_f32_16x16x32_bf16 v[6:9], v[232:235], v[244:247], v[6:9]
	v_mfma_f32_16x16x32_bf16 v[2:5], v[232:235], v[248:251], v[2:5]
	s_setprio 0
	s_min_u32 s7, s7, 60
	s_lshl_b32 s7, s7, 6
	s_addk_i32 s7, 0xc0
	s_waitcnt vmcnt(0) lgkmcnt(0)
	s_barrier
; DI void cfence() { asm volatile("" ::: "memory"); }
; DI int swz4(int row) { const int g = (row >> 2) & 3; return ((g << 1) ^ ((g >> 1) * 3)) & 3; }
; #define LSTORE2(RA, RB, P)                                       \
;   {                                                              \
;     char* dA_ = smem + (P) * 24576 + wofs;                       \
;     _Pragma("unroll") for (int j = 0; j < 4; ++j) *(u32x4*)(dA_ + j * 4096) = RA[j]; \
;     _Pragma("unroll") for (int j = 0; j < 2; ++j) *(u32x4*)(dA_ + 16384 + j * 4096) = RB[j]; \
;   }
; DI void gemm256_kloop(f32x4 (&acc)[8][4], const bf16_t* __restrict__ A, int lda, const bf16_t* __restrict__ Bt, int ldb,
;                       int K, int b, int s0, int col0, char* smem) {
;     ...
;   GLOAD2(xa, xb, 0);
;   GLOAD2(ya, yb, 1);
;   cfence();
;   LSTORE2(xa, xb, 0);
;   __syncthreads();
;   const int co = ((fq ^ swz4(fr)) << 4);
;   const int aofs = (wr * 128 + fr) * 64 + co, bofs = (wc * 64 + fr) * 64 + co;
;   for (int kt = 0; kt < nk; kt += 2) {
;     GLOAD2(xa, xb, kt + 2);
;     cfence();
;     COMPUTE2(0);
;     LSTORE2(ya, yb, 1);
;     __syncthreads();
;     if (kt + 1 < nk) {
;       GLOAD2(ya, yb, kt + 3);
;       cfence();
;       COMPUTE2(1);
;       LSTORE2(xa, xb, 0);
;       __syncthreads();
;     }
	s_setprio 1
	s_add_u32 m0, s98, 0x6000
	v_mfma_f32_16x16x32_bf16 v[126:129], v[130:133], v[170:173], v[126:129]
	buffer_load_dwordx4 v0, s[20:23], s7 offen lds
	s_add_u32 m0, m0, 0x1000
	v_mfma_f32_16x16x32_bf16 v[122:125], v[130:133], v[174:177], v[122:125]
	buffer_load_dwordx4 v154, s[20:23], s7 offen lds
	s_add_u32 m0, m0, 0x1000
	v_mfma_f32_16x16x32_bf16 v[118:121], v[130:133], v[178:181], v[118:121]
	buffer_load_dwordx4 v155, s[20:23], s7 offen lds
	s_add_u32 m0, m0, 0x1000
	v_mfma_f32_16x16x32_bf16 v[114:117], v[130:133], v[182:185], v[114:117]
	buffer_load_dwordx4 v156, s[20:23], s7 offen lds
	s_add_u32 m0, m0, 0x1000
	v_mfma_f32_16x16x32_bf16 v[110:113], v[134:137], v[170:173], v[110:113]
	buffer_load_dwordx4 v157, s[12:15], s7 offen lds
	s_add_u32 m0, m0, 0x1000
	v_mfma_f32_16x16x32_bf16 v[106:109], v[134:137], v[174:177], v[106:109]
	buffer_load_dwordx4 v158, s[12:15], s7 offen lds
	v_mfma_f32_16x16x32_bf16 v[102:105], v[134:137], v[178:181], v[102:105]
	ds_read_b128 v[236:239], v160 offset:16384
	v_mfma_f32_16x16x32_bf16 v[98:101], v[134:137], v[182:185], v[98:101]
	v_mfma_f32_16x16x32_bf16 v[94:97], v[138:141], v[170:173], v[94:97]
	ds_read_b128 v[240:243], v160 offset:17408
	v_mfma_f32_16x16x32_bf16 v[90:93], v[138:141], v[174:177], v[90:93]
	v_mfma_f32_16x16x32_bf16 v[86:89], v[138:141], v[178:181], v[86:89]
	ds_read_b128 v[244:247], v160 offset:18432
	v_mfma_f32_16x16x32_bf16 v[82:85], v[138:141], v[182:185], v[82:85]
	v_mfma_f32_16x16x32_bf16 v[78:81], v[142:145], v[170:173], v[78:81]
	ds_read_b128 v[248:251], v160 offset:19456
	v_mfma_f32_16x16x32_bf16 v[74:77], v[142:145], v[174:177], v[74:77]
	v_mfma_f32_16x16x32_bf16 v[70:73], v[142:145], v[178:181], v[70:73]
	ds_read_b128 v[186:189], v161
	v_mfma_f32_16x16x32_bf16 v[66:69], v[142:145], v[182:185], v[66:69]
	v_mfma_f32_16x16x32_bf16 v[62:65], v[146:149], v[170:173], v[62:65]
	ds_read_b128 v[190:193], v161 offset:1024
	v_mfma_f32_16x16x32_bf16 v[58:61], v[146:149], v[174:177], v[58:61]
	v_mfma_f32_16x16x32_bf16 v[54:57], v[146:149], v[178:181], v[54:57]
	ds_read_b128 v[212:215], v161 offset:2048
	v_mfma_f32_16x16x32_bf16 v[50:53], v[146:149], v[182:185], v[50:53]
	v_mfma_f32_16x16x32_bf16 v[46:49], v[150:153], v[170:173], v[46:49]
	ds_read_b128 v[216:219], v161 offset:3072
	v_mfma_f32_16x16x32_bf16 v[42:45], v[150:153], v[174:177], v[42:45]
	v_mfma_f32_16x16x32_bf16 v[38:41], v[150:153], v[178:181], v[38:41]
	ds_read_b128 v[220:223], v161 offset:4096
	v_mfma_f32_16x16x32_bf16 v[34:37], v[150:153], v[182:185], v[34:37]
	v_mfma_f32_16x16x32_bf16 v[30:33], v[162:165], v[170:173], v[30:33]
	ds_read_b128 v[224:227], v161 offset:5120
	v_mfma_f32_16x16x32_bf16 v[26:29], v[162:165], v[174:177], v[26:29]
	v_mfma_f32_16x16x32_bf16 v[22:25], v[162:165], v[178:181], v[22:25]
	ds_read_b128 v[228:231], v161 offset:6144
	v_mfma_f32_16x16x32_bf16 v[18:21], v[162:165], v[182:185], v[18:21]
	v_mfma_f32_16x16x32_bf16 v[14:17], v[166:169], v[170:173], v[14:17]
	ds_read_b128 v[232:235], v161 offset:7168
	v_mfma_f32_16x16x32_bf16 v[10:13], v[166:169], v[174:177], v[10:13]
	v_mfma_f32_16x16x32_bf16 v[6:9], v[166:169], v[178:181], v[6:9]
	v_mfma_f32_16x16x32_bf16 v[2:5], v[166:169], v[182:185], v[2:5]
	s_setprio 0
	s_addk_i32 s6, 0x80
	s_mov_b32 s7, s8
	s_waitcnt vmcnt(0) lgkmcnt(0)
	s_barrier
	s_cbranch_vccnz .LBB0_462
	s_ashr_i32 s6, s5, 2
	s_cmp_lt_i32 s6, 2
	s_cselect_b64 s[8:9], -1, 0
	s_ashr_i32 s7, s6, 31
	s_lshl_b64 s[6:7], s[6:7], 2
	s_add_u32 s10, s52, s6
	s_addc_u32 s11, s53, s7
	s_lshl_b32 s5, s51, 7
	s_mulk_i32 s4, 0x480
	s_sub_i32 s71, s5, s4
	s_add_i32 s71, s71, 0xfffcf400
	s_mov_b32 s38, 0
	s_mov_b64 s[14:15], -1
	s_waitcnt vmcnt(0)
	s_branch .LBB0_465

; DI int tidx() { int t = __builtin_amdgcn_workitem_id_x(); asm volatile("" : "+v"(t)); return t; }
; DI brsrc_t make_rsrc(const void* p) { return __builtin_amdgcn_make_buffer_rsrc((void*)p, 0, 0x7fffffff, 0x00020000); }
; DI void cfence() { asm volatile("" ::: "memory"); }
; DI int swz4(int row) { const int g = (row >> 2) & 3; return ((g << 1) ^ ((g >> 1) * 3)) & 3; }
; #define LSTORE2(RA, RB, P)                                       \
;   {                                                              \
;     char* dA_ = smem + (P) * 24576 + wofs;                       \
;     _Pragma("unroll") for (int j = 0; j < 4; ++j) *(u32x4*)(dA_ + j * 4096) = RA[j]; \
;     _Pragma("unroll") for (int j = 0; j < 2; ++j) *(u32x4*)(dA_ + 16384 + j * 4096) = RB[j]; \
;   }
; DI void gemm256_kloop(f32x4 (&acc)[8][4], const bf16_t* __restrict__ A, int lda, const bf16_t* __restrict__ Bt, int ldb,
;                       int K, int b, int s0, int col0, char* smem) {
;   const int tid = tidx(), lane = tid & 63, wid = tid >> 6;
;   const int wr = wid >> 1, wc = wid & 1, fr = lane & 15, fq = lane >> 4;
;   const int lrow = tid >> 2, lkc = tid & 3;
;   const brsrc_t rA = make_rsrc(A), rB = make_rsrc(Bt);
;   unsigned aoff[4];
; #pragma unroll
;   for (int j = 0; j < 4; ++j) {
;     int s = s0 + lrow + 64 * j;
;     s = s < 0 ? 0 : (s > SB - 1 ? SB - 1 : s);
;     aoff[j] = ((unsigned)(b * SB + s) * (unsigned)lda + lkc * 8) * 2u;
;   }
;   const unsigned boff = ((unsigned)(col0 + lrow) * (unsigned)ldb + lkc * 8) * 2u;
;   const unsigned bstep = 64u * (unsigned)ldb * 2u;
;   const int wofs = lrow * 64 + ((lkc ^ swz4(lrow)) << 4);
;   const int nk = K >> 5;
;   u32x4 xa[4], xb[2], ya[4], yb[2];
;     ...
;   GLOAD2(xa, xb, 0);
;   GLOAD2(ya, yb, 1);
;   cfence();
;   LSTORE2(xa, xb, 0);
;   __syncthreads();
;   const int co = ((fq ^ swz4(fr)) << 4);
;   const int aofs = (wr * 128 + fr) * 64 + co, bofs = (wc * 64 + fr) * 64 + co;
; template <class Epi>
; DI void gemm256_item_plain(const bf16_t* A, int lda, const bf16_t* Bt, int ldb, int K, int ntn, char* smem, const Epi& epi, int it) {
;   int mt = it / ntn, nt = it - mt * ntn;
;   int b = mt / 65, s0 = (mt - b * 65) * 256;
;   gemm256_tile(A, lda, Bt, ldb, K, b, s0, nt * 128, smem, epi, 128);
.LBB0_477:
	s_and_b64 vcc, exec, s[4:5]
	s_cbranch_vccz .LBB0_459
	s_mul_hi_i32 s4, s51, 0x2aaaaaab
	s_lshr_b32 s5, s4, 31
	s_ashr_i32 s38, s4, 1
	s_mul_hi_i32 s4, s51, 0xa80a80a9
	s_add_i32 s4, s4, s51
	s_lshr_b32 s6, s4, 31
	s_ashr_i32 s4, s4, 9
	s_add_i32 s6, s4, s6
	s_add_i32 s38, s38, s5
	s_mul_i32 s4, s6, 0xffffffbf
	s_add_i32 s4, s4, s38
	s_waitcnt vmcnt(0)
	v_mov_b32_e32 v7, v194
	s_lshl_b32 s69, s4, 8
	s_mul_i32 s4, s6, 0x4100
	v_ashrrev_i32_e32 v32, 2, v7
	v_add_u32_e32 v2, s69, v32
	v_max_i32_e32 v4, 0xffffffc0, v2
	v_add_u32_e32 v4, 64, v4
	v_min_u32_e32 v4, 0x40ff, v4
	v_and_b32_e32 v33, 3, v7
	s_movk_i32 s7, 0x1080
	v_add_u32_e32 v4, s4, v4
	v_lshlrev_b32_e32 v3, 4, v33
	v_mul_lo_u32 v4, v4, s7
	v_med3_i32 v0, v2, 0, v201
	v_or_b32_e32 v154, v4, v3
	v_max_i32_e32 v4, 0xffffff80, v2
	v_max_i32_e32 v2, 0xffffff40, v2
	v_add_u32_e32 v2, 0xc0, v2
	s_mul_i32 s5, s38, -12
	v_min_u32_e32 v2, 0x40ff, v2
	s_add_i32 s5, s5, s51
	v_add_u32_e32 v2, s4, v2
	s_lshl_b32 s34, s5, 7
	v_mul_lo_u32 v2, v2, s7
	v_add_u32_e32 v4, 0x80, v4
	v_or_b32_e32 v156, v2, v3
	v_add_u32_e32 v2, s34, v32
	v_min_u32_e32 v4, 0x40ff, v4
	v_mul_lo_u32 v2, v2, s7
	v_add_u32_e32 v0, s4, v0
	v_add_u32_e32 v4, s4, v4
	v_or_b32_e32 v157, v2, v3
	v_mul_lo_u32 v0, v0, s7
	v_mul_lo_u32 v4, v4, s7
	s_mov_b32 s18, s22
	s_mov_b32 s19, s23
	v_add_u32_e32 v158, 0x42000, v157
	v_or_b32_e32 v0, v0, v3
	v_or_b32_e32 v155, v4, v3
	v_bfe_u32 v162, v194, 4, 2
	v_lshlrev_b32_e32 v162, 2, v162
	v_mov_b32_e32 v163, 0x1320
	v_lshrrev_b32_e32 v162, v162, v163
	v_and_b32_e32 v162, 3, v162
	v_lshlrev_b32_e32 v162, 4, v162
	v_xor_b32_e32 v0, v0, v162
	v_xor_b32_e32 v154, v154, v162
	v_xor_b32_e32 v155, v155, v162
	v_xor_b32_e32 v156, v156, v162
	v_xor_b32_e32 v157, v157, v162
	v_xor_b32_e32 v158, v158, v162
	v_lshrrev_b32_e32 v163, 6, v194
	s_nop 0
	v_readfirstlane_b32 s98, v163
	s_lshl_b32 s98, s98, 10
	s_mov_b32 m0, s98
	s_nop 0
	buffer_load_dwordx4 v0, s[20:23], 0 offen lds
	s_add_u32 m0, m0, 0x1000
	s_nop 0
	buffer_load_dwordx4 v154, s[20:23], 0 offen lds
	s_add_u32 m0, m0, 0x1000
	s_nop 0
	buffer_load_dwordx4 v155, s[20:23], 0 offen lds
	s_add_u32 m0, m0, 0x1000
	s_nop 0
	buffer_load_dwordx4 v156, s[20:23], 0 offen lds
	s_add_u32 m0, m0, 0x1000
	s_nop 0
	buffer_load_dwordx4 v157, s[16:19], 0 offen lds
	s_add_u32 m0, m0, 0x1000
	s_nop 0
	buffer_load_dwordx4 v158, s[16:19], 0 offen lds
	s_add_u32 m0, s98, 0x6000
	s_nop 0
	buffer_load_dwordx4 v0, s[20:23], 64 offen lds
	s_add_u32 m0, m0, 0x1000
	s_nop 0
	buffer_load_dwordx4 v154, s[20:23], 64 offen lds
	s_add_u32 m0, m0, 0x1000
	s_nop 0
	buffer_load_dwordx4 v155, s[20:23], 64 offen lds
	s_add_u32 m0, m0, 0x1000
	s_nop 0
	buffer_load_dwordx4 v156, s[20:23], 64 offen lds
	s_add_u32 m0, m0, 0x1000
	s_nop 0
	buffer_load_dwordx4 v157, s[16:19], 64 offen lds
	s_add_u32 m0, m0, 0x1000
	s_nop 0
	buffer_load_dwordx4 v158, s[16:19], 64 offen lds
	v_lshrrev_b32_e32 v36, 1, v7
	v_bfe_i32 v35, v7, 3, 1
	v_lshlrev_b32_e32 v38, 6, v32
	v_lshrrev_b32_e32 v32, 1, v32
	v_and_b32_e32 v36, 2, v36
	v_bfe_i32 v34, v7, 5, 1
	v_and_b32_e32 v32, 2, v32
	v_bitop3_b32 v35, v35, v36, 3 bitop3:0x6c
	v_bitop3_b32 v32, v34, v32, 3 bitop3:0x6c
	v_lshlrev_b32_e32 v34, 4, v35
	v_lshlrev_b32_e32 v37, 6, v7
	v_xor_b32_e32 v32, v32, v33
	v_bitop3_b32 v7, v34, v7, 48 bitop3:0x78
	s_movk_i32 s9, 0x13c0
	v_mov_b32_e32 v2, 0
	v_lshl_or_b32 v159, v32, 4, v38
	v_and_or_b32 v160, v37, s9, v7
	s_movk_i32 s9, 0xe3c0
	s_mov_b32 s8, 0
	s_movk_i32 s7, 0x80
	v_mov_b32_e32 v3, v2
	v_mov_b32_e32 v4, v2
	v_mov_b32_e32 v5, v2
	v_mov_b32_e32 v6, v2
	v_and_or_b32 v161, v37, s9, v7
	v_mov_b32_e32 v7, v2
	v_mov_b32_e32 v32, v2
	v_mov_b32_e32 v33, v2
	v_mov_b32_e32 v34, v2
	v_mov_b32_e32 v35, v2
	v_mov_b32_e32 v36, v2
	v_mov_b32_e32 v37, v2
	v_mov_b32_e32 v38, v2
	v_mov_b32_e32 v39, v2
	v_mov_b32_e32 v40, v2
	v_mov_b32_e32 v41, v2
	v_mov_b32_e32 v42, v2
	v_mov_b32_e32 v43, v2
	v_mov_b32_e32 v44, v2
	v_mov_b32_e32 v45, v2
	v_mov_b32_e32 v46, v2
	v_mov_b32_e32 v47, v2
	v_mov_b32_e32 v48, v2
	v_mov_b32_e32 v49, v2
	v_mov_b32_e32 v50, v2
	v_mov_b32_e32 v51, v2
	v_mov_b32_e32 v52, v2
	v_mov_b32_e32 v53, v2
	v_mov_b32_e32 v8, v2
	v_mov_b32_e32 v9, v2
	v_mov_b32_e32 v10, v2
	v_mov_b32_e32 v11, v2
	v_mov_b32_e32 v12, v2
	v_mov_b32_e32 v13, v2
	v_mov_b32_e32 v14, v2
	v_mov_b32_e32 v15, v2
	v_mov_b32_e32 v16, v2
	v_mov_b32_e32 v17, v2
	v_mov_b32_e32 v18, v2
	v_mov_b32_e32 v19, v2
	v_mov_b32_e32 v20, v2
	v_mov_b32_e32 v21, v2
	v_mov_b32_e32 v22, v2
	v_mov_b32_e32 v23, v2
	v_mov_b32_e32 v24, v2
	v_mov_b32_e32 v25, v2
	v_mov_b32_e32 v26, v2
	v_mov_b32_e32 v27, v2
	v_mov_b32_e32 v28, v2
	v_mov_b32_e32 v29, v2
	v_mov_b32_e32 v30, v2
	v_mov_b32_e32 v31, v2
	v_mov_b32_e32 v54, v2
	v_mov_b32_e32 v55, v2
	v_mov_b32_e32 v56, v2
	v_mov_b32_e32 v57, v2
	v_mov_b32_e32 v58, v2
	v_mov_b32_e32 v59, v2
	v_mov_b32_e32 v60, v2
	v_mov_b32_e32 v61, v2
	v_mov_b32_e32 v62, v2
	v_mov_b32_e32 v63, v2
	v_mov_b32_e32 v64, v2
	v_mov_b32_e32 v65, v2
	v_mov_b32_e32 v66, v2
	v_mov_b32_e32 v67, v2
	v_mov_b32_e32 v68, v2
	v_mov_b32_e32 v69, v2
	v_mov_b32_e32 v70, v2
	v_mov_b32_e32 v71, v2
	v_mov_b32_e32 v72, v2
	v_mov_b32_e32 v73, v2
	v_mov_b32_e32 v74, v2
	v_mov_b32_e32 v75, v2
	v_mov_b32_e32 v76, v2
	v_mov_b32_e32 v77, v2
	v_mov_b32_e32 v78, v2
	v_mov_b32_e32 v79, v2
	v_mov_b32_e32 v80, v2
	v_mov_b32_e32 v81, v2
	v_mov_b32_e32 v82, v2
	v_mov_b32_e32 v83, v2
	v_mov_b32_e32 v84, v2
	v_mov_b32_e32 v85, v2
	v_mov_b32_e32 v86, v2
	v_mov_b32_e32 v87, v2
	v_mov_b32_e32 v88, v2
	v_mov_b32_e32 v89, v2
	v_mov_b32_e32 v90, v2
	v_mov_b32_e32 v91, v2
	v_mov_b32_e32 v92, v2
	v_mov_b32_e32 v93, v2
	v_mov_b32_e32 v94, v2
	v_mov_b32_e32 v95, v2
	v_mov_b32_e32 v96, v2
	v_mov_b32_e32 v97, v2
	v_mov_b32_e32 v98, v2
	v_mov_b32_e32 v99, v2
	v_mov_b32_e32 v100, v2
	v_mov_b32_e32 v101, v2
	v_mov_b32_e32 v102, v2
	v_mov_b32_e32 v103, v2
	v_mov_b32_e32 v104, v2
	v_mov_b32_e32 v105, v2
	v_mov_b32_e32 v106, v2
	v_mov_b32_e32 v107, v2
	v_mov_b32_e32 v108, v2
	v_mov_b32_e32 v109, v2
	v_mov_b32_e32 v110, v2
	v_mov_b32_e32 v111, v2
	v_mov_b32_e32 v112, v2
	v_mov_b32_e32 v113, v2
	v_mov_b32_e32 v114, v2
	v_mov_b32_e32 v115, v2
	v_mov_b32_e32 v116, v2
	v_mov_b32_e32 v117, v2
	v_mov_b32_e32 v118, v2
	v_mov_b32_e32 v119, v2
	v_mov_b32_e32 v120, v2
	v_mov_b32_e32 v121, v2
	v_mov_b32_e32 v122, v2
	v_mov_b32_e32 v123, v2
	v_mov_b32_e32 v124, v2
	v_mov_b32_e32 v125, v2
	v_mov_b32_e32 v126, v2
	v_mov_b32_e32 v127, v2
	v_mov_b32_e32 v128, v2
	v_mov_b32_e32 v129, v2
	s_waitcnt vmcnt(6) lgkmcnt(0)
	s_barrier
	ds_read_b128 v[236:239], v160 offset:16384
	ds_read_b128 v[240:243], v160 offset:17408
	ds_read_b128 v[244:247], v160 offset:18432
	ds_read_b128 v[248:251], v160 offset:19456
	ds_read_b128 v[186:189], v161
	ds_read_b128 v[190:193], v161 offset:1024
	ds_read_b128 v[212:215], v161 offset:2048
	ds_read_b128 v[216:219], v161 offset:3072
	ds_read_b128 v[220:223], v161 offset:4096
	ds_read_b128 v[224:227], v161 offset:5120
	ds_read_b128 v[228:231], v161 offset:6144
	ds_read_b128 v[232:235], v161 offset:7168
	s_waitcnt vmcnt(0) lgkmcnt(0)
	s_barrier
; DI void cfence() { asm volatile("" ::: "memory"); }
; DI int swz4(int row) { const int g = (row >> 2) & 3; return ((g << 1) ^ ((g >> 1) * 3)) & 3; }
; #define LSTORE2(RA, RB, P)                                       \
;   {                                                              \
;     char* dA_ = smem + (P) * 24576 + wofs;                       \
;     _Pragma("unroll") for (int j = 0; j < 4; ++j) *(u32x4*)(dA_ + j * 4096) = RA[j]; \
;     _Pragma("unroll") for (int j = 0; j < 2; ++j) *(u32x4*)(dA_ + 16384 + j * 4096) = RB[j]; \
;   }
; DI void gemm256_kloop(f32x4 (&acc)[8][4], const bf16_t* __restrict__ A, int lda, const bf16_t* __restrict__ Bt, int ldb,
;                       int K, int b, int s0, int col0, char* smem) {
;     ...
;   GLOAD2(xa, xb, 0);
;   GLOAD2(ya, yb, 1);
;   cfence();
;   LSTORE2(xa, xb, 0);
;   __syncthreads();
;   const int co = ((fq ^ swz4(fr)) << 4);
;   const int aofs = (wr * 128 + fr) * 64 + co, bofs = (wc * 64 + fr) * 64 + co;
;   for (int kt = 0; kt < nk; kt += 2) {
;     GLOAD2(xa, xb, kt + 2);
;     cfence();
;     COMPUTE2(0);
;     LSTORE2(ya, yb, 1);
;     __syncthreads();
.LBB0_479:
	s_add_i32 s9, s8, 2
	s_cmp_lt_u32 s8, 62
	s_cselect_b64 s[10:11], -1, 0
	s_and_b64 vcc, s[10:11], exec
	s_cselect_b32 s10, s7, 0xfc0
	s_setprio 1
	s_mov_b32 m0, s98
	v_mfma_f32_16x16x32_bf16 v[126:129], v[186:189], v[236:239], v[126:129]
	buffer_load_dwordx4 v0, s[20:23], s10 offen lds
	s_add_u32 m0, m0, 0x1000
	v_mfma_f32_16x16x32_bf16 v[122:125], v[186:189], v[240:243], v[122:125]
	buffer_load_dwordx4 v154, s[20:23], s10 offen lds
	s_add_u32 m0, m0, 0x1000
	v_mfma_f32_16x16x32_bf16 v[118:121], v[186:189], v[244:247], v[118:121]
	buffer_load_dwordx4 v155, s[20:23], s10 offen lds
	s_add_u32 m0, m0, 0x1000
	v_mfma_f32_16x16x32_bf16 v[114:117], v[186:189], v[248:251], v[114:117]
	buffer_load_dwordx4 v156, s[20:23], s10 offen lds
	s_add_u32 m0, m0, 0x1000
	v_mfma_f32_16x16x32_bf16 v[110:113], v[190:193], v[236:239], v[110:113]
	buffer_load_dwordx4 v157, s[16:19], s10 offen lds
	s_add_u32 m0, m0, 0x1000
	v_mfma_f32_16x16x32_bf16 v[106:109], v[190:193], v[240:243], v[106:109]
	buffer_load_dwordx4 v158, s[16:19], s10 offen lds
	v_mfma_f32_16x16x32_bf16 v[102:105], v[190:193], v[244:247], v[102:105]
	ds_read_b128 v[170:173], v160 offset:40960
	v_mfma_f32_16x16x32_bf16 v[98:101], v[190:193], v[248:251], v[98:101]
	v_mfma_f32_16x16x32_bf16 v[94:97], v[212:215], v[236:239], v[94:97]
	ds_read_b128 v[174:177], v160 offset:41984
	v_mfma_f32_16x16x32_bf16 v[90:93], v[212:215], v[240:243], v[90:93]
	v_mfma_f32_16x16x32_bf16 v[86:89], v[212:215], v[244:247], v[86:89]
	ds_read_b128 v[178:181], v160 offset:43008
	v_mfma_f32_16x16x32_bf16 v[82:85], v[212:215], v[248:251], v[82:85]
	v_mfma_f32_16x16x32_bf16 v[78:81], v[216:219], v[236:239], v[78:81]
	ds_read_b128 v[182:185], v160 offset:44032
	v_mfma_f32_16x16x32_bf16 v[74:77], v[216:219], v[240:243], v[74:77]
	v_mfma_f32_16x16x32_bf16 v[70:73], v[216:219], v[244:247], v[70:73]
	ds_read_b128 v[130:133], v161 offset:24576
	v_mfma_f32_16x16x32_bf16 v[66:69], v[216:219], v[248:251], v[66:69]
	v_mfma_f32_16x16x32_bf16 v[62:65], v[220:223], v[236:239], v[62:65]
	ds_read_b128 v[134:137], v161 offset:25600
	v_mfma_f32_16x16x32_bf16 v[58:61], v[220:223], v[240:243], v[58:61]
	v_mfma_f32_16x16x32_bf16 v[54:57], v[220:223], v[244:247], v[54:57]
	ds_read_b128 v[138:141], v161 offset:26624
	v_mfma_f32_16x16x32_bf16 v[50:53], v[220:223], v[248:251], v[50:53]
	v_mfma_f32_16x16x32_bf16 v[46:49], v[224:227], v[236:239], v[46:49]
	ds_read_b128 v[142:145], v161 offset:27648
	v_mfma_f32_16x16x32_bf16 v[42:45], v[224:227], v[240:243], v[42:45]
	v_mfma_f32_16x16x32_bf16 v[38:41], v[224:227], v[244:247], v[38:41]
	ds_read_b128 v[146:149], v161 offset:28672
	v_mfma_f32_16x16x32_bf16 v[34:37], v[224:227], v[248:251], v[34:37]
	v_mfma_f32_16x16x32_bf16 v[30:33], v[228:231], v[236:239], v[30:33]
	ds_read_b128 v[150:153], v161 offset:29696
	v_mfma_f32_16x16x32_bf16 v[26:29], v[228:231], v[240:243], v[26:29]
	v_mfma_f32_16x16x32_bf16 v[22:25], v[228:231], v[244:247], v[22:25]
	ds_read_b128 v[162:165], v161 offset:30720
	v_mfma_f32_16x16x32_bf16 v[18:21], v[228:231], v[248:251], v[18:21]
	v_mfma_f32_16x16x32_bf16 v[14:17], v[232:235], v[236:239], v[14:17]
	ds_read_b128 v[166:169], v161 offset:31744
	v_mfma_f32_16x16x32_bf16 v[10:13], v[232:235], v[240:243], v[10:13]
	v_mfma_f32_16x16x32_bf16 v[6:9], v[232:235], v[244:247], v[6:9]
	v_mfma_f32_16x16x32_bf16 v[2:5], v[232:235], v[248:251], v[2:5]
	s_setprio 0
	s_min_u32 s8, s8, 60
	s_lshl_b32 s8, s8, 6
	s_addk_i32 s8, 0xc0
	s_waitcnt vmcnt(0) lgkmcnt(0)
	s_barrier
; DI void cfence() { asm volatile("" ::: "memory"); }
; DI int swz4(int row) { const int g = (row >> 2) & 3; return ((g << 1) ^ ((g >> 1) * 3)) & 3; }
; #define LSTORE2(RA, RB, P)                                       \
;   {                                                              \
;     char* dA_ = smem + (P) * 24576 + wofs;                       \
;     _Pragma("unroll") for (int j = 0; j < 4; ++j) *(u32x4*)(dA_ + j * 4096) = RA[j]; \
;     _Pragma("unroll") for (int j = 0; j < 2; ++j) *(u32x4*)(dA_ + 16384 + j * 4096) = RB[j]; \
;   }
; DI void gemm256_kloop(f32x4 (&acc)[8][4], const bf16_t* __restrict__ A, int lda, const bf16_t* __restrict__ Bt, int ldb,
;                       int K, int b, int s0, int col0, char* smem) {
;     ...
;   GLOAD2(xa, xb, 0);
;   GLOAD2(ya, yb, 1);
;   cfence();
;   LSTORE2(xa, xb, 0);
;   __syncthreads();
;   const int co = ((fq ^ swz4(fr)) << 4);
;   const int aofs = (wr * 128 + fr) * 64 + co, bofs = (wc * 64 + fr) * 64 + co;
;   for (int kt = 0; kt < nk; kt += 2) {
;     GLOAD2(xa, xb, kt + 2);
;     cfence();
;     COMPUTE2(0);
;     LSTORE2(ya, yb, 1);
;     __syncthreads();
;     if (kt + 1 < nk) {
;       GLOAD2(ya, yb, kt + 3);
;       cfence();
;       COMPUTE2(1);
;       LSTORE2(xa, xb, 0);
;       __syncthreads();
;     }
	s_setprio 1
	s_add_u32 m0, s98, 0x6000
	v_mfma_f32_16x16x32_bf16 v[126:129], v[130:133], v[170:173], v[126:129]
	buffer_load_dwordx4 v0, s[20:23], s8 offen lds
	s_add_u32 m0, m0, 0x1000
	v_mfma_f32_16x16x32_bf16 v[122:125], v[130:133], v[174:177], v[122:125]
	buffer_load_dwordx4 v154, s[20:23], s8 offen lds
	s_add_u32 m0, m0, 0x1000
	v_mfma_f32_16x16x32_bf16 v[118:121], v[130:133], v[178:181], v[118:121]
	buffer_load_dwordx4 v155, s[20:23], s8 offen lds
	s_add_u32 m0, m0, 0x1000
	v_mfma_f32_16x16x32_bf16 v[114:117], v[130:133], v[182:185], v[114:117]
	buffer_load_dwordx4 v156, s[20:23], s8 offen lds
	s_add_u32 m0, m0, 0x1000
	v_mfma_f32_16x16x32_bf16 v[110:113], v[134:137], v[170:173], v[110:113]
	buffer_load_dwordx4 v157, s[16:19], s8 offen lds
	s_add_u32 m0, m0, 0x1000
	v_mfma_f32_16x16x32_bf16 v[106:109], v[134:137], v[174:177], v[106:109]
	buffer_load_dwordx4 v158, s[16:19], s8 offen lds
	v_mfma_f32_16x16x32_bf16 v[102:105], v[134:137], v[178:181], v[102:105]
	ds_read_b128 v[236:239], v160 offset:16384
	v_mfma_f32_16x16x32_bf16 v[98:101], v[134:137], v[182:185], v[98:101]
	v_mfma_f32_16x16x32_bf16 v[94:97], v[138:141], v[170:173], v[94:97]
	ds_read_b128 v[240:243], v160 offset:17408
	v_mfma_f32_16x16x32_bf16 v[90:93], v[138:141], v[174:177], v[90:93]
	v_mfma_f32_16x16x32_bf16 v[86:89], v[138:141], v[178:181], v[86:89]
	ds_read_b128 v[244:247], v160 offset:18432
	v_mfma_f32_16x16x32_bf16 v[82:85], v[138:141], v[182:185], v[82:85]
	v_mfma_f32_16x16x32_bf16 v[78:81], v[142:145], v[170:173], v[78:81]
	ds_read_b128 v[248:251], v160 offset:19456
	v_mfma_f32_16x16x32_bf16 v[74:77], v[142:145], v[174:177], v[74:77]
	v_mfma_f32_16x16x32_bf16 v[70:73], v[142:145], v[178:181], v[70:73]
	ds_read_b128 v[186:189], v161
	v_mfma_f32_16x16x32_bf16 v[66:69], v[142:145], v[182:185], v[66:69]
	v_mfma_f32_16x16x32_bf16 v[62:65], v[146:149], v[170:173], v[62:65]
	ds_read_b128 v[190:193], v161 offset:1024
	v_mfma_f32_16x16x32_bf16 v[58:61], v[146:149], v[174:177], v[58:61]
	v_mfma_f32_16x16x32_bf16 v[54:57], v[146:149], v[178:181], v[54:57]
	ds_read_b128 v[212:215], v161 offset:2048
	v_mfma_f32_16x16x32_bf16 v[50:53], v[146:149], v[182:185], v[50:53]
	v_mfma_f32_16x16x32_bf16 v[46:49], v[150:153], v[170:173], v[46:49]
	ds_read_b128 v[216:219], v161 offset:3072
	v_mfma_f32_16x16x32_bf16 v[42:45], v[150:153], v[174:177], v[42:45]
	v_mfma_f32_16x16x32_bf16 v[38:41], v[150:153], v[178:181], v[38:41]
	ds_read_b128 v[220:223], v161 offset:4096
	v_mfma_f32_16x16x32_bf16 v[34:37], v[150:153], v[182:185], v[34:37]
	v_mfma_f32_16x16x32_bf16 v[30:33], v[162:165], v[170:173], v[30:33]
	ds_read_b128 v[224:227], v161 offset:5120
	v_mfma_f32_16x16x32_bf16 v[26:29], v[162:165], v[174:177], v[26:29]
	v_mfma_f32_16x16x32_bf16 v[22:25], v[162:165], v[178:181], v[22:25]
	ds_read_b128 v[228:231], v161 offset:6144
	v_mfma_f32_16x16x32_bf16 v[18:21], v[162:165], v[182:185], v[18:21]
	v_mfma_f32_16x16x32_bf16 v[14:17], v[166:169], v[170:173], v[14:17]
	ds_read_b128 v[232:235], v161 offset:7168
	v_mfma_f32_16x16x32_bf16 v[10:13], v[166:169], v[174:177], v[10:13]
	v_mfma_f32_16x16x32_bf16 v[6:9], v[166:169], v[178:181], v[6:9]
	v_mfma_f32_16x16x32_bf16 v[2:5], v[166:169], v[182:185], v[2:5]
	s_setprio 0
	s_addk_i32 s7, 0x80
	s_mov_b32 s8, s9
	s_waitcnt vmcnt(0) lgkmcnt(0)
	s_barrier
	s_cbranch_vccnz .LBB0_479
	s_cmp_gt_i32 s5, 9
	s_cselect_b64 s[8:9], -1, 0
	s_ashr_i32 s7, s6, 31
	s_lshl_b64 s[10:11], s[6:7], 8
	s_add_i32 s7, s34, 0xfffffb00
	s_add_u32 s10, s10, s7
	s_addc_u32 s11, s11, 0
	s_cmp_gt_i32 s5, 7
	s_cselect_b64 s[14:15], -1, 0
	s_cmp_lt_i32 s5, 8
	s_cselect_b64 vcc, -1, 0
	s_mul_hi_i32 s5, s6, 0x4100
	s_ashr_i32 s19, s34, 31
	s_lshl_b64 s[6:7], s[34:35], 1
	s_mov_b32 s18, s34
	s_add_u32 s6, s92, s6
	s_addc_u32 s7, s93, s7
	s_lshl_b64 s[18:19], s[18:19], 1
	v_mov_b32_e32 v0, 0x3e38aa3b
	s_add_u32 s18, s76, s18
	s_waitcnt vmcnt(3)
	v_cndmask_b32_e32 v146, 1.0, v0, vcc
	s_addc_u32 s19, s77, s19
	s_lshl_b32 s34, s38, 8
	v_mov_b32_e32 v147, v146
	s_sub_i32 s34, s34, s4
	s_mov_b32 s70, 0
	s_mov_b64 s[38:39], -1
	s_branch .LBB0_483

; DI int tidx() { int t = __builtin_amdgcn_workitem_id_x(); asm volatile("" : "+v"(t)); return t; }
; DI int bidx() { int t = __builtin_amdgcn_workgroup_id_x(); asm volatile("" : "+s"(t)); return t; }
; DI int gdim() { int t = (int)__ockl_get_num_groups(0); asm volatile("" : "+s"(t)); return t; }
; DI brsrc_t make_rsrc(const void* p) { return __builtin_amdgcn_make_buffer_rsrc((void*)p, 0, 0x7fffffff, 0x00020000); }
; DI void cfence() { asm volatile("" ::: "memory"); }
; DI int swz4(int row) { const int g = (row >> 2) & 3; return ((g << 1) ^ ((g >> 1) * 3)) & 3; }
; DI void gemm256_kloop(f32x4 (&acc)[8][4], const bf16_t* __restrict__ A, int lda, const bf16_t* __restrict__ Bt, int ldb,
;                       int K, int b, int s0, int col0, char* smem) {
;   const int tid = tidx(), lane = tid & 63, wid = tid >> 6;
;   const int wr = wid >> 1, wc = wid & 1, fr = lane & 15, fq = lane >> 4;
;   const int lrow = tid >> 2, lkc = tid & 3;
;   const brsrc_t rA = make_rsrc(A), rB = make_rsrc(Bt);
;   unsigned aoff[4];
; #pragma unroll
;   for (int j = 0; j < 4; ++j) {
;     int s = s0 + lrow + 64 * j;
;     s = s < 0 ? 0 : (s > SB - 1 ? SB - 1 : s);
;     aoff[j] = ((unsigned)(b * SB + s) * (unsigned)lda + lkc * 8) * 2u;
;   }
;   const unsigned boff = ((unsigned)(col0 + lrow) * (unsigned)ldb + lkc * 8) * 2u;
;   const unsigned bstep = 64u * (unsigned)ldb * 2u;
;   const int wofs = lrow * 64 + ((lkc ^ swz4(lrow)) << 4);
;   const int nk = K >> 5;
;   u32x4 xa[4], xb[2], ya[4], yb[2];
;     ...
;   GLOAD2(xa, xb, 0);
;   GLOAD2(ya, yb, 1);
;   cfence();
;   LSTORE2(xa, xb, 0);
;   __syncthreads();
;   const int co = ((fq ^ swz4(fr)) << 4);
;   const int aofs = (wr * 128 + fr) * 64 + co, bofs = (wc * 64 + fr) * 64 + co;
; template <class Epi>
; DI void gemm256_phase_overlap(const bf16_t* A, int lda, const bf16_t* Bt, int ldb, int K, int ntn, char* smem, const Epi& epi) {
;     ...
;   for (int it = bidx(); it < total; it += gdim()) {
;     int mt = it / ntn, nt = it - mt * ntn;
;     int b = mt / 67, s0 = (mt - b * 67) * 252 - 1;
;     gemm256_tile(A, lda, Bt, ldb, K, b, s0, nt * 128, smem, epi, 126);
.LBB0_577:
	s_mul_hi_i32 s2, s34, 0x92492493
	s_add_i32 s2, s2, s34
	s_lshr_b32 s3, s2, 31
	s_ashr_i32 s5, s2, 4
	s_add_i32 s5, s5, s3
	s_mul_hi_i32 s3, s34, 0x8bbc50c9
	s_add_i32 s3, s3, s34
	s_lshr_b32 s4, s3, 31
	s_ashr_i32 s3, s3, 10
	s_add_i32 s4, s3, s4
	s_mul_i32 s3, s4, 0xffffffbd
	s_add_i32 s3, s3, s5
	s_waitcnt vmcnt(0)
	v_mov_b32_e32 v30, v194
	s_mulk_i32 s3, 0xfc
	s_movk_i32 s6, 0x1080
	v_ashrrev_i32_e32 v31, 2, v30
	v_add3_u32 v2, s3, -1, v31
	v_max_i32_e32 v4, 0xffffffc0, v2
	v_add_u32_e32 v4, 64, v4
	s_mul_i32 s3, s4, 0x4100
	v_min_u32_e32 v4, 0x40ff, v4
	v_and_b32_e32 v32, 3, v30
	v_add_u32_e32 v4, s3, v4
	v_lshlrev_b32_e32 v3, 4, v32
	v_mul_lo_u32 v4, v4, s6
	v_med3_i32 v0, v2, 0, v201
	v_or_b32_e32 v154, v4, v3
	v_max_i32_e32 v4, 0xffffff80, v2
	v_max_i32_e32 v2, 0xffffff40, v2
	v_add_u32_e32 v2, 0xc0, v2
	s_mul_i32 s2, s5, 0xffffffe4
	v_min_u32_e32 v2, 0x40ff, v2
	s_add_i32 s2, s2, s34
	v_add_u32_e32 v2, s3, v2
	s_lshl_b32 s71, s2, 7
	v_mul_lo_u32 v2, v2, s6
	v_add_u32_e32 v4, 0x80, v4
	v_or_b32_e32 v156, v2, v3
	v_add_u32_e32 v2, s71, v31
	v_min_u32_e32 v4, 0x40ff, v4
	v_mul_lo_u32 v2, v2, s6
	v_add_u32_e32 v0, s3, v0
	v_add_u32_e32 v4, s3, v4
	v_or_b32_e32 v157, v2, v3
	v_mul_lo_u32 v0, v0, s6
	v_mul_lo_u32 v4, v4, s6
	s_mov_b32 s14, s22
	s_mov_b32 s15, s23
	v_add_u32_e32 v158, 0x42000, v157
	v_or_b32_e32 v0, v0, v3
	v_or_b32_e32 v155, v4, v3
	v_bfe_u32 v162, v194, 4, 2
	v_lshlrev_b32_e32 v162, 2, v162
	v_mov_b32_e32 v163, 0x1320
	v_lshrrev_b32_e32 v162, v162, v163
	v_and_b32_e32 v162, 3, v162
	v_lshlrev_b32_e32 v162, 4, v162
	v_xor_b32_e32 v0, v0, v162
	v_xor_b32_e32 v154, v154, v162
	v_xor_b32_e32 v155, v155, v162
	v_xor_b32_e32 v156, v156, v162
	v_xor_b32_e32 v157, v157, v162
	v_xor_b32_e32 v158, v158, v162
	v_lshrrev_b32_e32 v163, 6, v194
	s_nop 0
	v_readfirstlane_b32 s98, v163
	s_lshl_b32 s98, s98, 10
	s_mov_b32 m0, s98
	s_nop 0
	buffer_load_dwordx4 v0, s[20:23], 0 offen lds
	s_add_u32 m0, m0, 0x1000
	s_nop 0
	buffer_load_dwordx4 v154, s[20:23], 0 offen lds
	s_add_u32 m0, m0, 0x1000
	s_nop 0
	buffer_load_dwordx4 v155, s[20:23], 0 offen lds
	s_add_u32 m0, m0, 0x1000
	s_nop 0
	buffer_load_dwordx4 v156, s[20:23], 0 offen lds
	s_add_u32 m0, m0, 0x1000
	s_nop 0
	buffer_load_dwordx4 v157, s[12:15], 0 offen lds
	s_add_u32 m0, m0, 0x1000
	s_nop 0
	buffer_load_dwordx4 v158, s[12:15], 0 offen lds
	s_add_u32 m0, s98, 0x6000
	s_nop 0
	buffer_load_dwordx4 v0, s[20:23], 64 offen lds
	s_add_u32 m0, m0, 0x1000
	s_nop 0
	buffer_load_dwordx4 v154, s[20:23], 64 offen lds
	s_add_u32 m0, m0, 0x1000
	s_nop 0
	buffer_load_dwordx4 v155, s[20:23], 64 offen lds
	s_add_u32 m0, m0, 0x1000
	s_nop 0
	buffer_load_dwordx4 v156, s[20:23], 64 offen lds
	s_add_u32 m0, m0, 0x1000
	s_nop 0
	buffer_load_dwordx4 v157, s[12:15], 64 offen lds
	s_add_u32 m0, m0, 0x1000
	s_nop 0
	buffer_load_dwordx4 v158, s[12:15], 64 offen lds
	v_bfe_i32 v33, v30, 5, 1
	v_lshrrev_b32_e32 v35, 1, v30
	v_bfe_i32 v34, v30, 3, 1
	v_lshlrev_b32_e32 v37, 6, v31
	v_lshrrev_b32_e32 v31, 1, v31
	v_and_b32_e32 v33, 3, v33
	v_and_b32_e32 v35, 2, v35
	v_bitop3_b32 v31, v31, v33, 2 bitop3:0x6c
	v_bitop3_b32 v33, v34, v35, 3 bitop3:0x6c
	v_xor_b32_e32 v31, v31, v32
	v_lshlrev_b32_e32 v32, 4, v33
	v_lshlrev_b32_e32 v36, 6, v30
	v_bitop3_b32 v30, v32, v30, 48 bitop3:0x78
	s_movk_i32 s7, 0x13c0
	v_mov_b32_e32 v2, 0
	v_lshl_or_b32 v159, v31, 4, v37
	v_and_or_b32 v160, v36, s7, v30
	s_movk_i32 s7, 0xe3c0
	s_mov_b32 s6, 0
	s_movk_i32 s3, 0x80
	v_mov_b32_e32 v3, v2
	v_mov_b32_e32 v4, v2
	v_mov_b32_e32 v5, v2
	v_and_or_b32 v161, v36, s7, v30
	v_mov_b32_e32 v30, v2
	v_mov_b32_e32 v31, v2
	v_mov_b32_e32 v32, v2
	v_mov_b32_e32 v33, v2
	v_mov_b32_e32 v34, v2
	v_mov_b32_e32 v35, v2
	v_mov_b32_e32 v36, v2
	v_mov_b32_e32 v37, v2
	v_mov_b32_e32 v38, v2
	v_mov_b32_e32 v39, v2
	v_mov_b32_e32 v40, v2
	v_mov_b32_e32 v41, v2
	v_mov_b32_e32 v42, v2
	v_mov_b32_e32 v43, v2
	v_mov_b32_e32 v44, v2
	v_mov_b32_e32 v45, v2
	v_mov_b32_e32 v46, v2
	v_mov_b32_e32 v47, v2
	v_mov_b32_e32 v48, v2
	v_mov_b32_e32 v49, v2
	v_mov_b32_e32 v50, v2
	v_mov_b32_e32 v51, v2
	v_mov_b32_e32 v52, v2
	v_mov_b32_e32 v53, v2
	v_mov_b32_e32 v54, v2
	v_mov_b32_e32 v6, v2
	v_mov_b32_e32 v7, v2
	v_mov_b32_e32 v8, v2
	v_mov_b32_e32 v9, v2
	v_mov_b32_e32 v10, v2
	v_mov_b32_e32 v11, v2
	v_mov_b32_e32 v12, v2
	v_mov_b32_e32 v13, v2
	v_mov_b32_e32 v14, v2
	v_mov_b32_e32 v15, v2
	v_mov_b32_e32 v16, v2
	v_mov_b32_e32 v17, v2
	v_mov_b32_e32 v18, v2
	v_mov_b32_e32 v19, v2
	v_mov_b32_e32 v20, v2
	v_mov_b32_e32 v21, v2
	v_mov_b32_e32 v22, v2
	v_mov_b32_e32 v23, v2
	v_mov_b32_e32 v24, v2
	v_mov_b32_e32 v25, v2
	v_mov_b32_e32 v26, v2
	v_mov_b32_e32 v27, v2
	v_mov_b32_e32 v28, v2
	v_mov_b32_e32 v29, v2
	v_mov_b32_e32 v55, v2
	v_mov_b32_e32 v56, v2
	v_mov_b32_e32 v57, v2
	v_mov_b32_e32 v58, v2
	v_mov_b32_e32 v59, v2
	v_mov_b32_e32 v60, v2
	v_mov_b32_e32 v61, v2
	v_mov_b32_e32 v62, v2
	v_mov_b32_e32 v63, v2
	v_mov_b32_e32 v64, v2
	v_mov_b32_e32 v65, v2
	v_mov_b32_e32 v66, v2
	v_mov_b32_e32 v67, v2
	v_mov_b32_e32 v68, v2
	v_mov_b32_e32 v69, v2
	v_mov_b32_e32 v70, v2
	v_mov_b32_e32 v71, v2
	v_mov_b32_e32 v72, v2
	v_mov_b32_e32 v73, v2
	v_mov_b32_e32 v74, v2
	v_mov_b32_e32 v75, v2
	v_mov_b32_e32 v76, v2
	v_mov_b32_e32 v77, v2
	v_mov_b32_e32 v78, v2
	v_mov_b32_e32 v79, v2
	v_mov_b32_e32 v80, v2
	v_mov_b32_e32 v81, v2
	v_mov_b32_e32 v82, v2
	v_mov_b32_e32 v83, v2
	v_mov_b32_e32 v84, v2
	v_mov_b32_e32 v85, v2
	v_mov_b32_e32 v86, v2
	v_mov_b32_e32 v87, v2
	v_mov_b32_e32 v88, v2
	v_mov_b32_e32 v89, v2
	v_mov_b32_e32 v90, v2
	v_mov_b32_e32 v91, v2
	v_mov_b32_e32 v92, v2
	v_mov_b32_e32 v93, v2
	v_mov_b32_e32 v94, v2
	v_mov_b32_e32 v95, v2
	v_mov_b32_e32 v96, v2
	v_mov_b32_e32 v97, v2
	v_mov_b32_e32 v98, v2
	v_mov_b32_e32 v99, v2
	v_mov_b32_e32 v100, v2
	v_mov_b32_e32 v101, v2
	v_mov_b32_e32 v102, v2
	v_mov_b32_e32 v103, v2
	v_mov_b32_e32 v104, v2
	v_mov_b32_e32 v105, v2
	v_mov_b32_e32 v106, v2
	v_mov_b32_e32 v107, v2
	v_mov_b32_e32 v108, v2
	v_mov_b32_e32 v109, v2
	v_mov_b32_e32 v110, v2
	v_mov_b32_e32 v111, v2
	v_mov_b32_e32 v112, v2
	v_mov_b32_e32 v113, v2
	v_mov_b32_e32 v114, v2
	v_mov_b32_e32 v115, v2
	v_mov_b32_e32 v116, v2
	v_mov_b32_e32 v117, v2
	v_mov_b32_e32 v118, v2
	v_mov_b32_e32 v119, v2
	v_mov_b32_e32 v120, v2
	v_mov_b32_e32 v121, v2
	v_mov_b32_e32 v122, v2
	v_mov_b32_e32 v123, v2
	v_mov_b32_e32 v124, v2
	v_mov_b32_e32 v125, v2
	v_mov_b32_e32 v126, v2
	v_mov_b32_e32 v127, v2
	v_mov_b32_e32 v128, v2
	v_mov_b32_e32 v129, v2
	s_waitcnt vmcnt(6) lgkmcnt(0)
	s_barrier
	ds_read_b128 v[236:239], v160 offset:16384
	ds_read_b128 v[240:243], v160 offset:17408
	ds_read_b128 v[244:247], v160 offset:18432
	ds_read_b128 v[248:251], v160 offset:19456
	ds_read_b128 v[186:189], v161
	ds_read_b128 v[190:193], v161 offset:1024
	ds_read_b128 v[212:215], v161 offset:2048
	ds_read_b128 v[216:219], v161 offset:3072
	ds_read_b128 v[220:223], v161 offset:4096
	ds_read_b128 v[224:227], v161 offset:5120
	ds_read_b128 v[228:231], v161 offset:6144
	ds_read_b128 v[232:235], v161 offset:7168
	s_waitcnt vmcnt(0) lgkmcnt(0)
	s_barrier
; DI void cfence() { asm volatile("" ::: "memory"); }
; DI int swz4(int row) { const int g = (row >> 2) & 3; return ((g << 1) ^ ((g >> 1) * 3)) & 3; }
; #define LSTORE2(RA, RB, P)                                       \
;   {                                                              \
;     char* dA_ = smem + (P) * 24576 + wofs;                       \
;     _Pragma("unroll") for (int j = 0; j < 4; ++j) *(u32x4*)(dA_ + j * 4096) = RA[j]; \
;     _Pragma("unroll") for (int j = 0; j < 2; ++j) *(u32x4*)(dA_ + 16384 + j * 4096) = RB[j]; \
;   }
; DI void gemm256_kloop(f32x4 (&acc)[8][4], const bf16_t* __restrict__ A, int lda, const bf16_t* __restrict__ Bt, int ldb,
;                       int K, int b, int s0, int col0, char* smem) {
;     ...
;   GLOAD2(xa, xb, 0);
;   GLOAD2(ya, yb, 1);
;   cfence();
;   LSTORE2(xa, xb, 0);
;   __syncthreads();
;   const int co = ((fq ^ swz4(fr)) << 4);
;   const int aofs = (wr * 128 + fr) * 64 + co, bofs = (wc * 64 + fr) * 64 + co;
;   for (int kt = 0; kt < nk; kt += 2) {
;     GLOAD2(xa, xb, kt + 2);
;     cfence();
;     COMPUTE2(0);
;     LSTORE2(ya, yb, 1);
;     __syncthreads();
.LBB0_578:
	s_add_i32 s7, s6, 2
	s_cmp_lt_u32 s6, 62
	s_cselect_b64 s[8:9], -1, 0
	s_and_b64 vcc, s[8:9], exec
	s_cselect_b32 s8, s3, 0xfc0
	s_setprio 1
	s_mov_b32 m0, s98
	v_mfma_f32_16x16x32_bf16 v[126:129], v[186:189], v[236:239], v[126:129]
	buffer_load_dwordx4 v0, s[20:23], s8 offen lds
	s_add_u32 m0, m0, 0x1000
	v_mfma_f32_16x16x32_bf16 v[122:125], v[186:189], v[240:243], v[122:125]
	buffer_load_dwordx4 v154, s[20:23], s8 offen lds
	s_add_u32 m0, m0, 0x1000
	v_mfma_f32_16x16x32_bf16 v[118:121], v[186:189], v[244:247], v[118:121]
	buffer_load_dwordx4 v155, s[20:23], s8 offen lds
	s_add_u32 m0, m0, 0x1000
	v_mfma_f32_16x16x32_bf16 v[114:117], v[186:189], v[248:251], v[114:117]
	buffer_load_dwordx4 v156, s[20:23], s8 offen lds
	s_add_u32 m0, m0, 0x1000
	v_mfma_f32_16x16x32_bf16 v[110:113], v[190:193], v[236:239], v[110:113]
	buffer_load_dwordx4 v157, s[12:15], s8 offen lds
	s_add_u32 m0, m0, 0x1000
	v_mfma_f32_16x16x32_bf16 v[106:109], v[190:193], v[240:243], v[106:109]
	buffer_load_dwordx4 v158, s[12:15], s8 offen lds
	v_mfma_f32_16x16x32_bf16 v[102:105], v[190:193], v[244:247], v[102:105]
	ds_read_b128 v[170:173], v160 offset:40960
	v_mfma_f32_16x16x32_bf16 v[98:101], v[190:193], v[248:251], v[98:101]
	v_mfma_f32_16x16x32_bf16 v[94:97], v[212:215], v[236:239], v[94:97]
	ds_read_b128 v[174:177], v160 offset:41984
	v_mfma_f32_16x16x32_bf16 v[90:93], v[212:215], v[240:243], v[90:93]
	v_mfma_f32_16x16x32_bf16 v[86:89], v[212:215], v[244:247], v[86:89]
	ds_read_b128 v[178:181], v160 offset:43008
	v_mfma_f32_16x16x32_bf16 v[82:85], v[212:215], v[248:251], v[82:85]
	v_mfma_f32_16x16x32_bf16 v[78:81], v[216:219], v[236:239], v[78:81]
	ds_read_b128 v[182:185], v160 offset:44032
	v_mfma_f32_16x16x32_bf16 v[74:77], v[216:219], v[240:243], v[74:77]
	v_mfma_f32_16x16x32_bf16 v[70:73], v[216:219], v[244:247], v[70:73]
	ds_read_b128 v[130:133], v161 offset:24576
	v_mfma_f32_16x16x32_bf16 v[66:69], v[216:219], v[248:251], v[66:69]
	v_mfma_f32_16x16x32_bf16 v[62:65], v[220:223], v[236:239], v[62:65]
	ds_read_b128 v[134:137], v161 offset:25600
	v_mfma_f32_16x16x32_bf16 v[58:61], v[220:223], v[240:243], v[58:61]
	v_mfma_f32_16x16x32_bf16 v[54:57], v[220:223], v[244:247], v[54:57]
	ds_read_b128 v[138:141], v161 offset:26624
	v_mfma_f32_16x16x32_bf16 v[50:53], v[220:223], v[248:251], v[50:53]
	v_mfma_f32_16x16x32_bf16 v[46:49], v[224:227], v[236:239], v[46:49]
	ds_read_b128 v[142:145], v161 offset:27648
	v_mfma_f32_16x16x32_bf16 v[42:45], v[224:227], v[240:243], v[42:45]
	v_mfma_f32_16x16x32_bf16 v[38:41], v[224:227], v[244:247], v[38:41]
	ds_read_b128 v[146:149], v161 offset:28672
	v_mfma_f32_16x16x32_bf16 v[34:37], v[224:227], v[248:251], v[34:37]
	v_mfma_f32_16x16x32_bf16 v[30:33], v[228:231], v[236:239], v[30:33]
	ds_read_b128 v[150:153], v161 offset:29696
	v_mfma_f32_16x16x32_bf16 v[26:29], v[228:231], v[240:243], v[26:29]
	v_mfma_f32_16x16x32_bf16 v[22:25], v[228:231], v[244:247], v[22:25]
	ds_read_b128 v[162:165], v161 offset:30720
	v_mfma_f32_16x16x32_bf16 v[18:21], v[228:231], v[248:251], v[18:21]
	v_mfma_f32_16x16x32_bf16 v[14:17], v[232:235], v[236:239], v[14:17]
	ds_read_b128 v[166:169], v161 offset:31744
	v_mfma_f32_16x16x32_bf16 v[10:13], v[232:235], v[240:243], v[10:13]
	v_mfma_f32_16x16x32_bf16 v[6:9], v[232:235], v[244:247], v[6:9]
	v_mfma_f32_16x16x32_bf16 v[2:5], v[232:235], v[248:251], v[2:5]
	s_setprio 0
	s_min_u32 s6, s6, 60
	s_lshl_b32 s6, s6, 6
	s_addk_i32 s6, 0xc0
	s_waitcnt vmcnt(0) lgkmcnt(0)
	s_barrier
; DI void cfence() { asm volatile("" ::: "memory"); }
; DI int swz4(int row) { const int g = (row >> 2) & 3; return ((g << 1) ^ ((g >> 1) * 3)) & 3; }
; #define LSTORE2(RA, RB, P)                                       \
;   {                                                              \
;     char* dA_ = smem + (P) * 24576 + wofs;                       \
;     _Pragma("unroll") for (int j = 0; j < 4; ++j) *(u32x4*)(dA_ + j * 4096) = RA[j]; \
;     _Pragma("unroll") for (int j = 0; j < 2; ++j) *(u32x4*)(dA_ + 16384 + j * 4096) = RB[j]; \
;   }
; DI void gemm256_kloop(f32x4 (&acc)[8][4], const bf16_t* __restrict__ A, int lda, const bf16_t* __restrict__ Bt, int ldb,
;                       int K, int b, int s0, int col0, char* smem) {
;     ...
;   GLOAD2(xa, xb, 0);
;   GLOAD2(ya, yb, 1);
;   cfence();
;   LSTORE2(xa, xb, 0);
;   __syncthreads();
;   const int co = ((fq ^ swz4(fr)) << 4);
;   const int aofs = (wr * 128 + fr) * 64 + co, bofs = (wc * 64 + fr) * 64 + co;
;   for (int kt = 0; kt < nk; kt += 2) {
;     GLOAD2(xa, xb, kt + 2);
;     cfence();
;     COMPUTE2(0);
;     LSTORE2(ya, yb, 1);
;     __syncthreads();
;     if (kt + 1 < nk) {
;       GLOAD2(ya, yb, kt + 3);
;       cfence();
;       COMPUTE2(1);
;       LSTORE2(xa, xb, 0);
;       __syncthreads();
;     }
	s_setprio 1
	s_add_u32 m0, s98, 0x6000
	v_mfma_f32_16x16x32_bf16 v[126:129], v[130:133], v[170:173], v[126:129]
	buffer_load_dwordx4 v0, s[20:23], s6 offen lds
	s_add_u32 m0, m0, 0x1000
	v_mfma_f32_16x16x32_bf16 v[122:125], v[130:133], v[174:177], v[122:125]
	buffer_load_dwordx4 v154, s[20:23], s6 offen lds
	s_add_u32 m0, m0, 0x1000
	v_mfma_f32_16x16x32_bf16 v[118:121], v[130:133], v[178:181], v[118:121]
	buffer_load_dwordx4 v155, s[20:23], s6 offen lds
	s_add_u32 m0, m0, 0x1000
	v_mfma_f32_16x16x32_bf16 v[114:117], v[130:133], v[182:185], v[114:117]
	buffer_load_dwordx4 v156, s[20:23], s6 offen lds
	s_add_u32 m0, m0, 0x1000
	v_mfma_f32_16x16x32_bf16 v[110:113], v[134:137], v[170:173], v[110:113]
	buffer_load_dwordx4 v157, s[12:15], s6 offen lds
	s_add_u32 m0, m0, 0x1000
	v_mfma_f32_16x16x32_bf16 v[106:109], v[134:137], v[174:177], v[106:109]
	buffer_load_dwordx4 v158, s[12:15], s6 offen lds
	v_mfma_f32_16x16x32_bf16 v[102:105], v[134:137], v[178:181], v[102:105]
	ds_read_b128 v[236:239], v160 offset:16384
	v_mfma_f32_16x16x32_bf16 v[98:101], v[134:137], v[182:185], v[98:101]
	v_mfma_f32_16x16x32_bf16 v[94:97], v[138:141], v[170:173], v[94:97]
	ds_read_b128 v[240:243], v160 offset:17408
	v_mfma_f32_16x16x32_bf16 v[90:93], v[138:141], v[174:177], v[90:93]
	v_mfma_f32_16x16x32_bf16 v[86:89], v[138:141], v[178:181], v[86:89]
	ds_read_b128 v[244:247], v160 offset:18432
	v_mfma_f32_16x16x32_bf16 v[82:85], v[138:141], v[182:185], v[82:85]
	v_mfma_f32_16x16x32_bf16 v[78:81], v[142:145], v[170:173], v[78:81]
	ds_read_b128 v[248:251], v160 offset:19456
	v_mfma_f32_16x16x32_bf16 v[74:77], v[142:145], v[174:177], v[74:77]
	v_mfma_f32_16x16x32_bf16 v[70:73], v[142:145], v[178:181], v[70:73]
	ds_read_b128 v[186:189], v161
	v_mfma_f32_16x16x32_bf16 v[66:69], v[142:145], v[182:185], v[66:69]
	v_mfma_f32_16x16x32_bf16 v[62:65], v[146:149], v[170:173], v[62:65]
	ds_read_b128 v[190:193], v161 offset:1024
	v_mfma_f32_16x16x32_bf16 v[58:61], v[146:149], v[174:177], v[58:61]
	v_mfma_f32_16x16x32_bf16 v[54:57], v[146:149], v[178:181], v[54:57]
	ds_read_b128 v[212:215], v161 offset:2048
	v_mfma_f32_16x16x32_bf16 v[50:53], v[146:149], v[182:185], v[50:53]
	v_mfma_f32_16x16x32_bf16 v[46:49], v[150:153], v[170:173], v[46:49]
	ds_read_b128 v[216:219], v161 offset:3072
	v_mfma_f32_16x16x32_bf16 v[42:45], v[150:153], v[174:177], v[42:45]
	v_mfma_f32_16x16x32_bf16 v[38:41], v[150:153], v[178:181], v[38:41]
	ds_read_b128 v[220:223], v161 offset:4096
	v_mfma_f32_16x16x32_bf16 v[34:37], v[150:153], v[182:185], v[34:37]
	v_mfma_f32_16x16x32_bf16 v[30:33], v[162:165], v[170:173], v[30:33]
	ds_read_b128 v[224:227], v161 offset:5120
	v_mfma_f32_16x16x32_bf16 v[26:29], v[162:165], v[174:177], v[26:29]
	v_mfma_f32_16x16x32_bf16 v[22:25], v[162:165], v[178:181], v[22:25]
	ds_read_b128 v[228:231], v161 offset:6144
	v_mfma_f32_16x16x32_bf16 v[18:21], v[162:165], v[182:185], v[18:21]
	v_mfma_f32_16x16x32_bf16 v[14:17], v[166:169], v[170:173], v[14:17]
	ds_read_b128 v[232:235], v161 offset:7168
	v_mfma_f32_16x16x32_bf16 v[10:13], v[166:169], v[174:177], v[10:13]
	v_mfma_f32_16x16x32_bf16 v[6:9], v[166:169], v[178:181], v[6:9]
	v_mfma_f32_16x16x32_bf16 v[2:5], v[166:169], v[182:185], v[2:5]
	s_setprio 0
	s_addk_i32 s3, 0x80
	s_mov_b32 s6, s7
	s_waitcnt vmcnt(0) lgkmcnt(0)
	s_barrier
	s_cbranch_vccnz .LBB0_578
	s_cmp_gt_i32 s2, 23
	s_cselect_b64 s[2:3], -1, 0
	s_cmpk_gt_u32 s71, 0xd7f
	s_mulk_i32 s5, 0xfc
	s_mul_i32 s6, s4, 0x41f4
	s_cselect_b64 s[8:9], -1, 0
	s_sub_i32 s72, s5, s6
	s_mul_i32 s6, s4, 0x1248000
	s_mul_hi_i32 s5, s4, 0x1248000
	s_add_u32 s14, s48, s6
	s_addc_u32 s15, s49, s5
	s_add_u32 s16, s50, s6
	s_addc_u32 s17, s51, s5
	s_mul_i32 s6, s4, 0x2080000
	s_mul_hi_i32 s5, s4, 0x2080000
	s_add_u32 s18, s52, s6
	s_addc_u32 s19, s53, s5
	s_mul_hi_i32 s5, s4, 0x6180000
	s_mul_i32 s4, s4, 0x6180000
	s_add_u32 s24, s69, s4
	s_addc_u32 s25, s70, s5
	s_mov_b32 s73, 0
	s_mov_b64 s[26:27], -1
	s_branch .LBB0_582

; __global__ void __launch_bounds__(256, 2) mega(Params P) {
;   __shared__ __attribute__((aligned(16))) char smem[69632];
;   const int p0 = P.p0, p1 = P.p1;
	.amdhsa_kernel _Z4mega6Params
		.amdhsa_group_segment_fixed_size 69632
		.amdhsa_private_segment_fixed_size 0
		.amdhsa_kernarg_size 560
		.amdhsa_user_sgpr_count 2
		.amdhsa_user_sgpr_dispatch_ptr 0
		.amdhsa_user_sgpr_queue_ptr 0
		.amdhsa_user_sgpr_kernarg_segment_ptr 1
		.amdhsa_user_sgpr_dispatch_id 0
		.amdhsa_user_sgpr_kernarg_preload_length 0
		.amdhsa_user_sgpr_kernarg_preload_offset 0
		.amdhsa_user_sgpr_private_segment_size 0
		.amdhsa_uses_dynamic_stack 0
		.amdhsa_enable_private_segment 0
		.amdhsa_system_sgpr_workgroup_id_x 1
		.amdhsa_system_sgpr_workgroup_id_y 0
		.amdhsa_system_sgpr_workgroup_id_z 0
		.amdhsa_system_sgpr_workgroup_info 0
		.amdhsa_system_vgpr_workitem_id 2
		.amdhsa_next_free_vgpr 254
		.amdhsa_next_free_sgpr 102
		.amdhsa_accum_offset 256
		.amdhsa_reserve_vcc 1
		.amdhsa_float_round_mode_32 0
		.amdhsa_float_round_mode_16_64 0
		.amdhsa_float_denorm_mode_32 3
		.amdhsa_float_denorm_mode_16_64 3
		.amdhsa_dx10_clamp 1
		.amdhsa_ieee_mode 1
		.amdhsa_fp16_overflow 0
		.amdhsa_tg_split 0
		.amdhsa_exception_fp_ieee_invalid_op 0
		.amdhsa_exception_fp_denorm_src 0
		.amdhsa_exception_fp_ieee_div_zero 0
		.amdhsa_exception_fp_ieee_overflow 0
		.amdhsa_exception_fp_ieee_underflow 0
		.amdhsa_exception_fp_ieee_inexact 0
		.amdhsa_exception_int_div_zero 0
	.end_amdhsa_kernel

; __global__ void __launch_bounds__(256, 2) mega(Params P) {
;   __shared__ __attribute__((aligned(16))) char smem[69632];
;   const int p0 = P.p0, p1 = P.p1;
amdhsa.kernels:
  - .agpr_count:     0
    .args:
      - .offset:         0
        .size:           304
        .value_kind:     by_value
      - .offset:         304
        .size:           4
        .value_kind:     hidden_block_count_x
      - .offset:         308
        .size:           4
        .value_kind:     hidden_block_count_y
      - .offset:         312
        .size:           4
        .value_kind:     hidden_block_count_z
      - .offset:         316
        .size:           2
        .value_kind:     hidden_group_size_x
      - .offset:         318
        .size:           2
        .value_kind:     hidden_group_size_y
      - .offset:         320
        .size:           2
        .value_kind:     hidden_group_size_z
      - .offset:         322
        .size:           2
        .value_kind:     hidden_remainder_x
      - .offset:         324
        .size:           2
        .value_kind:     hidden_remainder_y
      - .offset:         326
        .size:           2
        .value_kind:     hidden_remainder_z
      - .offset:         344
        .size:           8
        .value_kind:     hidden_global_offset_x
      - .offset:         352
        .size:           8
        .value_kind:     hidden_global_offset_y
      - .offset:         360
        .size:           8
        .value_kind:     hidden_global_offset_z
      - .offset:         368
        .size:           2
        .value_kind:     hidden_grid_dims
      - .offset:         392
        .size:           8
        .value_kind:     hidden_multigrid_sync_arg
    .group_segment_fixed_size: 69632
    .kernarg_segment_align: 8
    .kernarg_segment_size: 560
    .language:       OpenCL C
    .language_version:
      - 2
      - 0
    .max_flat_workgroup_size: 256
    .name:           _Z4mega6Params
    .private_segment_fixed_size: 0
    .sgpr_count:     108
    .sgpr_spill_count: 70
    .symbol:         _Z4mega6Params.kd
    .uniform_work_group_size: 1
    .uses_dynamic_stack: false
    .vgpr_count:     254
    .vgpr_spill_count: 0
    .wavefront_size: 64
